# speedup vs baseline: 1.0428x; 1.0207x over previous
; #define WAIT_V(n) asm volatile("s_waitcnt vmcnt(" #n ")" ::: "memory")
; #define BAR __builtin_amdgcn_s_barrier()
;     ...
;   f32x4 acc[2][2][4][2] = {};
;   bf16x8 At[4][2], B0[2][2], B1[2][2];
;   const int nt = K / BK;
;   unsigned soff0, soff1;
;   { int _r, _c; stage_rc(tx * 16, _r, _c); soff0 = (unsigned)(_r * K + _c) * 2u;
;     stage_rc(tx * 16 + 8192, _r, _c); soff1 = (unsigned)(_r * K + _c) * 2u; }
;   STAGE(SB(0, 0), Bt, bcol, 0); STAGE(SA(0, 0), A, brow, 0);
;   STAGE(SB(0, 1), Bt, bcol1, 0); STAGE(SA(0, 1), A, brow + HALF, 0);
;   if (wr == 1) BAR;
;   WAIT_V(4); BAR;
;   STAGE(SB(1, 0), Bt, bcol, 1); STAGE(SA(1, 0), A, brow, 1); STAGE(SB(1, 1), Bt, bcol1, 1);
;   WAIT_V(6); BAR;
.LBB0_68:
	s_or_b64 exec, exec, s[12:13]
	v_add_u32_e32 v155, s54, v18
	v_add_u32_e32 v156, 0x2000, v155
	v_readfirstlane_b32 s12, v155
	v_lshl_add_u64 v[10:11], v[10:11], 0, s[24:25]
	s_mov_b32 m0, s12
	v_readfirstlane_b32 s12, v156
	v_add_u32_e32 v157, 0x8000, v147
	s_waitcnt vmcnt(4)
	s_barrier
	global_load_lds_dwordx4 v[10:11], off
	v_lshl_add_u64 v[8:9], v[8:9], 0, s[24:25]
	s_mov_b32 m0, s12
	v_readfirstlane_b32 s12, v157
	v_add_u32_e32 v158, 0xa000, v147
	global_load_lds_dwordx4 v[8:9], off
	v_lshl_add_u64 v[6:7], v[6:7], 0, s[24:25]
	s_mov_b32 m0, s12
	v_readfirstlane_b32 s12, v158
	v_add_u32_e32 v159, s55, v18
	global_load_lds_dwordx4 v[6:7], off
	v_lshl_add_u64 v[4:5], v[4:5], 0, s[24:25]
	s_mov_b32 m0, s12
	v_readfirstlane_b32 s12, v159
	v_add_u32_e32 v160, 0x2000, v159
	global_load_lds_dwordx4 v[4:5], off
	v_lshl_add_u64 v[2:3], v[2:3], 0, s[24:25]
	s_mov_b32 m0, s12
	v_readfirstlane_b32 s12, v160
	global_load_lds_dwordx4 v[2:3], off
	v_lshl_add_u64 v[0:1], v[0:1], 0, s[24:25]
	s_mov_b32 m0, s12
	v_and_b32_e32 v239, 15, v142
	global_load_lds_dwordx4 v[0:1], off
	v_lshlrev_b32_e32 v1, 2, v142
	v_and_b32_e32 v237, 48, v142
	v_lshlrev_b32_e32 v0, 6, v239
	v_and_b32_e32 v1, 32, v1
	v_bitop3_b32 v0, v0, v1, v237 bitop3:0x36
	v_add_u32_e32 v5, s33, v0
	v_add_u32_e32 v6, s53, v0
	v_add_u32_e32 v7, s54, v0
	v_add_u32_e32 v8, s55, v0
	v_add_u32_e32 v10, 0, v0
	v_lshlrev_b32_e32 v0, 6, v142
	v_and_or_b32 v0, v0, s56, v237
	v_xad_u32 v11, v0, v1, 0
	v_lshlrev_b32_e32 v0, 16, v12
	v_lshlrev_b32_e32 v2, 16, v14
	v_and_b32_e32 v0, 0xfffe0000, v0
	v_and_b32_e32 v2, 0xfffe0000, v2
	v_lshl_add_u32 v0, v13, 13, v0
	v_and_b32_e32 v1, 1, v12
	v_lshl_add_u32 v2, v16, 13, v2
	v_and_b32_e32 v3, 1, v14
	v_lshl_or_b32 v0, v1, 6, v0
	s_add_u32 s8, s20, s8
	v_lshl_or_b32 v2, v3, 6, v2
	v_lshl_add_u32 v0, v15, 1, v0
	v_mov_b32_e32 v1, v185
	s_addc_u32 s9, s21, s9
	v_lshl_add_u32 v2, v17, 1, v2
	v_mov_b32_e32 v3, v185
	v_lshl_add_u64 v[130:131], s[8:9], 0, v[0:1]
	v_lshl_add_u64 v[132:133], s[8:9], 0, v[2:3]
	s_add_u32 s8, s18, s10
	v_bfe_u32 v236, v143, 6, 2
	s_waitcnt vmcnt(6)
	v_lshlrev_b32_e32 v9, 13, v238
	s_addc_u32 s9, s19, s11
	v_lshlrev_b32_e32 v4, 12, v236
	v_or_b32_e32 v18, 0x800, v9
	v_or_b32_e32 v19, 0x1000, v9
	v_or_b32_e32 v20, 0x1800, v9
	v_lshl_add_u64 v[134:135], s[8:9], 0, v[0:1]
	v_mov_b32_e32 v0, 0
	v_lshlrev_b32_e32 v138, 6, v238
	v_lshl_add_u64 v[136:137], s[8:9], 0, v[2:3]
	s_mov_b32 s10, -2
	s_mov_b64 s[8:9], 0
	v_add_u32_e32 v162, v5, v4
	v_add_u32_e32 v144, v10, v9
	v_add_u32_e32 v141, v11, v18
	v_add_u32_e32 v140, v11, v19
	v_add_u32_e32 v139, v11, v20
	v_add_u32_e32 v161, v6, v4
	v_add_u32_e32 v152, v7, v4
	v_add_u32_e32 v148, v8, v4
	v_mov_b32_e32 v1, v0
	v_mov_b32_e32 v2, v0
	v_mov_b32_e32 v3, v0
	v_mov_b32_e32 v4, v0
	v_mov_b32_e32 v5, v0
	v_mov_b32_e32 v6, v0
	v_mov_b32_e32 v7, v0
	v_mov_b32_e32 v8, v0
	v_mov_b32_e32 v9, v0
	v_mov_b32_e32 v10, v0
	v_mov_b32_e32 v11, v0
	v_mov_b32_e32 v12, v0
	v_mov_b32_e32 v13, v0
	v_mov_b32_e32 v14, v0
	v_mov_b32_e32 v15, v0
	v_mov_b32_e32 v16, v0
	v_mov_b32_e32 v17, v0
	v_mov_b32_e32 v18, v0
	v_mov_b32_e32 v19, v0
	v_mov_b32_e32 v20, v0
	v_mov_b32_e32 v21, v0
	v_mov_b32_e32 v22, v0
	v_mov_b32_e32 v23, v0
	v_mov_b32_e32 v24, v0
	v_mov_b32_e32 v25, v0
	v_mov_b32_e32 v26, v0
	v_mov_b32_e32 v27, v0
	v_mov_b32_e32 v28, v0
	v_mov_b32_e32 v29, v0
	v_mov_b32_e32 v30, v0
	v_mov_b32_e32 v31, v0
	v_mov_b32_e32 v32, v0
	v_mov_b32_e32 v33, v0
	v_mov_b32_e32 v34, v0
	v_mov_b32_e32 v35, v0
	v_mov_b32_e32 v36, v0
	v_mov_b32_e32 v37, v0
	v_mov_b32_e32 v38, v0
	v_mov_b32_e32 v39, v0
	v_mov_b32_e32 v40, v0
	v_mov_b32_e32 v41, v0
	v_mov_b32_e32 v42, v0
	v_mov_b32_e32 v43, v0
	v_mov_b32_e32 v44, v0
	v_mov_b32_e32 v45, v0
	v_mov_b32_e32 v46, v0
	v_mov_b32_e32 v47, v0
	v_mov_b32_e32 v48, v0
	v_mov_b32_e32 v49, v0
	v_mov_b32_e32 v50, v0
	v_mov_b32_e32 v51, v0
	v_mov_b32_e32 v52, v0
	v_mov_b32_e32 v53, v0
	v_mov_b32_e32 v54, v0
	v_mov_b32_e32 v55, v0
	v_mov_b32_e32 v56, v0
	v_mov_b32_e32 v57, v0
	v_mov_b32_e32 v58, v0
	v_mov_b32_e32 v59, v0
	v_mov_b32_e32 v60, v0
	v_mov_b32_e32 v61, v0
	v_mov_b32_e32 v62, v0
	v_mov_b32_e32 v63, v0
	v_mov_b32_e32 v64, v0
	v_mov_b32_e32 v65, v0
	v_mov_b32_e32 v66, v0
	v_mov_b32_e32 v67, v0
	v_mov_b32_e32 v68, v0
	v_mov_b32_e32 v69, v0
	v_mov_b32_e32 v70, v0
	v_mov_b32_e32 v71, v0
	v_mov_b32_e32 v72, v0
	v_mov_b32_e32 v73, v0
	v_mov_b32_e32 v74, v0
	v_mov_b32_e32 v75, v0
	v_mov_b32_e32 v76, v0
	v_mov_b32_e32 v77, v0
	v_mov_b32_e32 v78, v0
	v_mov_b32_e32 v79, v0
	v_mov_b32_e32 v80, v0
	v_mov_b32_e32 v81, v0
	v_mov_b32_e32 v82, v0
	v_mov_b32_e32 v83, v0
	v_mov_b32_e32 v84, v0
	v_mov_b32_e32 v85, v0
	v_mov_b32_e32 v86, v0
	v_mov_b32_e32 v87, v0
	v_mov_b32_e32 v88, v0
	v_mov_b32_e32 v89, v0
	v_mov_b32_e32 v90, v0
	v_mov_b32_e32 v91, v0
	v_mov_b32_e32 v92, v0
	v_mov_b32_e32 v93, v0
	v_mov_b32_e32 v94, v0
	v_mov_b32_e32 v95, v0
	v_mov_b32_e32 v96, v0
	v_mov_b32_e32 v97, v0
	v_mov_b32_e32 v98, v0
	v_mov_b32_e32 v99, v0
	v_mov_b32_e32 v100, v0
	v_mov_b32_e32 v101, v0
	v_mov_b32_e32 v102, v0
	v_mov_b32_e32 v103, v0
	v_mov_b32_e32 v104, v0
	v_mov_b32_e32 v105, v0
	v_mov_b32_e32 v106, v0
	v_mov_b32_e32 v107, v0
	v_mov_b32_e32 v108, v0
	v_mov_b32_e32 v109, v0
	v_mov_b32_e32 v110, v0
	v_mov_b32_e32 v111, v0
	v_mov_b32_e32 v112, v0
	v_mov_b32_e32 v113, v0
	v_mov_b32_e32 v114, v0
	v_mov_b32_e32 v115, v0
	v_mov_b32_e32 v116, v0
	v_mov_b32_e32 v117, v0
	v_mov_b32_e32 v118, v0
	v_mov_b32_e32 v119, v0
	v_mov_b32_e32 v120, v0
	v_mov_b32_e32 v121, v0
	v_mov_b32_e32 v122, v0
	v_mov_b32_e32 v123, v0
	v_mov_b32_e32 v124, v0
	v_mov_b32_e32 v125, v0
	v_mov_b32_e32 v126, v0
	v_mov_b32_e32 v127, v0
	v_or_b32_e32 v235, v138, v239
	s_barrier
; #define WAIT_L(n) asm volatile("s_waitcnt lgkmcnt(" #n ")" ::: "memory")
; #define BAR __builtin_amdgcn_s_barrier()
; #define SCHED __builtin_amdgcn_sched_barrier(0)
;     ...
;   for (int t = 0; t < nt - 2; t += 2) {
;     LDB(B0, 0, 0); SCHED; LDA(At, 0, 0); STAGE(SA(1, 1), A, brow + HALF, t + 1);
;     WAIT_L(8); BAR; WAIT_L(0); MMA(0, 0, At, B0); BAR; SCHED;
	v_readfirstlane_b32 s11, v147
	v_writelane_b32 v254, s64, 0
	v_writelane_b32 v254, s65, 1
	v_writelane_b32 v254, s66, 2
	v_writelane_b32 v254, s67, 3
	v_writelane_b32 v254, s68, 4
	v_writelane_b32 v254, s69, 5
	v_writelane_b32 v254, s70, 6
	v_writelane_b32 v254, s71, 7
	v_writelane_b32 v254, s72, 8
	v_writelane_b32 v254, s73, 9
	v_writelane_b32 v254, s74, 10
	v_writelane_b32 v254, s75, 11
	v_writelane_b32 v254, s76, 12
	v_writelane_b32 v254, s77, 13
	v_writelane_b32 v254, s78, 14
	v_writelane_b32 v254, s79, 15
	v_writelane_b32 v254, s80, 16
	v_writelane_b32 v254, s81, 17
	v_writelane_b32 v254, s82, 18
	v_writelane_b32 v254, s83, 19
	v_writelane_b32 v254, s84, 20
	v_writelane_b32 v254, s85, 21
	v_writelane_b32 v254, s86, 22
	v_writelane_b32 v254, s87, 23
	v_writelane_b32 v254, s88, 24
	v_writelane_b32 v254, s89, 25
	v_writelane_b32 v254, s90, 26
	v_writelane_b32 v254, s91, 27
	v_writelane_b32 v254, s92, 28
	v_writelane_b32 v254, s93, 29
	v_writelane_b32 v254, s94, 30
	v_writelane_b32 v254, s95, 31
	v_readfirstlane_b32 s64, v134
	v_readfirstlane_b32 s65, v135
	v_readfirstlane_b32 s66, v136
	v_readfirstlane_b32 s67, v137
	v_readfirstlane_b32 s68, v130
	v_readfirstlane_b32 s69, v131
	v_readfirstlane_b32 s70, v132
	v_readfirstlane_b32 s71, v133
	v_readfirstlane_b32 s72, v134
	v_readfirstlane_b32 s73, v135
	v_readfirstlane_b32 s74, v136
	v_readfirstlane_b32 s75, v137
	v_readfirstlane_b32 s76, v130
	v_readfirstlane_b32 s77, v131
	v_readfirstlane_b32 s78, v132
	v_readfirstlane_b32 s79, v133
	v_readfirstlane_b32 s80, v134
	v_readfirstlane_b32 s81, v135
	v_readfirstlane_b32 s82, v136
	v_readfirstlane_b32 s83, v137
	v_readfirstlane_b32 s84, v130
	v_readfirstlane_b32 s85, v131
	v_readfirstlane_b32 s86, v132
	v_readfirstlane_b32 s87, v133
	v_readfirstlane_b32 s88, v134
	v_readfirstlane_b32 s89, v135
	v_readfirstlane_b32 s90, v136
	v_readfirstlane_b32 s91, v137
	v_readfirstlane_b32 s92, v130
	v_readfirstlane_b32 s93, v131
	v_readfirstlane_b32 s94, v132
	v_readfirstlane_b32 s95, v133
	s_nop 3
	v_subrev_u32_e32 v151, s64, v134
	v_subrev_u32_e32 v153, s66, v136
	v_subrev_u32_e32 v149, s68, v130
	v_subrev_u32_e32 v150, s70, v132
	s_add_u32 s64, s64, s8
	s_addc_u32 s65, s65, s9
	s_add_u32 s64, s64, s26
	s_addc_u32 s65, s65, s27
	s_add_u32 s66, s66, s8
	s_addc_u32 s67, s67, s9
	s_add_u32 s66, s66, s26
	s_addc_u32 s67, s67, s27
	s_add_u32 s68, s68, s8
	s_addc_u32 s69, s69, s9
	s_add_u32 s68, s68, s28
	s_addc_u32 s69, s69, s29
	s_add_u32 s70, s70, s8
	s_addc_u32 s71, s71, s9
	s_add_u32 s70, s70, s28
	s_addc_u32 s71, s71, s29
	s_add_u32 s72, s72, s8
	s_addc_u32 s73, s73, s9
	s_add_u32 s72, s72, s28
	s_addc_u32 s73, s73, s29
	s_add_u32 s74, s74, s8
	s_addc_u32 s75, s75, s9
	s_add_u32 s74, s74, s28
	s_addc_u32 s75, s75, s29
	s_add_u32 s76, s76, s8
	s_addc_u32 s77, s77, s9
	s_add_u32 s76, s76, s30
	s_addc_u32 s77, s77, s31
	s_add_u32 s78, s78, s8
	s_addc_u32 s79, s79, s9
	s_add_u32 s78, s78, s30
	s_addc_u32 s79, s79, s31
	s_add_u32 s80, s80, s8
	s_addc_u32 s81, s81, s9
	s_add_u32 s80, s80, s30
	s_addc_u32 s81, s81, s31
	s_add_u32 s82, s82, s8
	s_addc_u32 s83, s83, s9
	s_add_u32 s82, s82, s30
	s_addc_u32 s83, s83, s31
	s_add_u32 s84, s84, s8
	s_addc_u32 s85, s85, s9
	s_add_u32 s84, s84, s34
	s_addc_u32 s85, s85, s35
	s_add_u32 s86, s86, s8
	s_addc_u32 s87, s87, s9
	s_add_u32 s86, s86, s34
	s_addc_u32 s87, s87, s35
	s_add_u32 s88, s88, s8
	s_addc_u32 s89, s89, s9
	s_add_u32 s88, s88, s34
	s_addc_u32 s89, s89, s35
	s_add_u32 s90, s90, s8
	s_addc_u32 s91, s91, s9
	s_add_u32 s90, s90, s34
	s_addc_u32 s91, s91, s35
	s_add_u32 s92, s92, s8
	s_addc_u32 s93, s93, s9
	s_add_u32 s92, s92, s36
	s_addc_u32 s93, s93, s37
	s_add_u32 s94, s94, s8
	s_addc_u32 s95, s95, s9
	s_add_u32 s94, s94, s36
	s_addc_u32 s95, s95, s37
.LBB0_69:
	ds_read_b128 v[166:169], v162
	ds_read_b128 v[170:173], v162 offset:1024
	ds_read_b128 v[174:177], v162 offset:2048
	ds_read_b128 v[178:181], v162 offset:3072
	v_add_u32_e32 v163, 0xc000, v147
	s_add_u32 m0, s11, 0xc000
	ds_read_b128 v[186:189], v144
	ds_read_b128 v[190:193], v144 offset:1024
	ds_read_b128 v[194:197], v141
	ds_read_b128 v[198:201], v141 offset:1024
	ds_read_b128 v[202:205], v140
	ds_read_b128 v[206:209], v140 offset:1024
	ds_read_b128 v[210:213], v139
	ds_read_b128 v[214:217], v139 offset:1024
	global_load_lds_dwordx4 v151, s[64:65]
	s_add_u32 s64, s64, 0x100
	s_addc_u32 s65, s65, 0
	v_add_u32_e32 v164, 0xe000, v147
	s_add_u32 m0, s11, 0xe000
	s_nop 0
	global_load_lds_dwordx4 v153, s[66:67]
	s_add_u32 s66, s66, 0x100
	s_addc_u32 s67, s67, 0
	s_waitcnt lgkmcnt(8)
	s_barrier
	s_waitcnt lgkmcnt(0)
	s_waitcnt lgkmcnt(0)
	v_mfma_f32_16x16x32_bf16 v[124:127], v[166:169], v[186:189], v[124:127]
	v_mfma_f32_16x16x32_bf16 v[120:123], v[174:177], v[186:189], v[120:123]
	v_mfma_f32_16x16x32_bf16 v[116:119], v[166:169], v[194:197], v[116:119]
	v_mfma_f32_16x16x32_bf16 v[112:115], v[174:177], v[194:197], v[112:115]
	v_mfma_f32_16x16x32_bf16 v[108:111], v[166:169], v[202:205], v[108:111]
	v_mfma_f32_16x16x32_bf16 v[104:107], v[174:177], v[202:205], v[104:107]
	v_mfma_f32_16x16x32_bf16 v[100:103], v[166:169], v[210:213], v[100:103]
	v_mfma_f32_16x16x32_bf16 v[96:99], v[174:177], v[210:213], v[96:99]
	v_mfma_f32_16x16x32_bf16 v[124:127], v[170:173], v[190:193], v[124:127]
	v_mfma_f32_16x16x32_bf16 v[120:123], v[178:181], v[190:193], v[120:123]
	v_mfma_f32_16x16x32_bf16 v[116:119], v[170:173], v[198:201], v[116:119]
	v_mfma_f32_16x16x32_bf16 v[112:115], v[178:181], v[198:201], v[112:115]
	v_mfma_f32_16x16x32_bf16 v[108:111], v[170:173], v[206:209], v[108:111]
	v_mfma_f32_16x16x32_bf16 v[104:107], v[178:181], v[206:209], v[104:107]
	v_mfma_f32_16x16x32_bf16 v[100:103], v[170:173], v[214:217], v[100:103]
	v_mfma_f32_16x16x32_bf16 v[96:99], v[178:181], v[214:217], v[96:99]
	s_barrier
; #define WAIT_V(n) asm volatile("s_waitcnt vmcnt(" #n ")" ::: "memory")
; #define WAIT_L(n) asm volatile("s_waitcnt lgkmcnt(" #n ")" ::: "memory")
; #define BAR __builtin_amdgcn_s_barrier()
; #define SCHED __builtin_amdgcn_sched_barrier(0)
;     ...
;     LDB(B1, 0, 1); STAGE(SB(0, 0), Bt, bcol, t + 2);
;     BAR; WAIT_L(0); MMA(0, 1, At, B1); BAR;
;     LDA(At, 0, 1); STAGE(SA(0, 0), A, brow, t + 2);
;     BAR; WAIT_L(0); MMA(1, 0, At, B0); BAR; SCHED;
;     STAGE(SB(0, 1), Bt, bcol1, t + 2);
;     WAIT_V(6); BAR; MMA(1, 1, At, B1); BAR;
;     LDB(B0, 1, 0); SCHED; LDA(At, 1, 0); STAGE(SA(0, 1), A, brow + HALF, t + 2);
;     WAIT_L(8); BAR; WAIT_L(0); MMA(0, 0, At, B0); BAR; SCHED;
;     LDB(B1, 1, 1); STAGE(SB(1, 0), Bt, bcol, t + 3);
	s_add_u32 m0, s11, s33
	ds_read_b128 v[218:221], v161
	ds_read_b128 v[222:225], v161 offset:1024
	ds_read_b128 v[226:229], v161 offset:2048
	ds_read_b128 v[240:243], v161 offset:3072
	global_load_lds_dwordx4 v149, s[68:69]
	s_add_u32 s68, s68, 0x100
	s_addc_u32 s69, s69, 0
	s_add_u32 m0, s11, 0x2000
	s_add_u32 m0, m0, s33
	s_nop 0
	global_load_lds_dwordx4 v150, s[70:71]
	s_add_u32 s70, s70, 0x100
	s_addc_u32 s71, s71, 0
	s_barrier
	s_waitcnt lgkmcnt(0)
	s_waitcnt lgkmcnt(0)
	v_mfma_f32_16x16x32_bf16 v[92:95], v[218:221], v[186:189], v[92:95]
	v_mfma_f32_16x16x32_bf16 v[88:91], v[226:229], v[186:189], v[88:91]
	v_mfma_f32_16x16x32_bf16 v[84:87], v[218:221], v[194:197], v[84:87]
	v_mfma_f32_16x16x32_bf16 v[80:83], v[226:229], v[194:197], v[80:83]
	v_mfma_f32_16x16x32_bf16 v[76:79], v[218:221], v[202:205], v[76:79]
	v_mfma_f32_16x16x32_bf16 v[72:75], v[226:229], v[202:205], v[72:75]
	v_mfma_f32_16x16x32_bf16 v[68:71], v[218:221], v[210:213], v[68:71]
	v_mfma_f32_16x16x32_bf16 v[64:67], v[226:229], v[210:213], v[64:67]
	v_mfma_f32_16x16x32_bf16 v[92:95], v[222:225], v[190:193], v[92:95]
	v_mfma_f32_16x16x32_bf16 v[88:91], v[240:243], v[190:193], v[88:91]
	v_mfma_f32_16x16x32_bf16 v[84:87], v[222:225], v[198:201], v[84:87]
	v_mfma_f32_16x16x32_bf16 v[80:83], v[240:243], v[198:201], v[80:83]
	v_mfma_f32_16x16x32_bf16 v[76:79], v[222:225], v[206:209], v[76:79]
	v_mfma_f32_16x16x32_bf16 v[72:75], v[240:243], v[206:209], v[72:75]
	v_mfma_f32_16x16x32_bf16 v[68:71], v[222:225], v[214:217], v[68:71]
	v_mfma_f32_16x16x32_bf16 v[64:67], v[240:243], v[214:217], v[64:67]
	s_mov_b32 m0, s11
	s_barrier
	ds_read_b128 v[186:189], v144 offset:16384
	ds_read_b128 v[190:193], v144 offset:17408
	ds_read_b128 v[194:197], v141 offset:16384
	ds_read_b128 v[198:201], v141 offset:17408
	ds_read_b128 v[202:205], v140 offset:16384
	ds_read_b128 v[206:209], v140 offset:17408
	ds_read_b128 v[210:213], v139 offset:16384
	ds_read_b128 v[214:217], v139 offset:17408
	global_load_lds_dwordx4 v151, s[72:73]
	s_add_u32 s72, s72, 0x100
	s_addc_u32 s73, s73, 0
	s_add_u32 m0, s11, 0x2000
	s_nop 0
	global_load_lds_dwordx4 v153, s[74:75]
	s_add_u32 s74, s74, 0x100
	s_addc_u32 s75, s75, 0
	s_barrier
	s_waitcnt lgkmcnt(0)
	s_waitcnt lgkmcnt(0)
	v_mfma_f32_16x16x32_bf16 v[60:63], v[166:169], v[186:189], v[60:63]
	v_mfma_f32_16x16x32_bf16 v[56:59], v[174:177], v[186:189], v[56:59]
	v_mfma_f32_16x16x32_bf16 v[52:55], v[166:169], v[194:197], v[52:55]
	v_mfma_f32_16x16x32_bf16 v[48:51], v[174:177], v[194:197], v[48:51]
	v_mfma_f32_16x16x32_bf16 v[44:47], v[166:169], v[202:205], v[44:47]
	v_mfma_f32_16x16x32_bf16 v[40:43], v[174:177], v[202:205], v[40:43]
	v_mfma_f32_16x16x32_bf16 v[36:39], v[166:169], v[210:213], v[36:39]
	v_mfma_f32_16x16x32_bf16 v[32:35], v[174:177], v[210:213], v[32:35]
	v_mfma_f32_16x16x32_bf16 v[60:63], v[170:173], v[190:193], v[60:63]
	v_mfma_f32_16x16x32_bf16 v[56:59], v[178:181], v[190:193], v[56:59]
	v_mfma_f32_16x16x32_bf16 v[52:55], v[170:173], v[198:201], v[52:55]
	v_mfma_f32_16x16x32_bf16 v[48:51], v[178:181], v[198:201], v[48:51]
	v_mfma_f32_16x16x32_bf16 v[44:47], v[170:173], v[206:209], v[44:47]
	v_mfma_f32_16x16x32_bf16 v[40:43], v[178:181], v[206:209], v[40:43]
	v_mfma_f32_16x16x32_bf16 v[36:39], v[170:173], v[214:217], v[36:39]
	v_mfma_f32_16x16x32_bf16 v[32:35], v[178:181], v[214:217], v[32:35]
	s_barrier
	s_add_u32 m0, s11, s53
	s_nop 0
	global_load_lds_dwordx4 v149, s[76:77]
	s_add_u32 s76, s76, 0x100
	s_addc_u32 s77, s77, 0
	s_add_u32 m0, s11, 0x2000
	s_add_u32 m0, m0, s53
	s_nop 0
	global_load_lds_dwordx4 v150, s[78:79]
	s_add_u32 s78, s78, 0x100
	s_addc_u32 s79, s79, 0
	s_waitcnt vmcnt(6)
	s_barrier
	v_mfma_f32_16x16x32_bf16 v[28:31], v[218:221], v[186:189], v[28:31]
	v_mfma_f32_16x16x32_bf16 v[24:27], v[226:229], v[186:189], v[24:27]
	v_mfma_f32_16x16x32_bf16 v[20:23], v[218:221], v[194:197], v[20:23]
	v_mfma_f32_16x16x32_bf16 v[16:19], v[226:229], v[194:197], v[16:19]
	v_mfma_f32_16x16x32_bf16 v[12:15], v[218:221], v[202:205], v[12:15]
	v_mfma_f32_16x16x32_bf16 v[8:11], v[226:229], v[202:205], v[8:11]
	v_mfma_f32_16x16x32_bf16 v[4:7], v[218:221], v[210:213], v[4:7]
	v_mfma_f32_16x16x32_bf16 v[0:3], v[226:229], v[210:213], v[0:3]
	v_mfma_f32_16x16x32_bf16 v[28:31], v[222:225], v[190:193], v[28:31]
	v_mfma_f32_16x16x32_bf16 v[24:27], v[240:243], v[190:193], v[24:27]
	v_mfma_f32_16x16x32_bf16 v[20:23], v[222:225], v[198:201], v[20:23]
	v_mfma_f32_16x16x32_bf16 v[16:19], v[240:243], v[198:201], v[16:19]
	v_mfma_f32_16x16x32_bf16 v[12:15], v[222:225], v[206:209], v[12:15]
	v_mfma_f32_16x16x32_bf16 v[8:11], v[240:243], v[206:209], v[8:11]
	v_mfma_f32_16x16x32_bf16 v[4:7], v[222:225], v[214:217], v[4:7]
	v_mfma_f32_16x16x32_bf16 v[0:3], v[240:243], v[214:217], v[0:3]
	s_barrier
	ds_read_b128 v[166:169], v152
	ds_read_b128 v[170:173], v152 offset:1024
	ds_read_b128 v[174:177], v152 offset:2048
	ds_read_b128 v[178:181], v152 offset:3072
	s_add_u32 m0, s11, 0x4000
	ds_read_b128 v[186:189], v144 offset:32768
	ds_read_b128 v[190:193], v144 offset:33792
	ds_read_b128 v[194:197], v141 offset:32768
	ds_read_b128 v[198:201], v141 offset:33792
	ds_read_b128 v[202:205], v140 offset:32768
	ds_read_b128 v[206:209], v140 offset:33792
	ds_read_b128 v[210:213], v139 offset:32768
	ds_read_b128 v[214:217], v139 offset:33792
	global_load_lds_dwordx4 v151, s[80:81]
	s_add_u32 s80, s80, 0x100
	s_addc_u32 s81, s81, 0
	s_add_u32 m0, s11, 0x6000
	s_nop 0
	global_load_lds_dwordx4 v153, s[82:83]
	s_add_u32 s82, s82, 0x100
	s_addc_u32 s83, s83, 0
	s_waitcnt lgkmcnt(8)
	s_barrier
; #define WAIT_V(n) asm volatile("s_waitcnt vmcnt(" #n ")" ::: "memory")
; #define WAIT_L(n) asm volatile("s_waitcnt lgkmcnt(" #n ")" ::: "memory")
; #define BAR __builtin_amdgcn_s_barrier()
; #define SCHED __builtin_amdgcn_sched_barrier(0)
;     ...
;     WAIT_L(8); BAR; WAIT_L(0); MMA(0, 0, At, B0); BAR; SCHED;
;     LDB(B1, 1, 1); STAGE(SB(1, 0), Bt, bcol, t + 3);
;     BAR; WAIT_L(0); MMA(0, 1, At, B1); BAR;
;     LDA(At, 1, 1); STAGE(SA(1, 0), A, brow, t + 3);
;     BAR; WAIT_L(0); MMA(1, 0, At, B0); BAR; SCHED;
;     STAGE(SB(1, 1), Bt, bcol1, t + 3);
;     WAIT_V(6); BAR; MMA(1, 1, At, B1); BAR;
;   }
	s_waitcnt lgkmcnt(0)
	s_waitcnt lgkmcnt(0)
	v_mfma_f32_16x16x32_bf16 v[124:127], v[166:169], v[186:189], v[124:127]
	v_mfma_f32_16x16x32_bf16 v[120:123], v[174:177], v[186:189], v[120:123]
	v_mfma_f32_16x16x32_bf16 v[116:119], v[166:169], v[194:197], v[116:119]
	v_mfma_f32_16x16x32_bf16 v[112:115], v[174:177], v[194:197], v[112:115]
	v_mfma_f32_16x16x32_bf16 v[108:111], v[166:169], v[202:205], v[108:111]
	v_mfma_f32_16x16x32_bf16 v[104:107], v[174:177], v[202:205], v[104:107]
	v_mfma_f32_16x16x32_bf16 v[100:103], v[166:169], v[210:213], v[100:103]
	v_mfma_f32_16x16x32_bf16 v[96:99], v[174:177], v[210:213], v[96:99]
	v_mfma_f32_16x16x32_bf16 v[124:127], v[170:173], v[190:193], v[124:127]
	v_mfma_f32_16x16x32_bf16 v[120:123], v[178:181], v[190:193], v[120:123]
	v_mfma_f32_16x16x32_bf16 v[116:119], v[170:173], v[198:201], v[116:119]
	v_mfma_f32_16x16x32_bf16 v[112:115], v[178:181], v[198:201], v[112:115]
	v_mfma_f32_16x16x32_bf16 v[108:111], v[170:173], v[206:209], v[108:111]
	v_mfma_f32_16x16x32_bf16 v[104:107], v[178:181], v[206:209], v[104:107]
	v_mfma_f32_16x16x32_bf16 v[100:103], v[170:173], v[214:217], v[100:103]
	v_mfma_f32_16x16x32_bf16 v[96:99], v[178:181], v[214:217], v[96:99]
	s_barrier
	s_add_u32 m0, s11, s54
	ds_read_b128 v[218:221], v148
	ds_read_b128 v[222:225], v148 offset:1024
	ds_read_b128 v[226:229], v148 offset:2048
	ds_read_b128 v[240:243], v148 offset:3072
	global_load_lds_dwordx4 v149, s[84:85]
	s_add_u32 s84, s84, 0x100
	s_addc_u32 s85, s85, 0
	s_add_u32 m0, s11, 0x2000
	s_add_u32 m0, m0, s54
	s_nop 0
	global_load_lds_dwordx4 v150, s[86:87]
	s_add_u32 s86, s86, 0x100
	s_addc_u32 s87, s87, 0
	s_barrier
	s_waitcnt lgkmcnt(0)
	s_waitcnt lgkmcnt(0)
	v_mfma_f32_16x16x32_bf16 v[92:95], v[218:221], v[186:189], v[92:95]
	v_mfma_f32_16x16x32_bf16 v[88:91], v[226:229], v[186:189], v[88:91]
	v_mfma_f32_16x16x32_bf16 v[84:87], v[218:221], v[194:197], v[84:87]
	v_mfma_f32_16x16x32_bf16 v[80:83], v[226:229], v[194:197], v[80:83]
	v_mfma_f32_16x16x32_bf16 v[76:79], v[218:221], v[202:205], v[76:79]
	v_mfma_f32_16x16x32_bf16 v[72:75], v[226:229], v[202:205], v[72:75]
	v_mfma_f32_16x16x32_bf16 v[68:71], v[218:221], v[210:213], v[68:71]
	v_mfma_f32_16x16x32_bf16 v[64:67], v[226:229], v[210:213], v[64:67]
	v_mfma_f32_16x16x32_bf16 v[92:95], v[222:225], v[190:193], v[92:95]
	v_mfma_f32_16x16x32_bf16 v[88:91], v[240:243], v[190:193], v[88:91]
	v_mfma_f32_16x16x32_bf16 v[84:87], v[222:225], v[198:201], v[84:87]
	v_mfma_f32_16x16x32_bf16 v[80:83], v[240:243], v[198:201], v[80:83]
	v_mfma_f32_16x16x32_bf16 v[76:79], v[222:225], v[206:209], v[76:79]
	v_mfma_f32_16x16x32_bf16 v[72:75], v[240:243], v[206:209], v[72:75]
	v_mfma_f32_16x16x32_bf16 v[68:71], v[222:225], v[214:217], v[68:71]
	v_mfma_f32_16x16x32_bf16 v[64:67], v[240:243], v[214:217], v[64:67]
	s_add_u32 m0, s11, 0x8000
	s_barrier
	ds_read_b128 v[186:189], v144 offset:49152
	ds_read_b128 v[190:193], v144 offset:50176
	ds_read_b128 v[194:197], v141 offset:49152
	ds_read_b128 v[198:201], v141 offset:50176
	ds_read_b128 v[202:205], v140 offset:49152
	ds_read_b128 v[206:209], v140 offset:50176
	ds_read_b128 v[210:213], v139 offset:49152
	ds_read_b128 v[214:217], v139 offset:50176
	global_load_lds_dwordx4 v151, s[88:89]
	s_add_u32 s88, s88, 0x100
	s_addc_u32 s89, s89, 0
	s_add_u32 m0, s11, 0xa000
	s_nop 0
	global_load_lds_dwordx4 v153, s[90:91]
	s_add_u32 s90, s90, 0x100
	s_addc_u32 s91, s91, 0
	s_barrier
	s_waitcnt lgkmcnt(0)
	s_waitcnt lgkmcnt(0)
	v_mfma_f32_16x16x32_bf16 v[60:63], v[166:169], v[186:189], v[60:63]
	v_mfma_f32_16x16x32_bf16 v[56:59], v[174:177], v[186:189], v[56:59]
	v_mfma_f32_16x16x32_bf16 v[52:55], v[166:169], v[194:197], v[52:55]
	v_mfma_f32_16x16x32_bf16 v[48:51], v[174:177], v[194:197], v[48:51]
	v_mfma_f32_16x16x32_bf16 v[44:47], v[166:169], v[202:205], v[44:47]
	v_mfma_f32_16x16x32_bf16 v[40:43], v[174:177], v[202:205], v[40:43]
	v_mfma_f32_16x16x32_bf16 v[36:39], v[166:169], v[210:213], v[36:39]
	v_mfma_f32_16x16x32_bf16 v[32:35], v[174:177], v[210:213], v[32:35]
	v_mfma_f32_16x16x32_bf16 v[60:63], v[170:173], v[190:193], v[60:63]
	v_mfma_f32_16x16x32_bf16 v[56:59], v[178:181], v[190:193], v[56:59]
	v_mfma_f32_16x16x32_bf16 v[52:55], v[170:173], v[198:201], v[52:55]
	v_mfma_f32_16x16x32_bf16 v[48:51], v[178:181], v[198:201], v[48:51]
	v_mfma_f32_16x16x32_bf16 v[44:47], v[170:173], v[206:209], v[44:47]
	v_mfma_f32_16x16x32_bf16 v[40:43], v[178:181], v[206:209], v[40:43]
	v_mfma_f32_16x16x32_bf16 v[36:39], v[170:173], v[214:217], v[36:39]
	v_mfma_f32_16x16x32_bf16 v[32:35], v[178:181], v[214:217], v[32:35]
	s_barrier
	s_add_u32 m0, s11, s55
	s_nop 0
	global_load_lds_dwordx4 v149, s[92:93]
	s_add_u32 s92, s92, 0x100
	s_addc_u32 s93, s93, 0
	s_add_u32 m0, s11, 0x2000
	s_add_u32 m0, m0, s55
	s_nop 0
	global_load_lds_dwordx4 v150, s[94:95]
	s_add_u32 s94, s94, 0x100
	s_addc_u32 s95, s95, 0
	s_waitcnt vmcnt(6)
	s_barrier
	v_mfma_f32_16x16x32_bf16 v[28:31], v[218:221], v[186:189], v[28:31]
	v_mfma_f32_16x16x32_bf16 v[24:27], v[226:229], v[186:189], v[24:27]
	v_mfma_f32_16x16x32_bf16 v[20:23], v[218:221], v[194:197], v[20:23]
	v_mfma_f32_16x16x32_bf16 v[16:19], v[226:229], v[194:197], v[16:19]
	v_mfma_f32_16x16x32_bf16 v[12:15], v[218:221], v[202:205], v[12:15]
	v_mfma_f32_16x16x32_bf16 v[8:11], v[226:229], v[202:205], v[8:11]
	v_mfma_f32_16x16x32_bf16 v[4:7], v[218:221], v[210:213], v[4:7]
	v_mfma_f32_16x16x32_bf16 v[0:3], v[226:229], v[210:213], v[0:3]
	v_mfma_f32_16x16x32_bf16 v[28:31], v[222:225], v[190:193], v[28:31]
	v_mfma_f32_16x16x32_bf16 v[24:27], v[240:243], v[190:193], v[24:27]
	v_mfma_f32_16x16x32_bf16 v[20:23], v[222:225], v[198:201], v[20:23]
	v_mfma_f32_16x16x32_bf16 v[16:19], v[240:243], v[198:201], v[16:19]
	v_mfma_f32_16x16x32_bf16 v[12:15], v[222:225], v[206:209], v[12:15]
	v_mfma_f32_16x16x32_bf16 v[8:11], v[240:243], v[206:209], v[8:11]
	v_mfma_f32_16x16x32_bf16 v[4:7], v[222:225], v[214:217], v[4:7]
	v_mfma_f32_16x16x32_bf16 v[0:3], v[240:243], v[214:217], v[0:3]
	s_add_i32 s10, s10, 2
	s_add_u32 s8, s8, 0x100
	s_addc_u32 s9, s9, 0
	s_cmp_lt_u32 s10, 60
	s_barrier
; #define WAIT_V(n) asm volatile("s_waitcnt vmcnt(" #n ")" ::: "memory")
; #define WAIT_L(n) asm volatile("s_waitcnt lgkmcnt(" #n ")" ::: "memory")
; #define BAR __builtin_amdgcn_s_barrier()
;     ...
;   }
;   { LDB(B0, 0, 0); LDA(At, 0, 0); STAGE(SA(1, 1), A, brow + HALF, nt - 1);
;     BAR; WAIT_L(0); MMA(0, 0, At, B0); BAR;
;     LDB(B1, 0, 1); BAR; WAIT_L(0); MMA(0, 1, At, B1); BAR;
;     LDA(At, 0, 1); WAIT_V(4); BAR; WAIT_L(0); MMA(1, 0, At, B0); MMA(1, 1, At, B1); BAR; }
;   { LDB(B0, 1, 0); LDA(At, 1, 0); WAIT_V(2); BAR; WAIT_L(0); MMA(0, 0, At, B0); BAR;
	s_cbranch_scc1 .LBB0_69
	v_readlane_b32 s64, v254, 0
	v_readlane_b32 s65, v254, 1
	v_readlane_b32 s66, v254, 2
	v_readlane_b32 s67, v254, 3
	v_readlane_b32 s68, v254, 4
	v_readlane_b32 s69, v254, 5
	v_readlane_b32 s70, v254, 6
	v_readlane_b32 s71, v254, 7
	v_readlane_b32 s72, v254, 8
	v_readlane_b32 s73, v254, 9
	v_readlane_b32 s74, v254, 10
	v_readlane_b32 s75, v254, 11
	v_readlane_b32 s76, v254, 12
	v_readlane_b32 s77, v254, 13
	v_readlane_b32 s78, v254, 14
	v_readlane_b32 s79, v254, 15
	v_readlane_b32 s80, v254, 16
	v_readlane_b32 s81, v254, 17
	v_readlane_b32 s82, v254, 18
	v_readlane_b32 s83, v254, 19
	v_readlane_b32 s84, v254, 20
	v_readlane_b32 s85, v254, 21
	v_readlane_b32 s86, v254, 22
	v_readlane_b32 s87, v254, 23
	v_readlane_b32 s88, v254, 24
	v_readlane_b32 s89, v254, 25
	v_readlane_b32 s90, v254, 26
	v_readlane_b32 s91, v254, 27
	v_readlane_b32 s92, v254, 28
	v_readlane_b32 s93, v254, 29
	v_readlane_b32 s94, v254, 30
	v_readlane_b32 s95, v254, 31
	s_nop 4
	s_add_u32 s4, s4, 0x1f80
	s_addc_u32 s5, s5, 0
	v_readfirstlane_b32 s8, v163
	v_lshl_add_u64 v[146:147], s[4:5], 0, v[184:185]
	s_mov_b32 m0, s8
	v_lshl_add_u64 v[128:129], s[4:5], 0, v[128:129]
	v_readfirstlane_b32 s4, v164
	ds_read_b128 v[130:133], v162
	ds_read_b128 v[134:137], v162 offset:1024
	ds_read_b128 v[154:157], v162 offset:2048
	ds_read_b128 v[166:169], v162 offset:3072
	ds_read_b128 v[170:173], v144
	ds_read_b128 v[174:177], v144 offset:1024
	ds_read_b128 v[178:181], v141
	ds_read_b128 v[186:189], v141 offset:1024
	ds_read_b128 v[190:193], v140
	ds_read_b128 v[194:197], v140 offset:1024
	ds_read_b128 v[198:201], v139
	ds_read_b128 v[202:205], v139 offset:1024
	global_load_lds_dwordx4 v[146:147], off
	s_mov_b32 m0, s4
	s_nop 0
	global_load_lds_dwordx4 v[128:129], off
	s_barrier
	s_waitcnt lgkmcnt(0)
	s_waitcnt lgkmcnt(0)
	v_mfma_f32_16x16x32_bf16 v[124:127], v[130:133], v[170:173], v[124:127]
	v_mfma_f32_16x16x32_bf16 v[120:123], v[154:157], v[170:173], v[120:123]
	v_mfma_f32_16x16x32_bf16 v[116:119], v[130:133], v[178:181], v[116:119]
	v_mfma_f32_16x16x32_bf16 v[108:111], v[130:133], v[190:193], v[108:111]
	v_mfma_f32_16x16x32_bf16 v[104:107], v[154:157], v[190:193], v[104:107]
	v_mfma_f32_16x16x32_bf16 v[124:127], v[134:137], v[174:177], v[124:127]
	v_mfma_f32_16x16x32_bf16 v[120:123], v[166:169], v[174:177], v[120:123]
	v_mfma_f32_16x16x32_bf16 v[116:119], v[134:137], v[186:189], v[116:119]
	v_mfma_f32_16x16x32_bf16 v[112:115], v[154:157], v[178:181], v[112:115]
	v_mfma_f32_16x16x32_bf16 v[108:111], v[134:137], v[194:197], v[108:111]
	v_mfma_f32_16x16x32_bf16 v[104:107], v[166:169], v[194:197], v[104:107]
	v_mfma_f32_16x16x32_bf16 v[100:103], v[130:133], v[198:201], v[100:103]
	v_mfma_f32_16x16x32_bf16 v[96:99], v[154:157], v[198:201], v[96:99]
	v_mfma_f32_16x16x32_bf16 v[162:165], v[166:169], v[186:189], v[112:115]
	v_mfma_f32_16x16x32_bf16 v[206:209], v[134:137], v[202:205], v[100:103]
	v_mfma_f32_16x16x32_bf16 v[210:213], v[166:169], v[202:205], v[96:99]
	s_barrier
	s_nop 2
	ds_read_b128 v[96:99], v161
	ds_read_b128 v[100:103], v161 offset:1024
	ds_read_b128 v[112:115], v161 offset:2048
	ds_read_b128 v[158:161], v161 offset:3072
	s_barrier
	s_waitcnt lgkmcnt(0)
	s_waitcnt lgkmcnt(0)
	v_mfma_f32_16x16x32_bf16 v[92:95], v[96:99], v[170:173], v[92:95]
	v_mfma_f32_16x16x32_bf16 v[88:91], v[112:115], v[170:173], v[88:91]
	v_mfma_f32_16x16x32_bf16 v[84:87], v[96:99], v[178:181], v[84:87]
	v_mfma_f32_16x16x32_bf16 v[76:79], v[96:99], v[190:193], v[76:79]
	v_mfma_f32_16x16x32_bf16 v[72:75], v[112:115], v[190:193], v[72:75]
	v_mfma_f32_16x16x32_bf16 v[92:95], v[100:103], v[174:177], v[92:95]
	v_mfma_f32_16x16x32_bf16 v[88:91], v[158:161], v[174:177], v[88:91]
	v_mfma_f32_16x16x32_bf16 v[84:87], v[100:103], v[186:189], v[84:87]
	v_mfma_f32_16x16x32_bf16 v[80:83], v[112:115], v[178:181], v[80:83]
	v_mfma_f32_16x16x32_bf16 v[76:79], v[100:103], v[194:197], v[76:79]
	v_mfma_f32_16x16x32_bf16 v[72:75], v[158:161], v[194:197], v[72:75]
	v_mfma_f32_16x16x32_bf16 v[68:71], v[96:99], v[198:201], v[68:71]
	v_mfma_f32_16x16x32_bf16 v[64:67], v[112:115], v[198:201], v[64:67]
	v_mfma_f32_16x16x32_bf16 v[170:173], v[158:161], v[186:189], v[80:83]
	v_mfma_f32_16x16x32_bf16 v[174:177], v[100:103], v[202:205], v[68:71]
	v_mfma_f32_16x16x32_bf16 v[178:181], v[158:161], v[202:205], v[64:67]
	s_barrier
	s_nop 2
	ds_read_b128 v[64:67], v144 offset:16384
	ds_read_b128 v[68:71], v144 offset:17408
	ds_read_b128 v[80:83], v141 offset:16384
	ds_read_b128 v[186:189], v141 offset:17408
	ds_read_b128 v[190:193], v140 offset:16384
	ds_read_b128 v[194:197], v140 offset:17408
	ds_read_b128 v[198:201], v139 offset:16384
	ds_read_b128 v[202:205], v139 offset:17408
	s_waitcnt vmcnt(4)
	s_barrier
; #define WAIT_V(n) asm volatile("s_waitcnt vmcnt(" #n ")" ::: "memory")
; #define WAIT_L(n) asm volatile("s_waitcnt lgkmcnt(" #n ")" ::: "memory")
; #define BAR __builtin_amdgcn_s_barrier()
;     ...
;     LDA(At, 0, 1); WAIT_V(4); BAR; WAIT_L(0); MMA(1, 0, At, B0); MMA(1, 1, At, B1); BAR; }
;   { LDB(B0, 1, 0); LDA(At, 1, 0); WAIT_V(2); BAR; WAIT_L(0); MMA(0, 0, At, B0); BAR;
	s_waitcnt lgkmcnt(0)
	s_waitcnt lgkmcnt(0)
	v_mfma_f32_16x16x32_bf16 v[60:63], v[130:133], v[64:67], v[60:63]
	v_mfma_f32_16x16x32_bf16 v[56:59], v[154:157], v[64:67], v[56:59]
	v_mfma_f32_16x16x32_bf16 v[52:55], v[130:133], v[80:83], v[52:55]
	v_mfma_f32_16x16x32_bf16 v[44:47], v[130:133], v[190:193], v[44:47]
	v_mfma_f32_16x16x32_bf16 v[40:43], v[154:157], v[190:193], v[40:43]
	v_mfma_f32_16x16x32_bf16 v[60:63], v[134:137], v[68:71], v[60:63]
	v_mfma_f32_16x16x32_bf16 v[56:59], v[166:169], v[68:71], v[56:59]
	v_mfma_f32_16x16x32_bf16 v[52:55], v[134:137], v[186:189], v[52:55]
	v_mfma_f32_16x16x32_bf16 v[48:51], v[154:157], v[80:83], v[48:51]
	v_mfma_f32_16x16x32_bf16 v[44:47], v[134:137], v[194:197], v[44:47]
	v_mfma_f32_16x16x32_bf16 v[40:43], v[166:169], v[194:197], v[40:43]
	v_mfma_f32_16x16x32_bf16 v[36:39], v[130:133], v[198:201], v[36:39]
	v_mfma_f32_16x16x32_bf16 v[32:35], v[154:157], v[198:201], v[32:35]
	v_mfma_f32_16x16x32_bf16 v[214:217], v[166:169], v[186:189], v[48:51]
	v_mfma_f32_16x16x32_bf16 v[128:131], v[134:137], v[202:205], v[36:39]
	v_mfma_f32_16x16x32_bf16 v[132:135], v[166:169], v[202:205], v[32:35]
	v_mfma_f32_16x16x32_bf16 v[28:31], v[96:99], v[64:67], v[28:31]
	v_mfma_f32_16x16x32_bf16 v[24:27], v[112:115], v[64:67], v[24:27]
	v_mfma_f32_16x16x32_bf16 v[20:23], v[96:99], v[80:83], v[20:23]
	v_mfma_f32_16x16x32_bf16 v[12:15], v[96:99], v[190:193], v[12:15]
	v_mfma_f32_16x16x32_bf16 v[8:11], v[112:115], v[190:193], v[8:11]
	v_mfma_f32_16x16x32_bf16 v[28:31], v[100:103], v[68:71], v[28:31]
	v_mfma_f32_16x16x32_bf16 v[24:27], v[158:161], v[68:71], v[24:27]
	v_mfma_f32_16x16x32_bf16 v[20:23], v[100:103], v[186:189], v[20:23]
	v_mfma_f32_16x16x32_bf16 v[16:19], v[112:115], v[80:83], v[16:19]
	v_mfma_f32_16x16x32_bf16 v[12:15], v[100:103], v[194:197], v[12:15]
	v_mfma_f32_16x16x32_bf16 v[8:11], v[158:161], v[194:197], v[8:11]
	v_mfma_f32_16x16x32_bf16 v[4:7], v[96:99], v[198:201], v[4:7]
	v_mfma_f32_16x16x32_bf16 v[0:3], v[112:115], v[198:201], v[0:3]
	v_mfma_f32_16x16x32_bf16 v[154:157], v[158:161], v[186:189], v[16:19]
	v_mfma_f32_16x16x32_bf16 v[166:169], v[100:103], v[202:205], v[4:7]
	v_mfma_f32_16x16x32_bf16 v[158:161], v[158:161], v[202:205], v[0:3]
	s_barrier
	s_nop 2
	ds_read_b128 v[0:3], v152
	ds_read_b128 v[4:7], v152 offset:1024
	ds_read_b128 v[16:19], v152 offset:2048
	ds_read_b128 v[150:153], v152 offset:3072
	ds_read_b128 v[32:35], v144 offset:32768
	ds_read_b128 v[36:39], v144 offset:33792
	ds_read_b128 v[48:51], v141 offset:32768
	ds_read_b128 v[68:71], v141 offset:33792
	ds_read_b128 v[186:189], v140 offset:32768
	ds_read_b128 v[190:193], v140 offset:33792
	ds_read_b128 v[194:197], v139 offset:32768
	ds_read_b128 v[198:201], v139 offset:33792
	s_waitcnt vmcnt(2)
	s_barrier
	s_waitcnt lgkmcnt(0)
	s_waitcnt lgkmcnt(0)
	v_mfma_f32_16x16x32_bf16 v[64:67], v[0:3], v[32:35], v[124:127]
	v_mfma_f32_16x16x32_bf16 v[112:115], v[4:7], v[36:39], v[64:67]
	v_mfma_f32_16x16x32_bf16 v[64:67], v[16:19], v[32:35], v[120:123]
	v_mfma_f32_16x16x32_bf16 v[96:99], v[150:153], v[36:39], v[64:67]
	v_mfma_f32_16x16x32_bf16 v[64:67], v[0:3], v[48:51], v[116:119]
	v_mfma_f32_16x16x32_bf16 v[116:119], v[4:7], v[68:71], v[64:67]
	v_mfma_f32_16x16x32_bf16 v[64:67], v[16:19], v[48:51], v[162:165]
	v_mfma_f32_16x16x32_bf16 v[100:103], v[150:153], v[68:71], v[64:67]
	v_mfma_f32_16x16x32_bf16 v[64:67], v[0:3], v[186:189], v[108:111]
	v_mfma_f32_16x16x32_bf16 v[120:123], v[4:7], v[190:193], v[64:67]
	v_mfma_f32_16x16x32_bf16 v[64:67], v[16:19], v[186:189], v[104:107]
	v_mfma_f32_16x16x32_bf16 v[104:107], v[150:153], v[190:193], v[64:67]
	v_mfma_f32_16x16x32_bf16 v[64:67], v[0:3], v[194:197], v[206:209]
	v_mfma_f32_16x16x32_bf16 v[124:127], v[4:7], v[198:201], v[64:67]
	v_mfma_f32_16x16x32_bf16 v[64:67], v[16:19], v[194:197], v[210:213]
	v_mfma_f32_16x16x32_bf16 v[108:111], v[150:153], v[198:201], v[64:67]
	s_barrier
; #define WAIT_V(n) asm volatile("s_waitcnt vmcnt(" #n ")" ::: "memory")
; #define WAIT_L(n) asm volatile("s_waitcnt lgkmcnt(" #n ")" ::: "memory")
; #define BAR __builtin_amdgcn_s_barrier()
;     ...
;   { LDB(B0, 1, 0); LDA(At, 1, 0); WAIT_V(2); BAR; WAIT_L(0); MMA(0, 0, At, B0); BAR;
;     LDB(B1, 1, 1); WAIT_V(0); BAR; WAIT_L(0); MMA(0, 1, At, B1); BAR;
;     LDA(At, 1, 1); BAR; WAIT_L(0); MMA(1, 0, At, B0); MMA(1, 1, At, B1); BAR; }
;   if (wr == 0) BAR;
	ds_read_b128 v[162:165], v148
	ds_read_b128 v[202:205], v148 offset:1024
	ds_read_b128 v[206:209], v148 offset:2048
	ds_read_b128 v[146:149], v148 offset:3072
	s_waitcnt vmcnt(0)
	s_barrier
	s_waitcnt lgkmcnt(0)
	s_waitcnt lgkmcnt(0)
	v_mfma_f32_16x16x32_bf16 v[64:67], v[162:165], v[32:35], v[92:95]
	v_mfma_f32_16x16x32_bf16 v[32:35], v[206:209], v[32:35], v[88:91]
	v_mfma_f32_16x16x32_bf16 v[80:83], v[202:205], v[36:39], v[64:67]
	v_mfma_f32_16x16x32_bf16 v[64:67], v[146:149], v[36:39], v[32:35]
	v_mfma_f32_16x16x32_bf16 v[32:35], v[162:165], v[48:51], v[84:87]
	v_mfma_f32_16x16x32_bf16 v[84:87], v[202:205], v[68:71], v[32:35]
	v_mfma_f32_16x16x32_bf16 v[32:35], v[206:209], v[48:51], v[170:173]
	v_mfma_f32_16x16x32_bf16 v[68:71], v[146:149], v[68:71], v[32:35]
	v_mfma_f32_16x16x32_bf16 v[32:35], v[162:165], v[186:189], v[76:79]
	v_mfma_f32_16x16x32_bf16 v[88:91], v[202:205], v[190:193], v[32:35]
	v_mfma_f32_16x16x32_bf16 v[32:35], v[206:209], v[186:189], v[72:75]
	v_mfma_f32_16x16x32_bf16 v[72:75], v[146:149], v[190:193], v[32:35]
	v_mfma_f32_16x16x32_bf16 v[32:35], v[162:165], v[194:197], v[174:177]
	v_mfma_f32_16x16x32_bf16 v[92:95], v[202:205], v[198:201], v[32:35]
	v_mfma_f32_16x16x32_bf16 v[32:35], v[206:209], v[194:197], v[178:181]
	v_mfma_f32_16x16x32_bf16 v[76:79], v[146:149], v[198:201], v[32:35]
	s_barrier
	ds_read_b128 v[170:173], v144 offset:49152
	ds_read_b128 v[174:177], v144 offset:50176
	ds_read_b128 v[178:181], v141 offset:49152
	ds_read_b128 v[186:189], v141 offset:50176
	ds_read_b128 v[190:193], v140 offset:49152
	ds_read_b128 v[194:197], v140 offset:50176
	ds_read_b128 v[198:201], v139 offset:49152
	ds_read_b128 v[210:213], v139 offset:50176
	s_barrier
	s_waitcnt lgkmcnt(0)
	s_waitcnt lgkmcnt(0)
	v_mfma_f32_16x16x32_bf16 v[32:35], v[0:3], v[170:173], v[60:63]
	v_mfma_f32_16x16x32_bf16 v[36:39], v[0:3], v[178:181], v[52:55]
	v_mfma_f32_16x16x32_bf16 v[44:47], v[0:3], v[190:193], v[44:47]
	v_mfma_f32_16x16x32_bf16 v[0:3], v[0:3], v[198:201], v[128:131]
	v_mfma_f32_16x16x32_bf16 v[48:51], v[4:7], v[174:177], v[32:35]
	v_mfma_f32_16x16x32_bf16 v[32:35], v[16:19], v[170:173], v[56:59]
	v_mfma_f32_16x16x32_bf16 v[52:55], v[4:7], v[186:189], v[36:39]
	v_mfma_f32_16x16x32_bf16 v[36:39], v[16:19], v[178:181], v[214:217]
	v_mfma_f32_16x16x32_bf16 v[40:43], v[16:19], v[190:193], v[40:43]
	v_mfma_f32_16x16x32_bf16 v[60:63], v[4:7], v[210:213], v[0:3]
	v_mfma_f32_16x16x32_bf16 v[0:3], v[16:19], v[198:201], v[132:135]
	v_mfma_f32_16x16x32_bf16 v[32:35], v[150:153], v[174:177], v[32:35]
	v_mfma_f32_16x16x32_bf16 v[36:39], v[150:153], v[186:189], v[36:39]
	v_mfma_f32_16x16x32_bf16 v[56:59], v[4:7], v[194:197], v[44:47]
	v_mfma_f32_16x16x32_bf16 v[40:43], v[150:153], v[194:197], v[40:43]
	v_mfma_f32_16x16x32_bf16 v[44:47], v[150:153], v[210:213], v[0:3]
	v_mfma_f32_16x16x32_bf16 v[0:3], v[162:165], v[170:173], v[28:31]
	v_mfma_f32_16x16x32_bf16 v[12:15], v[162:165], v[190:193], v[12:15]
	v_mfma_f32_16x16x32_bf16 v[16:19], v[202:205], v[174:177], v[0:3]
	v_mfma_f32_16x16x32_bf16 v[0:3], v[206:209], v[170:173], v[24:27]
	v_mfma_f32_16x16x32_bf16 v[4:7], v[162:165], v[178:181], v[20:23]
	v_mfma_f32_16x16x32_bf16 v[24:27], v[202:205], v[194:197], v[12:15]
	v_mfma_f32_16x16x32_bf16 v[12:15], v[162:165], v[198:201], v[166:169]
	v_mfma_f32_16x16x32_bf16 v[20:23], v[202:205], v[186:189], v[4:7]
	v_mfma_f32_16x16x32_bf16 v[4:7], v[206:209], v[178:181], v[154:157]
	v_mfma_f32_16x16x32_bf16 v[8:11], v[206:209], v[190:193], v[8:11]
	v_mfma_f32_16x16x32_bf16 v[28:31], v[202:205], v[210:213], v[12:15]
	v_mfma_f32_16x16x32_bf16 v[12:15], v[206:209], v[198:201], v[158:161]
	v_mfma_f32_16x16x32_bf16 v[0:3], v[146:149], v[174:177], v[0:3]
	v_mfma_f32_16x16x32_bf16 v[4:7], v[146:149], v[186:189], v[4:7]
	v_mfma_f32_16x16x32_bf16 v[8:11], v[146:149], v[194:197], v[8:11]
	v_mfma_f32_16x16x32_bf16 v[12:15], v[146:149], v[210:213], v[12:15]
	v_cmp_gt_u32_e32 vcc, s57, v143
	s_barrier
	s_and_saveexec_b64 s[4:5], vcc
	s_cbranch_execz .LBB0_72
	s_barrier

; #define WAIT_V(n) asm volatile("s_waitcnt vmcnt(" #n ")" ::: "memory")
; #define BAR __builtin_amdgcn_s_barrier()
;     ...
;   const int wid = tx >> 6, lane = tx & 63, wr = wid >> 2, wc = wid & 3, fr = lane & 15, fq = lane >> 4;
;   f32x4 acc[2][2][4][2] = {};
;   bf16x8 At[4][2], B0[2][2], B1[2][2];
;   const int nt = K / BK;
;   unsigned soff0, soff1;
;   { int _r, _c; stage_rc(tx * 16, _r, _c); soff0 = (unsigned)(_r * K + _c) * 2u;
;     stage_rc(tx * 16 + 8192, _r, _c); soff1 = (unsigned)(_r * K + _c) * 2u; }
;   STAGE(SB(0, 0), Bt, bcol, 0); STAGE(SA(0, 0), A, brow, 0);
;   STAGE(SB(0, 1), Bt, bcol1, 0); STAGE(SA(0, 1), A, brow + HALF, 0);
;   if (wr == 1) BAR;
;   WAIT_V(4); BAR;
;   STAGE(SB(1, 0), Bt, bcol, 1); STAGE(SA(1, 0), A, brow, 1); STAGE(SB(1, 1), Bt, bcol1, 1);
;   WAIT_V(6); BAR;
.LBB0_1141:
	s_or_b64 exec, exec, s[34:35]
	v_add_u32_e32 v162, s38, v18
	v_add_u32_e32 v163, 0x2000, v162
	v_readfirstlane_b32 s25, v162
	v_lshl_add_u64 v[10:11], v[10:11], 0, s[12:13]
	s_mov_b32 m0, s25
	v_readfirstlane_b32 s25, v163
	v_add_u32_e32 v164, 0x8000, v154
	s_waitcnt vmcnt(4)
	s_barrier
	global_load_lds_dwordx4 v[10:11], off
	v_lshl_add_u64 v[8:9], v[8:9], 0, s[12:13]
	s_mov_b32 m0, s25
	v_readfirstlane_b32 s25, v164
	v_add_u32_e32 v165, 0xa000, v154
	global_load_lds_dwordx4 v[8:9], off
	v_lshl_add_u64 v[6:7], v[6:7], 0, s[12:13]
	s_mov_b32 m0, s25
	v_readfirstlane_b32 s25, v165
	v_add_u32_e32 v166, s39, v18
	global_load_lds_dwordx4 v[6:7], off
	v_lshl_add_u64 v[4:5], v[4:5], 0, s[12:13]
	s_mov_b32 m0, s25
	v_readfirstlane_b32 s25, v166
	v_add_u32_e32 v167, 0x2000, v166
	global_load_lds_dwordx4 v[4:5], off
	v_lshl_add_u64 v[2:3], v[2:3], 0, s[12:13]
	s_mov_b32 m0, s25
	v_readfirstlane_b32 s25, v167
	global_load_lds_dwordx4 v[2:3], off
	v_lshl_add_u64 v[0:1], v[0:1], 0, s[12:13]
	s_mov_b32 m0, s25
	v_and_b32_e32 v142, 15, v140
	global_load_lds_dwordx4 v[0:1], off
	v_lshlrev_b32_e32 v2, 2, v140
	v_and_b32_e32 v0, 48, v140
	v_lshlrev_b32_e32 v1, 6, v142
	v_and_b32_e32 v2, 32, v2
	v_bitop3_b32 v1, v1, v2, v0 bitop3:0x36
	v_add_u32_e32 v5, s36, v1
	v_add_u32_e32 v6, s37, v1
	v_add_u32_e32 v7, s38, v1
	v_add_u32_e32 v8, s39, v1
	v_add_u32_e32 v10, 0, v1
	v_lshlrev_b32_e32 v1, 6, v140
	v_and_or_b32 v0, v1, s40, v0
	v_xad_u32 v11, v0, v2, 0
	v_lshlrev_b32_e32 v0, 16, v12
	v_lshlrev_b32_e32 v2, 16, v14
	v_and_b32_e32 v0, 0xfffe0000, v0
	v_and_b32_e32 v2, 0xfffe0000, v2
	v_lshl_add_u32 v0, v13, 13, v0
	v_and_b32_e32 v1, 1, v12
	v_lshl_add_u32 v2, v16, 13, v2
	v_and_b32_e32 v3, 1, v14
	v_lshl_or_b32 v0, v1, 6, v0
	s_add_u32 s30, s8, s30
	v_lshl_or_b32 v2, v3, 6, v2
	v_lshl_add_u32 v0, v15, 1, v0
	v_mov_b32_e32 v1, v137
	s_addc_u32 s31, s9, s31
	v_lshl_add_u32 v2, v17, 1, v2
	v_mov_b32_e32 v3, v137
	v_lshl_add_u64 v[130:131], s[30:31], 0, v[0:1]
	v_lshl_add_u64 v[132:133], s[30:31], 0, v[2:3]
	s_add_i32 s30, s46, s47
	s_ashr_i32 s31, s30, 31
	s_lshl_b64 s[30:31], s[30:31], 13
	s_add_u32 s30, s4, s30
	v_bfe_u32 v141, v150, 6, 2
	s_waitcnt vmcnt(6)
	v_lshlrev_b32_e32 v9, 13, v19
	s_addc_u32 s31, s5, s31
	v_lshlrev_b32_e32 v4, 12, v141
	v_lshlrev_b32_e32 v143, 6, v19
	v_or_b32_e32 v18, 0x800, v9
	v_or_b32_e32 v19, 0x1000, v9
	v_or_b32_e32 v20, 0x1800, v9
	v_lshl_add_u64 v[134:135], s[30:31], 0, v[0:1]
	v_mov_b32_e32 v0, 0
	v_or_b32_e32 v151, v143, v142
	v_lshl_add_u64 v[138:139], s[30:31], 0, v[2:3]
	s_mov_b32 s25, -2
	s_mov_b64 s[30:31], 0
	v_add_u32_e32 v169, v5, v4
	v_add_u32_e32 v147, v10, v9
	v_add_u32_e32 v146, v11, v18
	v_add_u32_e32 v145, v11, v19
	v_add_u32_e32 v144, v11, v20
	v_add_u32_e32 v168, v6, v4
	v_add_u32_e32 v160, v7, v4
	v_add_u32_e32 v155, v8, v4
	v_mov_b32_e32 v1, v0
	v_mov_b32_e32 v2, v0
	v_mov_b32_e32 v3, v0
	v_mov_b32_e32 v4, v0
	v_mov_b32_e32 v5, v0
	v_mov_b32_e32 v6, v0
	v_mov_b32_e32 v7, v0
	v_mov_b32_e32 v8, v0
	v_mov_b32_e32 v9, v0
	v_mov_b32_e32 v10, v0
	v_mov_b32_e32 v11, v0
	v_mov_b32_e32 v12, v0
	v_mov_b32_e32 v13, v0
	v_mov_b32_e32 v14, v0
	v_mov_b32_e32 v15, v0
	v_mov_b32_e32 v16, v0
	v_mov_b32_e32 v17, v0
	v_mov_b32_e32 v18, v0
	v_mov_b32_e32 v19, v0
	v_mov_b32_e32 v20, v0
	v_mov_b32_e32 v21, v0
	v_mov_b32_e32 v22, v0
	v_mov_b32_e32 v23, v0
	v_mov_b32_e32 v24, v0
	v_mov_b32_e32 v25, v0
	v_mov_b32_e32 v26, v0
	v_mov_b32_e32 v27, v0
	v_mov_b32_e32 v28, v0
	v_mov_b32_e32 v29, v0
	v_mov_b32_e32 v30, v0
	v_mov_b32_e32 v31, v0
	v_mov_b32_e32 v32, v0
	v_mov_b32_e32 v33, v0
	v_mov_b32_e32 v34, v0
	v_mov_b32_e32 v35, v0
	v_mov_b32_e32 v36, v0
	v_mov_b32_e32 v37, v0
	v_mov_b32_e32 v38, v0
	v_mov_b32_e32 v39, v0
	v_mov_b32_e32 v40, v0
	v_mov_b32_e32 v41, v0
	v_mov_b32_e32 v42, v0
	v_mov_b32_e32 v43, v0
	v_mov_b32_e32 v44, v0
	v_mov_b32_e32 v45, v0
	v_mov_b32_e32 v46, v0
	v_mov_b32_e32 v47, v0
	v_mov_b32_e32 v48, v0
	v_mov_b32_e32 v49, v0
	v_mov_b32_e32 v50, v0
	v_mov_b32_e32 v51, v0
	v_mov_b32_e32 v52, v0
	v_mov_b32_e32 v53, v0
	v_mov_b32_e32 v54, v0
	v_mov_b32_e32 v55, v0
	v_mov_b32_e32 v56, v0
	v_mov_b32_e32 v57, v0
	v_mov_b32_e32 v58, v0
	v_mov_b32_e32 v59, v0
	v_mov_b32_e32 v60, v0
	v_mov_b32_e32 v61, v0
	v_mov_b32_e32 v62, v0
	v_mov_b32_e32 v63, v0
	v_mov_b32_e32 v64, v0
	v_mov_b32_e32 v65, v0
	v_mov_b32_e32 v66, v0
	v_mov_b32_e32 v67, v0
	v_mov_b32_e32 v68, v0
	v_mov_b32_e32 v69, v0
	v_mov_b32_e32 v70, v0
	v_mov_b32_e32 v71, v0
	v_mov_b32_e32 v72, v0
	v_mov_b32_e32 v73, v0
	v_mov_b32_e32 v74, v0
	v_mov_b32_e32 v75, v0
	v_mov_b32_e32 v76, v0
	v_mov_b32_e32 v77, v0
	v_mov_b32_e32 v78, v0
	v_mov_b32_e32 v79, v0
	v_mov_b32_e32 v80, v0
	v_mov_b32_e32 v81, v0
	v_mov_b32_e32 v82, v0
	v_mov_b32_e32 v83, v0
	v_mov_b32_e32 v84, v0
	v_mov_b32_e32 v85, v0
	v_mov_b32_e32 v86, v0
	v_mov_b32_e32 v87, v0
	v_mov_b32_e32 v88, v0
	v_mov_b32_e32 v89, v0
	v_mov_b32_e32 v90, v0
	v_mov_b32_e32 v91, v0
	v_mov_b32_e32 v92, v0
	v_mov_b32_e32 v93, v0
	v_mov_b32_e32 v94, v0
	v_mov_b32_e32 v95, v0
	v_mov_b32_e32 v96, v0
	v_mov_b32_e32 v97, v0
	v_mov_b32_e32 v98, v0
	v_mov_b32_e32 v99, v0
	v_mov_b32_e32 v100, v0
	v_mov_b32_e32 v101, v0
	v_mov_b32_e32 v102, v0
	v_mov_b32_e32 v103, v0
	v_mov_b32_e32 v104, v0
	v_mov_b32_e32 v105, v0
	v_mov_b32_e32 v106, v0
	v_mov_b32_e32 v107, v0
	v_mov_b32_e32 v108, v0
	v_mov_b32_e32 v109, v0
	v_mov_b32_e32 v110, v0
	v_mov_b32_e32 v111, v0
	v_mov_b32_e32 v112, v0
	v_mov_b32_e32 v113, v0
	v_mov_b32_e32 v114, v0
	v_mov_b32_e32 v115, v0
	v_mov_b32_e32 v116, v0
	v_mov_b32_e32 v117, v0
	v_mov_b32_e32 v118, v0
	v_mov_b32_e32 v119, v0
	v_mov_b32_e32 v120, v0
	v_mov_b32_e32 v121, v0
	v_mov_b32_e32 v122, v0
	v_mov_b32_e32 v123, v0
	v_mov_b32_e32 v124, v0
	v_mov_b32_e32 v125, v0
	v_mov_b32_e32 v126, v0
	v_mov_b32_e32 v127, v0
	s_barrier
; #define WAIT_L(n) asm volatile("s_waitcnt lgkmcnt(" #n ")" ::: "memory")
; #define BAR __builtin_amdgcn_s_barrier()
; #define SCHED __builtin_amdgcn_sched_barrier(0)
;     ...
;   for (int t = 0; t < nt - 2; t += 2) {
;     LDB(B0, 0, 0); SCHED; LDA(At, 0, 0); STAGE(SA(1, 1), A, brow + HALF, t + 1);
;     WAIT_L(8); BAR; WAIT_L(0); MMA(0, 0, At, B0); BAR; SCHED;
;     LDB(B1, 0, 1); STAGE(SB(0, 0), Bt, bcol, t + 2);
	v_readfirstlane_b32 s27, v154
	v_writelane_b32 v254, s64, 0
	v_writelane_b32 v254, s65, 1
	v_writelane_b32 v254, s66, 2
	v_writelane_b32 v254, s67, 3
	v_writelane_b32 v254, s68, 4
	v_writelane_b32 v254, s69, 5
	v_writelane_b32 v254, s70, 6
	v_writelane_b32 v254, s71, 7
	v_writelane_b32 v254, s72, 8
	v_writelane_b32 v254, s73, 9
	v_writelane_b32 v254, s74, 10
	v_writelane_b32 v254, s75, 11
	v_writelane_b32 v254, s76, 12
	v_writelane_b32 v254, s77, 13
	v_writelane_b32 v254, s78, 14
	v_writelane_b32 v254, s79, 15
	v_writelane_b32 v254, s80, 16
	v_writelane_b32 v254, s81, 17
	v_writelane_b32 v254, s82, 18
	v_writelane_b32 v254, s83, 19
	v_writelane_b32 v254, s84, 20
	v_writelane_b32 v254, s85, 21
	v_writelane_b32 v254, s86, 22
	v_writelane_b32 v254, s87, 23
	v_writelane_b32 v254, s88, 24
	v_writelane_b32 v254, s89, 25
	v_writelane_b32 v254, s90, 26
	v_writelane_b32 v254, s91, 27
	v_writelane_b32 v254, s92, 28
	v_writelane_b32 v254, s93, 29
	v_writelane_b32 v254, s94, 30
	v_writelane_b32 v254, s95, 31
	v_readfirstlane_b32 s64, v134
	v_readfirstlane_b32 s65, v135
	v_readfirstlane_b32 s66, v138
	v_readfirstlane_b32 s67, v139
	v_readfirstlane_b32 s68, v130
	v_readfirstlane_b32 s69, v131
	v_readfirstlane_b32 s70, v132
	v_readfirstlane_b32 s71, v133
	v_readfirstlane_b32 s72, v134
	v_readfirstlane_b32 s73, v135
	v_readfirstlane_b32 s74, v138
	v_readfirstlane_b32 s75, v139
	v_readfirstlane_b32 s76, v130
	v_readfirstlane_b32 s77, v131
	v_readfirstlane_b32 s78, v132
	v_readfirstlane_b32 s79, v133
	v_readfirstlane_b32 s80, v134
	v_readfirstlane_b32 s81, v135
	v_readfirstlane_b32 s82, v138
	v_readfirstlane_b32 s83, v139
	v_readfirstlane_b32 s84, v130
	v_readfirstlane_b32 s85, v131
	v_readfirstlane_b32 s86, v132
	v_readfirstlane_b32 s87, v133
	v_readfirstlane_b32 s88, v134
	v_readfirstlane_b32 s89, v135
	v_readfirstlane_b32 s90, v138
	v_readfirstlane_b32 s91, v139
	v_readfirstlane_b32 s92, v130
	v_readfirstlane_b32 s93, v131
	v_readfirstlane_b32 s94, v132
	v_readfirstlane_b32 s95, v133
	s_nop 3
	v_subrev_u32_e32 v158, s64, v134
	v_subrev_u32_e32 v159, s66, v138
	v_subrev_u32_e32 v156, s68, v130
	v_subrev_u32_e32 v157, s70, v132
	s_add_u32 s64, s64, s30
	s_addc_u32 s65, s65, s31
	s_add_u32 s64, s64, s14
	s_addc_u32 s65, s65, s15
	s_add_u32 s66, s66, s30
	s_addc_u32 s67, s67, s31
	s_add_u32 s66, s66, s14
	s_addc_u32 s67, s67, s15
	s_add_u32 s68, s68, s30
	s_addc_u32 s69, s69, s31
	s_add_u32 s68, s68, s16
	s_addc_u32 s69, s69, s17
	s_add_u32 s70, s70, s30
	s_addc_u32 s71, s71, s31
	s_add_u32 s70, s70, s16
	s_addc_u32 s71, s71, s17
	s_add_u32 s72, s72, s30
	s_addc_u32 s73, s73, s31
	s_add_u32 s72, s72, s16
	s_addc_u32 s73, s73, s17
	s_add_u32 s74, s74, s30
	s_addc_u32 s75, s75, s31
	s_add_u32 s74, s74, s16
	s_addc_u32 s75, s75, s17
	s_add_u32 s76, s76, s30
	s_addc_u32 s77, s77, s31
	s_add_u32 s76, s76, s18
	s_addc_u32 s77, s77, s19
	s_add_u32 s78, s78, s30
	s_addc_u32 s79, s79, s31
	s_add_u32 s78, s78, s18
	s_addc_u32 s79, s79, s19
	s_add_u32 s80, s80, s30
	s_addc_u32 s81, s81, s31
	s_add_u32 s80, s80, s18
	s_addc_u32 s81, s81, s19
	s_add_u32 s82, s82, s30
	s_addc_u32 s83, s83, s31
	s_add_u32 s82, s82, s18
	s_addc_u32 s83, s83, s19
	s_add_u32 s84, s84, s30
	s_addc_u32 s85, s85, s31
	s_add_u32 s84, s84, s20
	s_addc_u32 s85, s85, s21
	s_add_u32 s86, s86, s30
	s_addc_u32 s87, s87, s31
	s_add_u32 s86, s86, s20
	s_addc_u32 s87, s87, s21
	s_add_u32 s88, s88, s30
	s_addc_u32 s89, s89, s31
	s_add_u32 s88, s88, s20
	s_addc_u32 s89, s89, s21
	s_add_u32 s90, s90, s30
	s_addc_u32 s91, s91, s31
	s_add_u32 s90, s90, s20
	s_addc_u32 s91, s91, s21
	s_add_u32 s92, s92, s30
	s_addc_u32 s93, s93, s31
	s_add_u32 s92, s92, s22
	s_addc_u32 s93, s93, s23
	s_add_u32 s94, s94, s30
	s_addc_u32 s95, s95, s31
	s_add_u32 s94, s94, s22
	s_addc_u32 s95, s95, s23
.LBB0_1142:
	ds_read_b128 v[172:175], v169
	ds_read_b128 v[176:179], v169 offset:1024
	ds_read_b128 v[180:183], v169 offset:2048
	ds_read_b128 v[184:187], v169 offset:3072
	v_add_u32_e32 v170, 0xc000, v154
	v_add_u32_e32 v171, 0xe000, v154
	s_add_u32 m0, s27, 0xc000
	ds_read_b128 v[188:191], v147
	ds_read_b128 v[192:195], v147 offset:1024
	ds_read_b128 v[196:199], v146
	ds_read_b128 v[200:203], v146 offset:1024
	ds_read_b128 v[204:207], v145
	ds_read_b128 v[208:211], v145 offset:1024
	ds_read_b128 v[212:215], v144
	ds_read_b128 v[216:219], v144 offset:1024
	global_load_lds_dwordx4 v158, s[64:65]
	s_add_u32 s64, s64, 0x100
	s_addc_u32 s65, s65, 0
	s_add_u32 m0, s27, 0xe000
	s_nop 0
	global_load_lds_dwordx4 v159, s[66:67]
	s_add_u32 s66, s66, 0x100
	s_addc_u32 s67, s67, 0
	s_waitcnt lgkmcnt(8)
	s_barrier
	s_waitcnt lgkmcnt(0)
	s_waitcnt lgkmcnt(0)
	v_mfma_f32_16x16x32_bf16 v[124:127], v[172:175], v[188:191], v[124:127]
	v_mfma_f32_16x16x32_bf16 v[120:123], v[180:183], v[188:191], v[120:123]
	v_mfma_f32_16x16x32_bf16 v[116:119], v[172:175], v[196:199], v[116:119]
	v_mfma_f32_16x16x32_bf16 v[112:115], v[180:183], v[196:199], v[112:115]
	v_mfma_f32_16x16x32_bf16 v[108:111], v[172:175], v[204:207], v[108:111]
	v_mfma_f32_16x16x32_bf16 v[104:107], v[180:183], v[204:207], v[104:107]
	v_mfma_f32_16x16x32_bf16 v[100:103], v[172:175], v[212:215], v[100:103]
	v_mfma_f32_16x16x32_bf16 v[96:99], v[180:183], v[212:215], v[96:99]
	v_mfma_f32_16x16x32_bf16 v[124:127], v[176:179], v[192:195], v[124:127]
	v_mfma_f32_16x16x32_bf16 v[120:123], v[184:187], v[192:195], v[120:123]
	v_mfma_f32_16x16x32_bf16 v[116:119], v[176:179], v[200:203], v[116:119]
	v_mfma_f32_16x16x32_bf16 v[112:115], v[184:187], v[200:203], v[112:115]
	v_mfma_f32_16x16x32_bf16 v[108:111], v[176:179], v[208:211], v[108:111]
	v_mfma_f32_16x16x32_bf16 v[104:107], v[184:187], v[208:211], v[104:107]
	v_mfma_f32_16x16x32_bf16 v[100:103], v[176:179], v[216:219], v[100:103]
	v_mfma_f32_16x16x32_bf16 v[96:99], v[184:187], v[216:219], v[96:99]
	s_barrier
; #define WAIT_V(n) asm volatile("s_waitcnt vmcnt(" #n ")" ::: "memory")
; #define WAIT_L(n) asm volatile("s_waitcnt lgkmcnt(" #n ")" ::: "memory")
; #define BAR __builtin_amdgcn_s_barrier()
; #define SCHED __builtin_amdgcn_sched_barrier(0)
;     ...
;     LDB(B1, 0, 1); STAGE(SB(0, 0), Bt, bcol, t + 2);
;     BAR; WAIT_L(0); MMA(0, 1, At, B1); BAR;
;     LDA(At, 0, 1); STAGE(SA(0, 0), A, brow, t + 2);
;     BAR; WAIT_L(0); MMA(1, 0, At, B0); BAR; SCHED;
;     STAGE(SB(0, 1), Bt, bcol1, t + 2);
;     WAIT_V(6); BAR; MMA(1, 1, At, B1); BAR;
;     LDB(B0, 1, 0); SCHED; LDA(At, 1, 0); STAGE(SA(0, 1), A, brow + HALF, t + 2);
;     WAIT_L(8); BAR; WAIT_L(0); MMA(0, 0, At, B0); BAR; SCHED;
;     LDB(B1, 1, 1); STAGE(SB(1, 0), Bt, bcol, t + 3);
	s_add_u32 m0, s27, s36
	ds_read_b128 v[220:223], v168
	ds_read_b128 v[224:227], v168 offset:1024
	ds_read_b128 v[228:231], v168 offset:2048
	ds_read_b128 v[232:235], v168 offset:3072
	global_load_lds_dwordx4 v156, s[68:69]
	s_add_u32 s68, s68, 0x100
	s_addc_u32 s69, s69, 0
	s_add_u32 m0, s27, 0x2000
	s_add_u32 m0, m0, s36
	s_nop 0
	global_load_lds_dwordx4 v157, s[70:71]
	s_add_u32 s70, s70, 0x100
	s_addc_u32 s71, s71, 0
	s_barrier
	s_waitcnt lgkmcnt(0)
	s_waitcnt lgkmcnt(0)
	v_mfma_f32_16x16x32_bf16 v[92:95], v[220:223], v[188:191], v[92:95]
	v_mfma_f32_16x16x32_bf16 v[88:91], v[228:231], v[188:191], v[88:91]
	v_mfma_f32_16x16x32_bf16 v[84:87], v[220:223], v[196:199], v[84:87]
	v_mfma_f32_16x16x32_bf16 v[80:83], v[228:231], v[196:199], v[80:83]
	v_mfma_f32_16x16x32_bf16 v[76:79], v[220:223], v[204:207], v[76:79]
	v_mfma_f32_16x16x32_bf16 v[72:75], v[228:231], v[204:207], v[72:75]
	v_mfma_f32_16x16x32_bf16 v[68:71], v[220:223], v[212:215], v[68:71]
	v_mfma_f32_16x16x32_bf16 v[64:67], v[228:231], v[212:215], v[64:67]
	v_mfma_f32_16x16x32_bf16 v[92:95], v[224:227], v[192:195], v[92:95]
	v_mfma_f32_16x16x32_bf16 v[88:91], v[232:235], v[192:195], v[88:91]
	v_mfma_f32_16x16x32_bf16 v[84:87], v[224:227], v[200:203], v[84:87]
	v_mfma_f32_16x16x32_bf16 v[80:83], v[232:235], v[200:203], v[80:83]
	v_mfma_f32_16x16x32_bf16 v[76:79], v[224:227], v[208:211], v[76:79]
	v_mfma_f32_16x16x32_bf16 v[72:75], v[232:235], v[208:211], v[72:75]
	v_mfma_f32_16x16x32_bf16 v[68:71], v[224:227], v[216:219], v[68:71]
	v_mfma_f32_16x16x32_bf16 v[64:67], v[232:235], v[216:219], v[64:67]
	s_mov_b32 m0, s27
	s_barrier
	ds_read_b128 v[188:191], v147 offset:16384
	ds_read_b128 v[192:195], v147 offset:17408
	ds_read_b128 v[196:199], v146 offset:16384
	ds_read_b128 v[200:203], v146 offset:17408
	ds_read_b128 v[204:207], v145 offset:16384
	ds_read_b128 v[208:211], v145 offset:17408
	ds_read_b128 v[212:215], v144 offset:16384
	ds_read_b128 v[216:219], v144 offset:17408
	global_load_lds_dwordx4 v158, s[72:73]
	s_add_u32 s72, s72, 0x100
	s_addc_u32 s73, s73, 0
	s_add_u32 m0, s27, 0x2000
	s_nop 0
	global_load_lds_dwordx4 v159, s[74:75]
	s_add_u32 s74, s74, 0x100
	s_addc_u32 s75, s75, 0
	s_barrier
	s_waitcnt lgkmcnt(0)
	s_waitcnt lgkmcnt(0)
	v_mfma_f32_16x16x32_bf16 v[60:63], v[172:175], v[188:191], v[60:63]
	v_mfma_f32_16x16x32_bf16 v[56:59], v[180:183], v[188:191], v[56:59]
	v_mfma_f32_16x16x32_bf16 v[52:55], v[172:175], v[196:199], v[52:55]
	v_mfma_f32_16x16x32_bf16 v[48:51], v[180:183], v[196:199], v[48:51]
	v_mfma_f32_16x16x32_bf16 v[44:47], v[172:175], v[204:207], v[44:47]
	v_mfma_f32_16x16x32_bf16 v[40:43], v[180:183], v[204:207], v[40:43]
	v_mfma_f32_16x16x32_bf16 v[36:39], v[172:175], v[212:215], v[36:39]
	v_mfma_f32_16x16x32_bf16 v[32:35], v[180:183], v[212:215], v[32:35]
	v_mfma_f32_16x16x32_bf16 v[60:63], v[176:179], v[192:195], v[60:63]
	v_mfma_f32_16x16x32_bf16 v[56:59], v[184:187], v[192:195], v[56:59]
	v_mfma_f32_16x16x32_bf16 v[52:55], v[176:179], v[200:203], v[52:55]
	v_mfma_f32_16x16x32_bf16 v[48:51], v[184:187], v[200:203], v[48:51]
	v_mfma_f32_16x16x32_bf16 v[44:47], v[176:179], v[208:211], v[44:47]
	v_mfma_f32_16x16x32_bf16 v[40:43], v[184:187], v[208:211], v[40:43]
	v_mfma_f32_16x16x32_bf16 v[36:39], v[176:179], v[216:219], v[36:39]
	v_mfma_f32_16x16x32_bf16 v[32:35], v[184:187], v[216:219], v[32:35]
	s_barrier
	s_add_u32 m0, s27, s37
	s_nop 0
	global_load_lds_dwordx4 v156, s[76:77]
	s_add_u32 s76, s76, 0x100
	s_addc_u32 s77, s77, 0
	s_add_u32 m0, s27, 0x2000
	s_add_u32 m0, m0, s37
	s_nop 0
	global_load_lds_dwordx4 v157, s[78:79]
	s_add_u32 s78, s78, 0x100
	s_addc_u32 s79, s79, 0
	s_waitcnt vmcnt(6)
	s_barrier
	v_mfma_f32_16x16x32_bf16 v[28:31], v[220:223], v[188:191], v[28:31]
	v_mfma_f32_16x16x32_bf16 v[24:27], v[228:231], v[188:191], v[24:27]
	v_mfma_f32_16x16x32_bf16 v[20:23], v[220:223], v[196:199], v[20:23]
	v_mfma_f32_16x16x32_bf16 v[16:19], v[228:231], v[196:199], v[16:19]
	v_mfma_f32_16x16x32_bf16 v[12:15], v[220:223], v[204:207], v[12:15]
	v_mfma_f32_16x16x32_bf16 v[8:11], v[228:231], v[204:207], v[8:11]
	v_mfma_f32_16x16x32_bf16 v[4:7], v[220:223], v[212:215], v[4:7]
	v_mfma_f32_16x16x32_bf16 v[0:3], v[228:231], v[212:215], v[0:3]
	v_mfma_f32_16x16x32_bf16 v[28:31], v[224:227], v[192:195], v[28:31]
	v_mfma_f32_16x16x32_bf16 v[24:27], v[232:235], v[192:195], v[24:27]
	v_mfma_f32_16x16x32_bf16 v[20:23], v[224:227], v[200:203], v[20:23]
	v_mfma_f32_16x16x32_bf16 v[16:19], v[232:235], v[200:203], v[16:19]
	v_mfma_f32_16x16x32_bf16 v[12:15], v[224:227], v[208:211], v[12:15]
	v_mfma_f32_16x16x32_bf16 v[8:11], v[232:235], v[208:211], v[8:11]
	v_mfma_f32_16x16x32_bf16 v[4:7], v[224:227], v[216:219], v[4:7]
	v_mfma_f32_16x16x32_bf16 v[0:3], v[232:235], v[216:219], v[0:3]
	s_barrier
	ds_read_b128 v[172:175], v160
	ds_read_b128 v[176:179], v160 offset:1024
	ds_read_b128 v[180:183], v160 offset:2048
	ds_read_b128 v[184:187], v160 offset:3072
	s_add_u32 m0, s27, 0x4000
	ds_read_b128 v[188:191], v147 offset:32768
	ds_read_b128 v[192:195], v147 offset:33792
	ds_read_b128 v[196:199], v146 offset:32768
	ds_read_b128 v[200:203], v146 offset:33792
	ds_read_b128 v[204:207], v145 offset:32768
	ds_read_b128 v[208:211], v145 offset:33792
	ds_read_b128 v[212:215], v144 offset:32768
	ds_read_b128 v[216:219], v144 offset:33792
	global_load_lds_dwordx4 v158, s[80:81]
	s_add_u32 s80, s80, 0x100
	s_addc_u32 s81, s81, 0
	s_add_u32 m0, s27, 0x6000
	s_nop 0
	global_load_lds_dwordx4 v159, s[82:83]
	s_add_u32 s82, s82, 0x100
	s_addc_u32 s83, s83, 0
	s_waitcnt lgkmcnt(8)
	s_barrier
; #define WAIT_V(n) asm volatile("s_waitcnt vmcnt(" #n ")" ::: "memory")
; #define WAIT_L(n) asm volatile("s_waitcnt lgkmcnt(" #n ")" ::: "memory")
; #define BAR __builtin_amdgcn_s_barrier()
; #define SCHED __builtin_amdgcn_sched_barrier(0)
;     ...
;     WAIT_L(8); BAR; WAIT_L(0); MMA(0, 0, At, B0); BAR; SCHED;
;     LDB(B1, 1, 1); STAGE(SB(1, 0), Bt, bcol, t + 3);
;     BAR; WAIT_L(0); MMA(0, 1, At, B1); BAR;
;     LDA(At, 1, 1); STAGE(SA(1, 0), A, brow, t + 3);
;     BAR; WAIT_L(0); MMA(1, 0, At, B0); BAR; SCHED;
;     STAGE(SB(1, 1), Bt, bcol1, t + 3);
;     WAIT_V(6); BAR; MMA(1, 1, At, B1); BAR;
;   }
	s_waitcnt lgkmcnt(0)
	s_waitcnt lgkmcnt(0)
	v_mfma_f32_16x16x32_bf16 v[124:127], v[172:175], v[188:191], v[124:127]
	v_mfma_f32_16x16x32_bf16 v[120:123], v[180:183], v[188:191], v[120:123]
	v_mfma_f32_16x16x32_bf16 v[116:119], v[172:175], v[196:199], v[116:119]
	v_mfma_f32_16x16x32_bf16 v[112:115], v[180:183], v[196:199], v[112:115]
	v_mfma_f32_16x16x32_bf16 v[108:111], v[172:175], v[204:207], v[108:111]
	v_mfma_f32_16x16x32_bf16 v[104:107], v[180:183], v[204:207], v[104:107]
	v_mfma_f32_16x16x32_bf16 v[100:103], v[172:175], v[212:215], v[100:103]
	v_mfma_f32_16x16x32_bf16 v[96:99], v[180:183], v[212:215], v[96:99]
	v_mfma_f32_16x16x32_bf16 v[124:127], v[176:179], v[192:195], v[124:127]
	v_mfma_f32_16x16x32_bf16 v[120:123], v[184:187], v[192:195], v[120:123]
	v_mfma_f32_16x16x32_bf16 v[116:119], v[176:179], v[200:203], v[116:119]
	v_mfma_f32_16x16x32_bf16 v[112:115], v[184:187], v[200:203], v[112:115]
	v_mfma_f32_16x16x32_bf16 v[108:111], v[176:179], v[208:211], v[108:111]
	v_mfma_f32_16x16x32_bf16 v[104:107], v[184:187], v[208:211], v[104:107]
	v_mfma_f32_16x16x32_bf16 v[100:103], v[176:179], v[216:219], v[100:103]
	v_mfma_f32_16x16x32_bf16 v[96:99], v[184:187], v[216:219], v[96:99]
	s_barrier
	s_add_u32 m0, s27, s38
	ds_read_b128 v[220:223], v155
	ds_read_b128 v[224:227], v155 offset:1024
	ds_read_b128 v[228:231], v155 offset:2048
	ds_read_b128 v[232:235], v155 offset:3072
	global_load_lds_dwordx4 v156, s[84:85]
	s_add_u32 s84, s84, 0x100
	s_addc_u32 s85, s85, 0
	s_add_u32 m0, s27, 0x2000
	s_add_u32 m0, m0, s38
	s_nop 0
	global_load_lds_dwordx4 v157, s[86:87]
	s_add_u32 s86, s86, 0x100
	s_addc_u32 s87, s87, 0
	s_barrier
	s_waitcnt lgkmcnt(0)
	s_waitcnt lgkmcnt(0)
	v_mfma_f32_16x16x32_bf16 v[92:95], v[220:223], v[188:191], v[92:95]
	v_mfma_f32_16x16x32_bf16 v[88:91], v[228:231], v[188:191], v[88:91]
	v_mfma_f32_16x16x32_bf16 v[84:87], v[220:223], v[196:199], v[84:87]
	v_mfma_f32_16x16x32_bf16 v[80:83], v[228:231], v[196:199], v[80:83]
	v_mfma_f32_16x16x32_bf16 v[76:79], v[220:223], v[204:207], v[76:79]
	v_mfma_f32_16x16x32_bf16 v[72:75], v[228:231], v[204:207], v[72:75]
	v_mfma_f32_16x16x32_bf16 v[68:71], v[220:223], v[212:215], v[68:71]
	v_mfma_f32_16x16x32_bf16 v[64:67], v[228:231], v[212:215], v[64:67]
	v_mfma_f32_16x16x32_bf16 v[92:95], v[224:227], v[192:195], v[92:95]
	v_mfma_f32_16x16x32_bf16 v[88:91], v[232:235], v[192:195], v[88:91]
	v_mfma_f32_16x16x32_bf16 v[84:87], v[224:227], v[200:203], v[84:87]
	v_mfma_f32_16x16x32_bf16 v[80:83], v[232:235], v[200:203], v[80:83]
	v_mfma_f32_16x16x32_bf16 v[76:79], v[224:227], v[208:211], v[76:79]
	v_mfma_f32_16x16x32_bf16 v[72:75], v[232:235], v[208:211], v[72:75]
	v_mfma_f32_16x16x32_bf16 v[68:71], v[224:227], v[216:219], v[68:71]
	v_mfma_f32_16x16x32_bf16 v[64:67], v[232:235], v[216:219], v[64:67]
	s_add_u32 m0, s27, 0x8000
	s_barrier
	ds_read_b128 v[188:191], v147 offset:49152
	ds_read_b128 v[192:195], v147 offset:50176
	ds_read_b128 v[196:199], v146 offset:49152
	ds_read_b128 v[200:203], v146 offset:50176
	ds_read_b128 v[204:207], v145 offset:49152
	ds_read_b128 v[208:211], v145 offset:50176
	ds_read_b128 v[212:215], v144 offset:49152
	ds_read_b128 v[216:219], v144 offset:50176
	global_load_lds_dwordx4 v158, s[88:89]
	s_add_u32 s88, s88, 0x100
	s_addc_u32 s89, s89, 0
	s_add_u32 m0, s27, 0xa000
	s_nop 0
	global_load_lds_dwordx4 v159, s[90:91]
	s_add_u32 s90, s90, 0x100
	s_addc_u32 s91, s91, 0
	s_barrier
	s_waitcnt lgkmcnt(0)
	s_waitcnt lgkmcnt(0)
	v_mfma_f32_16x16x32_bf16 v[60:63], v[172:175], v[188:191], v[60:63]
	v_mfma_f32_16x16x32_bf16 v[56:59], v[180:183], v[188:191], v[56:59]
	v_mfma_f32_16x16x32_bf16 v[52:55], v[172:175], v[196:199], v[52:55]
	v_mfma_f32_16x16x32_bf16 v[48:51], v[180:183], v[196:199], v[48:51]
	v_mfma_f32_16x16x32_bf16 v[44:47], v[172:175], v[204:207], v[44:47]
	v_mfma_f32_16x16x32_bf16 v[40:43], v[180:183], v[204:207], v[40:43]
	v_mfma_f32_16x16x32_bf16 v[36:39], v[172:175], v[212:215], v[36:39]
	v_mfma_f32_16x16x32_bf16 v[32:35], v[180:183], v[212:215], v[32:35]
	v_mfma_f32_16x16x32_bf16 v[60:63], v[176:179], v[192:195], v[60:63]
	v_mfma_f32_16x16x32_bf16 v[56:59], v[184:187], v[192:195], v[56:59]
	v_mfma_f32_16x16x32_bf16 v[52:55], v[176:179], v[200:203], v[52:55]
	v_mfma_f32_16x16x32_bf16 v[48:51], v[184:187], v[200:203], v[48:51]
	v_mfma_f32_16x16x32_bf16 v[44:47], v[176:179], v[208:211], v[44:47]
	v_mfma_f32_16x16x32_bf16 v[40:43], v[184:187], v[208:211], v[40:43]
	v_mfma_f32_16x16x32_bf16 v[36:39], v[176:179], v[216:219], v[36:39]
	v_mfma_f32_16x16x32_bf16 v[32:35], v[184:187], v[216:219], v[32:35]
	s_barrier
	s_add_u32 m0, s27, s39
	s_nop 0
	global_load_lds_dwordx4 v156, s[92:93]
	s_add_u32 s92, s92, 0x100
	s_addc_u32 s93, s93, 0
	s_add_u32 m0, s27, 0x2000
	s_add_u32 m0, m0, s39
	s_nop 0
	global_load_lds_dwordx4 v157, s[94:95]
	s_add_u32 s94, s94, 0x100
	s_addc_u32 s95, s95, 0
	s_waitcnt vmcnt(6)
	s_barrier
	v_mfma_f32_16x16x32_bf16 v[28:31], v[220:223], v[188:191], v[28:31]
	v_mfma_f32_16x16x32_bf16 v[24:27], v[228:231], v[188:191], v[24:27]
	v_mfma_f32_16x16x32_bf16 v[20:23], v[220:223], v[196:199], v[20:23]
	v_mfma_f32_16x16x32_bf16 v[16:19], v[228:231], v[196:199], v[16:19]
	v_mfma_f32_16x16x32_bf16 v[12:15], v[220:223], v[204:207], v[12:15]
	v_mfma_f32_16x16x32_bf16 v[8:11], v[228:231], v[204:207], v[8:11]
	v_mfma_f32_16x16x32_bf16 v[4:7], v[220:223], v[212:215], v[4:7]
	v_mfma_f32_16x16x32_bf16 v[0:3], v[228:231], v[212:215], v[0:3]
	v_mfma_f32_16x16x32_bf16 v[28:31], v[224:227], v[192:195], v[28:31]
	v_mfma_f32_16x16x32_bf16 v[24:27], v[232:235], v[192:195], v[24:27]
	v_mfma_f32_16x16x32_bf16 v[20:23], v[224:227], v[200:203], v[20:23]
	v_mfma_f32_16x16x32_bf16 v[16:19], v[232:235], v[200:203], v[16:19]
	v_mfma_f32_16x16x32_bf16 v[12:15], v[224:227], v[208:211], v[12:15]
	v_mfma_f32_16x16x32_bf16 v[8:11], v[232:235], v[208:211], v[8:11]
	v_mfma_f32_16x16x32_bf16 v[4:7], v[224:227], v[216:219], v[4:7]
	v_mfma_f32_16x16x32_bf16 v[0:3], v[232:235], v[216:219], v[0:3]
	s_add_i32 s25, s25, 2
	s_add_u32 s30, s30, 0x100
	s_addc_u32 s31, s31, 0
	s_cmp_lt_u32 s25, 60
	s_barrier
; #define WAIT_V(n) asm volatile("s_waitcnt vmcnt(" #n ")" ::: "memory")
; #define WAIT_L(n) asm volatile("s_waitcnt lgkmcnt(" #n ")" ::: "memory")
; #define BAR __builtin_amdgcn_s_barrier()
;     ...
;   }
;   { LDB(B0, 0, 0); LDA(At, 0, 0); STAGE(SA(1, 1), A, brow + HALF, nt - 1);
;     BAR; WAIT_L(0); MMA(0, 0, At, B0); BAR;
;     LDB(B1, 0, 1); BAR; WAIT_L(0); MMA(0, 1, At, B1); BAR;
;     LDA(At, 0, 1); WAIT_V(4); BAR; WAIT_L(0); MMA(1, 0, At, B0); MMA(1, 1, At, B1); BAR; }
;   { LDB(B0, 1, 0); LDA(At, 1, 0); WAIT_V(2); BAR; WAIT_L(0); MMA(0, 0, At, B0); BAR;
	s_cbranch_scc1 .LBB0_1142
	v_readlane_b32 s64, v254, 0
	v_readlane_b32 s65, v254, 1
	v_readlane_b32 s66, v254, 2
	v_readlane_b32 s67, v254, 3
	v_readlane_b32 s68, v254, 4
	v_readlane_b32 s69, v254, 5
	v_readlane_b32 s70, v254, 6
	v_readlane_b32 s71, v254, 7
	v_readlane_b32 s72, v254, 8
	v_readlane_b32 s73, v254, 9
	v_readlane_b32 s74, v254, 10
	v_readlane_b32 s75, v254, 11
	v_readlane_b32 s76, v254, 12
	v_readlane_b32 s77, v254, 13
	v_readlane_b32 s78, v254, 14
	v_readlane_b32 s79, v254, 15
	v_readlane_b32 s80, v254, 16
	v_readlane_b32 s81, v254, 17
	v_readlane_b32 s82, v254, 18
	v_readlane_b32 s83, v254, 19
	v_readlane_b32 s84, v254, 20
	v_readlane_b32 s85, v254, 21
	v_readlane_b32 s86, v254, 22
	v_readlane_b32 s87, v254, 23
	v_readlane_b32 s88, v254, 24
	v_readlane_b32 s89, v254, 25
	v_readlane_b32 s90, v254, 26
	v_readlane_b32 s91, v254, 27
	v_readlane_b32 s92, v254, 28
	v_readlane_b32 s93, v254, 29
	v_readlane_b32 s94, v254, 30
	v_readlane_b32 s95, v254, 31
	s_nop 4
	s_add_u32 s28, s28, 0x1f80
	s_addc_u32 s29, s29, 0
	v_readfirstlane_b32 s25, v170
	v_lshl_add_u64 v[134:135], s[28:29], 0, v[136:137]
	s_mov_b32 m0, s25
	v_readfirstlane_b32 s25, v171
	ds_read_b128 v[130:133], v169
	ds_read_b128 v[156:159], v169 offset:1024
	ds_read_b128 v[162:165], v169 offset:2048
	ds_read_b128 v[172:175], v169 offset:3072
	ds_read_b128 v[176:179], v147
	ds_read_b128 v[180:183], v147 offset:1024
	ds_read_b128 v[184:187], v146
	ds_read_b128 v[188:191], v146 offset:1024
	ds_read_b128 v[192:195], v145
	ds_read_b128 v[196:199], v145 offset:1024
	ds_read_b128 v[200:203], v144
	ds_read_b128 v[204:207], v144 offset:1024
	global_load_lds_dwordx4 v[134:135], off
	v_lshl_add_u64 v[128:129], s[28:29], 0, v[128:129]
	s_mov_b32 m0, s25
	s_nop 0
	global_load_lds_dwordx4 v[128:129], off
	s_barrier
	s_waitcnt lgkmcnt(0)
	s_waitcnt lgkmcnt(0)
	v_mfma_f32_16x16x32_bf16 v[124:127], v[130:133], v[176:179], v[124:127]
	v_mfma_f32_16x16x32_bf16 v[120:123], v[162:165], v[176:179], v[120:123]
	v_mfma_f32_16x16x32_bf16 v[116:119], v[130:133], v[184:187], v[116:119]
	v_mfma_f32_16x16x32_bf16 v[112:115], v[162:165], v[184:187], v[112:115]
	v_mfma_f32_16x16x32_bf16 v[108:111], v[130:133], v[192:195], v[108:111]
	v_mfma_f32_16x16x32_bf16 v[104:107], v[162:165], v[192:195], v[104:107]
	v_mfma_f32_16x16x32_bf16 v[96:99], v[162:165], v[200:203], v[96:99]
	v_mfma_f32_16x16x32_bf16 v[124:127], v[156:159], v[180:183], v[124:127]
	v_mfma_f32_16x16x32_bf16 v[120:123], v[172:175], v[180:183], v[120:123]
	v_mfma_f32_16x16x32_bf16 v[116:119], v[156:159], v[188:191], v[116:119]
	v_mfma_f32_16x16x32_bf16 v[112:115], v[172:175], v[188:191], v[112:115]
	v_mfma_f32_16x16x32_bf16 v[108:111], v[156:159], v[196:199], v[108:111]
	v_mfma_f32_16x16x32_bf16 v[104:107], v[172:175], v[196:199], v[104:107]
	v_mfma_f32_16x16x32_bf16 v[100:103], v[130:133], v[200:203], v[100:103]
	v_mfma_f32_16x16x32_bf16 v[96:99], v[172:175], v[204:207], v[96:99]
	v_mfma_f32_16x16x32_bf16 v[100:103], v[156:159], v[204:207], v[100:103]
	s_barrier
	ds_read_b128 v[208:211], v168
	ds_read_b128 v[212:215], v168 offset:1024
	ds_read_b128 v[216:219], v168 offset:2048
	ds_read_b128 v[166:169], v168 offset:3072
	s_barrier
	s_waitcnt lgkmcnt(0)
	s_waitcnt lgkmcnt(0)
	v_mfma_f32_16x16x32_bf16 v[92:95], v[208:211], v[176:179], v[92:95]
	v_mfma_f32_16x16x32_bf16 v[88:91], v[216:219], v[176:179], v[88:91]
	v_mfma_f32_16x16x32_bf16 v[84:87], v[208:211], v[184:187], v[84:87]
	v_mfma_f32_16x16x32_bf16 v[80:83], v[216:219], v[184:187], v[80:83]
	v_mfma_f32_16x16x32_bf16 v[76:79], v[208:211], v[192:195], v[76:79]
	v_mfma_f32_16x16x32_bf16 v[72:75], v[216:219], v[192:195], v[72:75]
	v_mfma_f32_16x16x32_bf16 v[68:71], v[208:211], v[200:203], v[68:71]
	v_mfma_f32_16x16x32_bf16 v[92:95], v[212:215], v[180:183], v[92:95]
	v_mfma_f32_16x16x32_bf16 v[88:91], v[166:169], v[180:183], v[88:91]
	v_mfma_f32_16x16x32_bf16 v[84:87], v[212:215], v[188:191], v[84:87]
	v_mfma_f32_16x16x32_bf16 v[80:83], v[166:169], v[188:191], v[80:83]
	v_mfma_f32_16x16x32_bf16 v[76:79], v[212:215], v[196:199], v[76:79]
	v_mfma_f32_16x16x32_bf16 v[176:179], v[166:169], v[196:199], v[72:75]
	v_mfma_f32_16x16x32_bf16 v[68:71], v[212:215], v[204:207], v[68:71]
	v_mfma_f32_16x16x32_bf16 v[64:67], v[216:219], v[200:203], v[64:67]
	v_mfma_f32_16x16x32_bf16 v[180:183], v[166:169], v[204:207], v[64:67]
	s_barrier
	s_nop 4
	ds_read_b128 v[64:67], v147 offset:16384
	ds_read_b128 v[72:75], v147 offset:17408
	ds_read_b128 v[184:187], v146 offset:16384
	ds_read_b128 v[188:191], v146 offset:17408
	ds_read_b128 v[192:195], v145 offset:16384
	ds_read_b128 v[196:199], v145 offset:17408
	ds_read_b128 v[200:203], v144 offset:16384
	ds_read_b128 v[204:207], v144 offset:17408
	s_waitcnt vmcnt(4)
	s_barrier
; #define WAIT_V(n) asm volatile("s_waitcnt vmcnt(" #n ")" ::: "memory")
; #define WAIT_L(n) asm volatile("s_waitcnt lgkmcnt(" #n ")" ::: "memory")
; #define BAR __builtin_amdgcn_s_barrier()
;     ...
;     LDA(At, 0, 1); WAIT_V(4); BAR; WAIT_L(0); MMA(1, 0, At, B0); MMA(1, 1, At, B1); BAR; }
;   { LDB(B0, 1, 0); LDA(At, 1, 0); WAIT_V(2); BAR; WAIT_L(0); MMA(0, 0, At, B0); BAR;
	s_waitcnt lgkmcnt(0)
	s_waitcnt lgkmcnt(0)
	v_mfma_f32_16x16x32_bf16 v[60:63], v[130:133], v[64:67], v[60:63]
	v_mfma_f32_16x16x32_bf16 v[36:39], v[130:133], v[200:203], v[36:39]
	v_mfma_f32_16x16x32_bf16 v[32:35], v[162:165], v[200:203], v[32:35]
	v_mfma_f32_16x16x32_bf16 v[60:63], v[156:159], v[72:75], v[60:63]
	v_mfma_f32_16x16x32_bf16 v[56:59], v[162:165], v[64:67], v[56:59]
	v_mfma_f32_16x16x32_bf16 v[52:55], v[130:133], v[184:187], v[52:55]
	v_mfma_f32_16x16x32_bf16 v[48:51], v[162:165], v[184:187], v[48:51]
	v_mfma_f32_16x16x32_bf16 v[44:47], v[130:133], v[192:195], v[44:47]
	v_mfma_f32_16x16x32_bf16 v[40:43], v[162:165], v[192:195], v[40:43]
	v_mfma_f32_16x16x32_bf16 v[128:131], v[156:159], v[204:207], v[36:39]
	v_mfma_f32_16x16x32_bf16 v[132:135], v[172:175], v[204:207], v[32:35]
	v_mfma_f32_16x16x32_bf16 v[220:223], v[172:175], v[72:75], v[56:59]
	v_mfma_f32_16x16x32_bf16 v[224:227], v[156:159], v[188:191], v[52:55]
	v_mfma_f32_16x16x32_bf16 v[228:231], v[172:175], v[188:191], v[48:51]
	v_mfma_f32_16x16x32_bf16 v[232:235], v[156:159], v[196:199], v[44:47]
	v_mfma_f32_16x16x32_bf16 v[236:239], v[172:175], v[196:199], v[40:43]
	v_mfma_f32_16x16x32_bf16 v[28:31], v[208:211], v[64:67], v[28:31]
	v_mfma_f32_16x16x32_bf16 v[24:27], v[216:219], v[64:67], v[24:27]
	v_mfma_f32_16x16x32_bf16 v[20:23], v[208:211], v[184:187], v[20:23]
	v_mfma_f32_16x16x32_bf16 v[16:19], v[216:219], v[184:187], v[16:19]
	v_mfma_f32_16x16x32_bf16 v[12:15], v[208:211], v[192:195], v[12:15]
	v_mfma_f32_16x16x32_bf16 v[8:11], v[216:219], v[192:195], v[8:11]
	v_mfma_f32_16x16x32_bf16 v[4:7], v[208:211], v[200:203], v[4:7]
	v_mfma_f32_16x16x32_bf16 v[0:3], v[216:219], v[200:203], v[0:3]
	v_mfma_f32_16x16x32_bf16 v[156:159], v[212:215], v[72:75], v[28:31]
	v_mfma_f32_16x16x32_bf16 v[24:27], v[166:169], v[72:75], v[24:27]
	v_mfma_f32_16x16x32_bf16 v[162:165], v[212:215], v[188:191], v[20:23]
	v_mfma_f32_16x16x32_bf16 v[170:173], v[166:169], v[188:191], v[16:19]
	v_mfma_f32_16x16x32_bf16 v[12:15], v[212:215], v[196:199], v[12:15]
	v_mfma_f32_16x16x32_bf16 v[184:187], v[166:169], v[196:199], v[8:11]
	v_mfma_f32_16x16x32_bf16 v[188:191], v[212:215], v[204:207], v[4:7]
	v_mfma_f32_16x16x32_bf16 v[166:169], v[166:169], v[204:207], v[0:3]
	s_barrier
	ds_read_b128 v[192:195], v160
	ds_read_b128 v[196:199], v160 offset:1024
	ds_read_b128 v[200:203], v160 offset:2048
	ds_read_b128 v[204:207], v160 offset:3072
	ds_read_b128 v[32:35], v147 offset:32768
	ds_read_b128 v[48:51], v147 offset:33792
	ds_read_b128 v[52:55], v146 offset:32768
	ds_read_b128 v[64:67], v146 offset:33792
	ds_read_b128 v[208:211], v145 offset:32768
	ds_read_b128 v[212:215], v145 offset:33792
	ds_read_b128 v[216:219], v144 offset:32768
	ds_read_b128 v[240:243], v144 offset:33792
	s_waitcnt vmcnt(2)
	s_barrier
	s_waitcnt lgkmcnt(0)
	s_waitcnt lgkmcnt(0)
	v_mfma_f32_16x16x32_bf16 v[0:3], v[192:195], v[32:35], v[124:127]
	v_mfma_f32_16x16x32_bf16 v[4:7], v[200:203], v[32:35], v[120:123]
	v_mfma_f32_16x16x32_bf16 v[8:11], v[192:195], v[52:55], v[116:119]
	v_mfma_f32_16x16x32_bf16 v[16:19], v[200:203], v[52:55], v[112:115]
	v_mfma_f32_16x16x32_bf16 v[20:23], v[192:195], v[208:211], v[108:111]
	v_mfma_f32_16x16x32_bf16 v[28:31], v[200:203], v[208:211], v[104:107]
	v_mfma_f32_16x16x32_bf16 v[36:39], v[192:195], v[216:219], v[100:103]
	v_mfma_f32_16x16x32_bf16 v[40:43], v[200:203], v[216:219], v[96:99]
	v_mfma_f32_16x16x32_bf16 v[0:3], v[196:199], v[48:51], v[0:3]
	v_mfma_f32_16x16x32_bf16 v[4:7], v[204:207], v[48:51], v[4:7]
	v_mfma_f32_16x16x32_bf16 v[8:11], v[196:199], v[64:67], v[8:11]
	v_mfma_f32_16x16x32_bf16 v[16:19], v[204:207], v[64:67], v[16:19]
	v_mfma_f32_16x16x32_bf16 v[20:23], v[196:199], v[212:215], v[20:23]
	v_mfma_f32_16x16x32_bf16 v[28:31], v[204:207], v[212:215], v[28:31]
	v_mfma_f32_16x16x32_bf16 v[36:39], v[196:199], v[240:243], v[36:39]
	v_mfma_f32_16x16x32_bf16 v[44:47], v[204:207], v[240:243], v[40:43]
	s_barrier
; #define WAIT_V(n) asm volatile("s_waitcnt vmcnt(" #n ")" ::: "memory")
; #define WAIT_L(n) asm volatile("s_waitcnt lgkmcnt(" #n ")" ::: "memory")
; #define BAR __builtin_amdgcn_s_barrier()
;     ...
;   { LDB(B0, 1, 0); LDA(At, 1, 0); WAIT_V(2); BAR; WAIT_L(0); MMA(0, 0, At, B0); BAR;
;     LDB(B1, 1, 1); WAIT_V(0); BAR; WAIT_L(0); MMA(0, 1, At, B1); BAR;
;     LDA(At, 1, 1); BAR; WAIT_L(0); MMA(1, 0, At, B0); MMA(1, 1, At, B1); BAR; }
;   if (wr == 0) BAR;
	ds_read_b128 v[244:247], v155
	ds_read_b128 v[248:251], v155 offset:1024
	ds_read_b128 v[100:103], v155 offset:2048
	ds_read_b128 v[152:155], v155 offset:3072
	s_waitcnt vmcnt(0)
	s_barrier
	s_waitcnt lgkmcnt(0)
	s_waitcnt lgkmcnt(0)
	v_mfma_f32_16x16x32_bf16 v[40:43], v[244:247], v[32:35], v[92:95]
	v_mfma_f32_16x16x32_bf16 v[32:35], v[100:103], v[32:35], v[88:91]
	v_mfma_f32_16x16x32_bf16 v[40:43], v[248:251], v[48:51], v[40:43]
	v_mfma_f32_16x16x32_bf16 v[32:35], v[152:155], v[48:51], v[32:35]
	v_mfma_f32_16x16x32_bf16 v[48:51], v[244:247], v[52:55], v[84:87]
	v_mfma_f32_16x16x32_bf16 v[56:59], v[248:251], v[64:67], v[48:51]
	v_mfma_f32_16x16x32_bf16 v[48:51], v[100:103], v[52:55], v[80:83]
	v_mfma_f32_16x16x32_bf16 v[52:55], v[244:247], v[208:211], v[76:79]
	v_mfma_f32_16x16x32_bf16 v[72:75], v[248:251], v[212:215], v[52:55]
	v_mfma_f32_16x16x32_bf16 v[52:55], v[100:103], v[208:211], v[176:179]
	v_mfma_f32_16x16x32_bf16 v[48:51], v[152:155], v[64:67], v[48:51]
	v_mfma_f32_16x16x32_bf16 v[64:67], v[152:155], v[212:215], v[52:55]
	v_mfma_f32_16x16x32_bf16 v[52:55], v[244:247], v[216:219], v[68:71]
	v_mfma_f32_16x16x32_bf16 v[88:91], v[248:251], v[240:243], v[52:55]
	v_mfma_f32_16x16x32_bf16 v[52:55], v[100:103], v[216:219], v[180:183]
	v_mfma_f32_16x16x32_bf16 v[76:79], v[152:155], v[240:243], v[52:55]
	s_barrier
	ds_read_b128 v[96:99], v147 offset:49152
	ds_read_b128 v[108:111], v147 offset:50176
	ds_read_b128 v[120:123], v146 offset:49152
	ds_read_b128 v[124:127], v146 offset:50176
	ds_read_b128 v[178:181], v145 offset:49152
	ds_read_b128 v[208:211], v145 offset:50176
	ds_read_b128 v[212:215], v144 offset:49152
	ds_read_b128 v[144:147], v144 offset:50176
	s_barrier
	s_waitcnt lgkmcnt(0)
	s_waitcnt lgkmcnt(0)
	v_mfma_f32_16x16x32_bf16 v[104:107], v[192:195], v[212:215], v[128:131]
	v_mfma_f32_16x16x32_bf16 v[52:55], v[192:195], v[96:99], v[60:63]
	v_mfma_f32_16x16x32_bf16 v[60:63], v[200:203], v[96:99], v[220:223]
	v_mfma_f32_16x16x32_bf16 v[68:71], v[192:195], v[120:123], v[224:227]
	v_mfma_f32_16x16x32_bf16 v[80:83], v[200:203], v[120:123], v[228:231]
	v_mfma_f32_16x16x32_bf16 v[84:87], v[192:195], v[178:181], v[232:235]
	v_mfma_f32_16x16x32_bf16 v[92:95], v[200:203], v[178:181], v[236:239]
	v_mfma_f32_16x16x32_bf16 v[174:177], v[196:199], v[144:147], v[104:107]
	v_mfma_f32_16x16x32_bf16 v[104:107], v[200:203], v[212:215], v[132:135]
	v_mfma_f32_16x16x32_bf16 v[52:55], v[196:199], v[108:111], v[52:55]
	v_mfma_f32_16x16x32_bf16 v[60:63], v[204:207], v[108:111], v[60:63]
	v_mfma_f32_16x16x32_bf16 v[68:71], v[196:199], v[124:127], v[68:71]
	v_mfma_f32_16x16x32_bf16 v[80:83], v[204:207], v[124:127], v[80:83]
	v_mfma_f32_16x16x32_bf16 v[84:87], v[196:199], v[208:211], v[84:87]
	v_mfma_f32_16x16x32_bf16 v[92:95], v[204:207], v[208:211], v[92:95]
	v_mfma_f32_16x16x32_bf16 v[112:115], v[204:207], v[144:147], v[104:107]
	v_mfma_f32_16x16x32_bf16 v[24:27], v[100:103], v[96:99], v[24:27]
	v_mfma_f32_16x16x32_bf16 v[104:107], v[244:247], v[96:99], v[156:159]
	v_mfma_f32_16x16x32_bf16 v[96:99], v[152:155], v[108:111], v[24:27]
	v_mfma_f32_16x16x32_bf16 v[24:27], v[244:247], v[120:123], v[162:165]
	v_mfma_f32_16x16x32_bf16 v[116:119], v[248:251], v[124:127], v[24:27]
	v_mfma_f32_16x16x32_bf16 v[24:27], v[100:103], v[120:123], v[170:173]
	v_mfma_f32_16x16x32_bf16 v[12:15], v[244:247], v[178:181], v[12:15]
	v_mfma_f32_16x16x32_bf16 v[104:107], v[248:251], v[108:111], v[104:107]
	v_mfma_f32_16x16x32_bf16 v[108:111], v[152:155], v[124:127], v[24:27]
	v_mfma_f32_16x16x32_bf16 v[124:127], v[248:251], v[208:211], v[12:15]
	v_mfma_f32_16x16x32_bf16 v[12:15], v[100:103], v[178:181], v[184:187]
	v_mfma_f32_16x16x32_bf16 v[120:123], v[152:155], v[208:211], v[12:15]
	v_mfma_f32_16x16x32_bf16 v[12:15], v[244:247], v[212:215], v[188:191]
	v_mfma_f32_16x16x32_bf16 v[132:135], v[248:251], v[144:147], v[12:15]
	v_mfma_f32_16x16x32_bf16 v[12:15], v[100:103], v[212:215], v[166:169]
	v_mfma_f32_16x16x32_bf16 v[128:131], v[152:155], v[144:147], v[12:15]
	v_cmp_gt_u32_e32 vcc, s41, v150
	s_barrier
	s_and_saveexec_b64 s[28:29], vcc
	s_cbranch_execz .LBB0_1145
	s_barrier

; #define WAIT_V(n) asm volatile("s_waitcnt vmcnt(" #n ")" ::: "memory")
; #define BAR __builtin_amdgcn_s_barrier()
;     ...
;   const int wid = tx >> 6, lane = tx & 63, wr = wid >> 2, wc = wid & 3, fr = lane & 15, fq = lane >> 4;
;   f32x4 acc[2][2][4][2] = {};
;   bf16x8 At[4][2], B0[2][2], B1[2][2];
;   const int nt = K / BK;
;   unsigned soff0, soff1;
;   { int _r, _c; stage_rc(tx * 16, _r, _c); soff0 = (unsigned)(_r * K + _c) * 2u;
;     stage_rc(tx * 16 + 8192, _r, _c); soff1 = (unsigned)(_r * K + _c) * 2u; }
;   STAGE(SB(0, 0), Bt, bcol, 0); STAGE(SA(0, 0), A, brow, 0);
;   STAGE(SB(0, 1), Bt, bcol1, 0); STAGE(SA(0, 1), A, brow + HALF, 0);
;   if (wr == 1) BAR;
;   WAIT_V(4); BAR;
;   STAGE(SB(1, 0), Bt, bcol, 1); STAGE(SA(1, 0), A, brow, 1); STAGE(SB(1, 1), Bt, bcol1, 1);
;   WAIT_V(6); BAR;
.LBB0_1235:
	s_or_b64 exec, exec, s[44:45]
	v_add_u32_e32 v162, s59, v15
	v_add_u32_e32 v163, 0x2000, v162
	v_readfirstlane_b32 s4, v162
	v_lshl_add_u64 v[6:7], v[6:7], 0, s[22:23]
	s_mov_b32 m0, s4
	v_readfirstlane_b32 s4, v163
	v_add_u32_e32 v164, 0x8000, v154
	s_waitcnt vmcnt(4)
	s_barrier
	global_load_lds_dwordx4 v[6:7], off
	v_lshl_add_u64 v[4:5], v[4:5], 0, s[22:23]
	s_mov_b32 m0, s4
	v_readfirstlane_b32 s4, v164
	v_add_u32_e32 v165, 0xa000, v154
	global_load_lds_dwordx4 v[4:5], off
	v_lshl_add_u64 v[2:3], v[2:3], 0, s[22:23]
	s_mov_b32 m0, s4
	v_readfirstlane_b32 s4, v165
	global_load_lds_dwordx4 v[2:3], off
	s_mov_b32 m0, s4
	s_add_u32 s4, s7, 0x5600080
	v_add_u32_e32 v168, s60, v15
	v_lshl_add_u64 v[0:1], v[0:1], 0, s[22:23]
	s_addc_u32 s5, s47, 0
	v_readfirstlane_b32 s7, v168
	global_load_lds_dwordx4 v[0:1], off
	v_lshl_add_u64 v[0:1], s[4:5], 0, v[148:149]
	s_mov_b32 m0, s7
	v_add_u32_e32 v171, 0x2000, v168
	global_load_lds_dwordx4 v[0:1], off
	v_lshl_add_u64 v[0:1], s[4:5], 0, v[128:129]
	v_readfirstlane_b32 s4, v171
	s_mov_b32 m0, s4
	v_and_b32_e32 v169, 15, v9
	global_load_lds_dwordx4 v[0:1], off
	v_bfe_u32 v146, v9, 4, 2
	v_lshlrev_b32_e32 v1, 2, v9
	v_lshlrev_b32_e32 v147, 4, v146
	v_lshlrev_b32_e32 v0, 6, v169
	v_and_b32_e32 v1, 32, v1
	v_bitop3_b32 v0, v147, v1, v0 bitop3:0x36
	v_add_u32_e32 v5, s33, v0
	v_add_u32_e32 v6, s58, v0
	v_add_u32_e32 v7, s59, v0
	v_add_u32_e32 v15, s60, v0
	v_add_u32_e32 v17, 0, v0
	v_lshlrev_b32_e32 v0, 6, v9
	v_and_or_b32 v0, v0, s83, v147
	v_xad_u32 v9, v0, v1, 0
	v_lshlrev_b32_e32 v0, 16, v8
	v_lshlrev_b32_e32 v2, 16, v11
	v_and_b32_e32 v0, 0xfffe0000, v0
	v_and_b32_e32 v2, 0xfffe0000, v2
	v_lshl_add_u32 v0, v10, 13, v0
	v_and_b32_e32 v1, 1, v8
	v_lshl_add_u32 v2, v13, 13, v2
	v_and_b32_e32 v3, 1, v11
	v_lshl_or_b32 v0, v1, 6, v0
	s_add_u32 s4, s20, s12
	v_lshl_or_b32 v2, v3, 6, v2
	v_lshl_add_u32 v0, v12, 1, v0
	v_mov_b32_e32 v1, v149
	s_addc_u32 s5, s21, s13
	v_lshl_add_u32 v2, v14, 1, v2
	v_mov_b32_e32 v3, v149
	v_lshl_add_u64 v[130:131], s[4:5], 0, v[0:1]
	v_lshl_add_u64 v[132:133], s[4:5], 0, v[2:3]
	s_add_u32 s4, s18, s14
	s_addc_u32 s5, s19, s15
	v_lshl_add_u64 v[134:135], s[4:5], 0, v[0:1]
	v_lshl_add_u64 v[136:137], s[4:5], 0, v[2:3]
	s_add_u32 s4, s20, s42
	v_bfe_u32 v144, v145, 6, 2
	s_waitcnt vmcnt(6)
	v_lshlrev_b32_e32 v16, 13, v167
	s_addc_u32 s5, s21, s43
	v_lshlrev_b32_e32 v4, 12, v144
	v_or_b32_e32 v18, 0x800, v16
	v_or_b32_e32 v19, 0x1000, v16
	v_or_b32_e32 v20, 0x1800, v16
	v_lshl_add_u64 v[138:139], s[4:5], 0, v[0:1]
	v_mov_b32_e32 v0, 0
	v_lshlrev_b32_e32 v170, 6, v167
	v_lshl_add_u64 v[140:141], s[4:5], 0, v[2:3]
	s_mov_b32 s7, -2
	s_mov_b64 s[4:5], 0
	v_add_u32_e32 v173, v5, v4
	v_add_u32_e32 v153, v17, v16
	v_add_u32_e32 v152, v9, v18
	v_add_u32_e32 v151, v9, v19
	v_add_u32_e32 v150, v9, v20
	v_add_u32_e32 v172, v6, v4
	v_add_u32_e32 v161, v7, v4
	v_add_u32_e32 v156, v15, v4
	v_mov_b32_e32 v1, v0
	v_mov_b32_e32 v2, v0
	v_mov_b32_e32 v3, v0
	v_mov_b32_e32 v4, v0
	v_mov_b32_e32 v5, v0
	v_mov_b32_e32 v6, v0
	v_mov_b32_e32 v7, v0
	v_mov_b32_e32 v8, v0
	v_mov_b32_e32 v9, v0
	v_mov_b32_e32 v10, v0
	v_mov_b32_e32 v11, v0
	v_mov_b32_e32 v12, v0
	v_mov_b32_e32 v13, v0
	v_mov_b32_e32 v14, v0
	v_mov_b32_e32 v15, v0
	v_mov_b32_e32 v16, v0
	v_mov_b32_e32 v17, v0
	v_mov_b32_e32 v18, v0
	v_mov_b32_e32 v19, v0
	v_mov_b32_e32 v20, v0
	v_mov_b32_e32 v21, v0
	v_mov_b32_e32 v22, v0
	v_mov_b32_e32 v23, v0
	v_mov_b32_e32 v24, v0
	v_mov_b32_e32 v25, v0
	v_mov_b32_e32 v26, v0
	v_mov_b32_e32 v27, v0
	v_mov_b32_e32 v28, v0
	v_mov_b32_e32 v29, v0
	v_mov_b32_e32 v30, v0
	v_mov_b32_e32 v31, v0
	v_mov_b32_e32 v32, v0
	v_mov_b32_e32 v33, v0
	v_mov_b32_e32 v34, v0
	v_mov_b32_e32 v35, v0
	v_mov_b32_e32 v36, v0
	v_mov_b32_e32 v37, v0
	v_mov_b32_e32 v38, v0
	v_mov_b32_e32 v39, v0
	v_mov_b32_e32 v40, v0
	v_mov_b32_e32 v41, v0
	v_mov_b32_e32 v42, v0
	v_mov_b32_e32 v43, v0
	v_mov_b32_e32 v44, v0
	v_mov_b32_e32 v45, v0
	v_mov_b32_e32 v46, v0
	v_mov_b32_e32 v47, v0
	v_mov_b32_e32 v48, v0
	v_mov_b32_e32 v49, v0
	v_mov_b32_e32 v50, v0
	v_mov_b32_e32 v51, v0
	v_mov_b32_e32 v52, v0
	v_mov_b32_e32 v53, v0
	v_mov_b32_e32 v54, v0
	v_mov_b32_e32 v55, v0
	v_mov_b32_e32 v56, v0
	v_mov_b32_e32 v57, v0
	v_mov_b32_e32 v58, v0
	v_mov_b32_e32 v59, v0
	v_mov_b32_e32 v60, v0
	v_mov_b32_e32 v61, v0
	v_mov_b32_e32 v62, v0
	v_mov_b32_e32 v63, v0
	v_mov_b32_e32 v64, v0
	v_mov_b32_e32 v65, v0
	v_mov_b32_e32 v66, v0
	v_mov_b32_e32 v67, v0
	v_mov_b32_e32 v68, v0
	v_mov_b32_e32 v69, v0
	v_mov_b32_e32 v70, v0
	v_mov_b32_e32 v71, v0
	v_mov_b32_e32 v72, v0
	v_mov_b32_e32 v73, v0
	v_mov_b32_e32 v74, v0
	v_mov_b32_e32 v75, v0
	v_mov_b32_e32 v76, v0
	v_mov_b32_e32 v77, v0
	v_mov_b32_e32 v78, v0
	v_mov_b32_e32 v79, v0
	v_mov_b32_e32 v80, v0
	v_mov_b32_e32 v81, v0
	v_mov_b32_e32 v82, v0
	v_mov_b32_e32 v83, v0
	v_mov_b32_e32 v84, v0
	v_mov_b32_e32 v85, v0
	v_mov_b32_e32 v86, v0
	v_mov_b32_e32 v87, v0
	v_mov_b32_e32 v88, v0
	v_mov_b32_e32 v89, v0
	v_mov_b32_e32 v90, v0
	v_mov_b32_e32 v91, v0
	v_mov_b32_e32 v92, v0
	v_mov_b32_e32 v93, v0
	v_mov_b32_e32 v94, v0
	v_mov_b32_e32 v95, v0
	v_mov_b32_e32 v96, v0
	v_mov_b32_e32 v97, v0
	v_mov_b32_e32 v98, v0
	v_mov_b32_e32 v99, v0
	v_mov_b32_e32 v100, v0
	v_mov_b32_e32 v101, v0
	v_mov_b32_e32 v102, v0
	v_mov_b32_e32 v103, v0
	v_mov_b32_e32 v104, v0
	v_mov_b32_e32 v105, v0
	v_mov_b32_e32 v106, v0
	v_mov_b32_e32 v107, v0
	v_mov_b32_e32 v108, v0
	v_mov_b32_e32 v109, v0
	v_mov_b32_e32 v110, v0
	v_mov_b32_e32 v111, v0
	v_mov_b32_e32 v112, v0
	v_mov_b32_e32 v113, v0
	v_mov_b32_e32 v114, v0
	v_mov_b32_e32 v115, v0
	v_mov_b32_e32 v116, v0
	v_mov_b32_e32 v117, v0
	v_mov_b32_e32 v118, v0
	v_mov_b32_e32 v119, v0
	v_mov_b32_e32 v120, v0
	v_mov_b32_e32 v121, v0
	v_mov_b32_e32 v122, v0
	v_mov_b32_e32 v123, v0
	v_mov_b32_e32 v124, v0
	v_mov_b32_e32 v125, v0
	v_mov_b32_e32 v126, v0
	v_mov_b32_e32 v127, v0
	s_barrier
; #define WAIT_L(n) asm volatile("s_waitcnt lgkmcnt(" #n ")" ::: "memory")
; #define BAR __builtin_amdgcn_s_barrier()
; #define SCHED __builtin_amdgcn_sched_barrier(0)
;     ...
;   for (int t = 0; t < nt - 2; t += 2) {
;     LDB(B0, 0, 0); SCHED; LDA(At, 0, 0); STAGE(SA(1, 1), A, brow + HALF, t + 1);
;     WAIT_L(8); BAR; WAIT_L(0); MMA(0, 0, At, B0); BAR; SCHED;
;     LDB(B1, 0, 1); STAGE(SB(0, 0), Bt, bcol, t + 2);
	v_readfirstlane_b32 s12, v154
	v_writelane_b32 v254, s64, 0
	v_writelane_b32 v254, s65, 1
	v_writelane_b32 v254, s66, 2
	v_writelane_b32 v254, s67, 3
	v_writelane_b32 v254, s68, 4
	v_writelane_b32 v254, s69, 5
	v_writelane_b32 v254, s70, 6
	v_writelane_b32 v254, s71, 7
	v_writelane_b32 v254, s72, 8
	v_writelane_b32 v254, s73, 9
	v_writelane_b32 v254, s74, 10
	v_writelane_b32 v254, s75, 11
	v_writelane_b32 v254, s76, 12
	v_writelane_b32 v254, s77, 13
	v_writelane_b32 v254, s78, 14
	v_writelane_b32 v254, s79, 15
	v_writelane_b32 v254, s80, 16
	v_writelane_b32 v254, s81, 17
	v_writelane_b32 v254, s82, 18
	v_writelane_b32 v254, s83, 19
	v_writelane_b32 v254, s84, 20
	v_writelane_b32 v254, s85, 21
	v_writelane_b32 v254, s86, 22
	v_writelane_b32 v254, s87, 23
	v_writelane_b32 v254, s88, 24
	v_writelane_b32 v254, s89, 25
	v_writelane_b32 v254, s90, 26
	v_writelane_b32 v254, s91, 27
	v_writelane_b32 v254, s92, 28
	v_writelane_b32 v254, s93, 29
	v_writelane_b32 v254, s94, 30
	v_writelane_b32 v254, s95, 31
	v_readfirstlane_b32 s64, v134
	v_readfirstlane_b32 s65, v135
	v_readfirstlane_b32 s66, v136
	v_readfirstlane_b32 s67, v137
	v_readfirstlane_b32 s68, v130
	v_readfirstlane_b32 s69, v131
	v_readfirstlane_b32 s70, v132
	v_readfirstlane_b32 s71, v133
	v_readfirstlane_b32 s72, v134
	v_readfirstlane_b32 s73, v135
	v_readfirstlane_b32 s74, v136
	v_readfirstlane_b32 s75, v137
	v_readfirstlane_b32 s76, v138
	v_readfirstlane_b32 s77, v139
	v_readfirstlane_b32 s78, v140
	v_readfirstlane_b32 s79, v141
	v_readfirstlane_b32 s80, v134
	v_readfirstlane_b32 s81, v135
	v_readfirstlane_b32 s82, v136
	v_readfirstlane_b32 s83, v137
	v_readfirstlane_b32 s84, v130
	v_readfirstlane_b32 s85, v131
	v_readfirstlane_b32 s86, v132
	v_readfirstlane_b32 s87, v133
	v_readfirstlane_b32 s88, v134
	v_readfirstlane_b32 s89, v135
	v_readfirstlane_b32 s90, v136
	v_readfirstlane_b32 s91, v137
	v_readfirstlane_b32 s92, v138
	v_readfirstlane_b32 s93, v139
	v_readfirstlane_b32 s94, v140
	v_readfirstlane_b32 s95, v141
	s_nop 3
	v_subrev_u32_e32 v159, s64, v134
	v_subrev_u32_e32 v160, s66, v136
	v_subrev_u32_e32 v157, s68, v130
	v_subrev_u32_e32 v158, s70, v132
	v_subrev_u32_e32 v162, s76, v138
	v_subrev_u32_e32 v163, s78, v140
	s_add_u32 s64, s64, s4
	s_addc_u32 s65, s65, s5
	s_add_u32 s64, s64, s24
	s_addc_u32 s65, s65, s25
	s_add_u32 s66, s66, s4
	s_addc_u32 s67, s67, s5
	s_add_u32 s66, s66, s24
	s_addc_u32 s67, s67, s25
	s_add_u32 s68, s68, s4
	s_addc_u32 s69, s69, s5
	s_add_u32 s68, s68, s26
	s_addc_u32 s69, s69, s27
	s_add_u32 s70, s70, s4
	s_addc_u32 s71, s71, s5
	s_add_u32 s70, s70, s26
	s_addc_u32 s71, s71, s27
	s_add_u32 s72, s72, s4
	s_addc_u32 s73, s73, s5
	s_add_u32 s72, s72, s26
	s_addc_u32 s73, s73, s27
	s_add_u32 s74, s74, s4
	s_addc_u32 s75, s75, s5
	s_add_u32 s74, s74, s26
	s_addc_u32 s75, s75, s27
	s_add_u32 s76, s76, s4
	s_addc_u32 s77, s77, s5
	s_add_u32 s76, s76, s28
	s_addc_u32 s77, s77, s29
	s_add_u32 s78, s78, s4
	s_addc_u32 s79, s79, s5
	s_add_u32 s78, s78, s28
	s_addc_u32 s79, s79, s29
	s_add_u32 s80, s80, s4
	s_addc_u32 s81, s81, s5
	s_add_u32 s80, s80, s30
	s_addc_u32 s81, s81, s31
	s_add_u32 s82, s82, s4
	s_addc_u32 s83, s83, s5
	s_add_u32 s82, s82, s30
	s_addc_u32 s83, s83, s31
	s_add_u32 s84, s84, s4
	s_addc_u32 s85, s85, s5
	s_add_u32 s84, s84, s34
	s_addc_u32 s85, s85, s35
	s_add_u32 s86, s86, s4
	s_addc_u32 s87, s87, s5
	s_add_u32 s86, s86, s34
	s_addc_u32 s87, s87, s35
	s_add_u32 s88, s88, s4
	s_addc_u32 s89, s89, s5
	s_add_u32 s88, s88, s34
	s_addc_u32 s89, s89, s35
	s_add_u32 s90, s90, s4
	s_addc_u32 s91, s91, s5
	s_add_u32 s90, s90, s34
	s_addc_u32 s91, s91, s35
	s_add_u32 s92, s92, s4
	s_addc_u32 s93, s93, s5
	s_add_u32 s92, s92, s36
	s_addc_u32 s93, s93, s37
	s_add_u32 s94, s94, s4
	s_addc_u32 s95, s95, s5
	s_add_u32 s94, s94, s36
	s_addc_u32 s95, s95, s37
.LBB0_1236:
	ds_read_b128 v[176:179], v173
	ds_read_b128 v[180:183], v173 offset:1024
	ds_read_b128 v[184:187], v173 offset:2048
	ds_read_b128 v[188:191], v173 offset:3072
	v_add_u32_e32 v174, 0xc000, v154
	v_add_u32_e32 v175, 0xe000, v154
	s_add_u32 m0, s12, 0xc000
	ds_read_b128 v[192:195], v153
	ds_read_b128 v[196:199], v153 offset:1024
	ds_read_b128 v[200:203], v152
	ds_read_b128 v[204:207], v152 offset:1024
	ds_read_b128 v[208:211], v151
	ds_read_b128 v[212:215], v151 offset:1024
	ds_read_b128 v[216:219], v150
	ds_read_b128 v[220:223], v150 offset:1024
	global_load_lds_dwordx4 v159, s[64:65]
	s_add_u32 s64, s64, 0x100
	s_addc_u32 s65, s65, 0
	s_add_u32 m0, s12, 0xe000
	s_nop 0
	global_load_lds_dwordx4 v160, s[66:67]
	s_add_u32 s66, s66, 0x100
	s_addc_u32 s67, s67, 0
	s_waitcnt lgkmcnt(8)
	s_barrier
	s_waitcnt lgkmcnt(0)
	s_waitcnt lgkmcnt(0)
	v_mfma_f32_16x16x32_bf16 v[124:127], v[176:179], v[192:195], v[124:127]
	v_mfma_f32_16x16x32_bf16 v[120:123], v[184:187], v[192:195], v[120:123]
	v_mfma_f32_16x16x32_bf16 v[116:119], v[176:179], v[200:203], v[116:119]
	v_mfma_f32_16x16x32_bf16 v[112:115], v[184:187], v[200:203], v[112:115]
	v_mfma_f32_16x16x32_bf16 v[108:111], v[176:179], v[208:211], v[108:111]
	v_mfma_f32_16x16x32_bf16 v[104:107], v[184:187], v[208:211], v[104:107]
	v_mfma_f32_16x16x32_bf16 v[100:103], v[176:179], v[216:219], v[100:103]
	v_mfma_f32_16x16x32_bf16 v[96:99], v[184:187], v[216:219], v[96:99]
	v_mfma_f32_16x16x32_bf16 v[124:127], v[180:183], v[196:199], v[124:127]
	v_mfma_f32_16x16x32_bf16 v[120:123], v[188:191], v[196:199], v[120:123]
	v_mfma_f32_16x16x32_bf16 v[116:119], v[180:183], v[204:207], v[116:119]
	v_mfma_f32_16x16x32_bf16 v[112:115], v[188:191], v[204:207], v[112:115]
	v_mfma_f32_16x16x32_bf16 v[108:111], v[180:183], v[212:215], v[108:111]
	v_mfma_f32_16x16x32_bf16 v[104:107], v[188:191], v[212:215], v[104:107]
	v_mfma_f32_16x16x32_bf16 v[100:103], v[180:183], v[220:223], v[100:103]
	v_mfma_f32_16x16x32_bf16 v[96:99], v[188:191], v[220:223], v[96:99]
	s_barrier
; #define WAIT_V(n) asm volatile("s_waitcnt vmcnt(" #n ")" ::: "memory")
; #define WAIT_L(n) asm volatile("s_waitcnt lgkmcnt(" #n ")" ::: "memory")
; #define BAR __builtin_amdgcn_s_barrier()
; #define SCHED __builtin_amdgcn_sched_barrier(0)
;     ...
;     LDB(B1, 0, 1); STAGE(SB(0, 0), Bt, bcol, t + 2);
;     BAR; WAIT_L(0); MMA(0, 1, At, B1); BAR;
;     LDA(At, 0, 1); STAGE(SA(0, 0), A, brow, t + 2);
;     BAR; WAIT_L(0); MMA(1, 0, At, B0); BAR; SCHED;
;     STAGE(SB(0, 1), Bt, bcol1, t + 2);
;     WAIT_V(6); BAR; MMA(1, 1, At, B1); BAR;
;     LDB(B0, 1, 0); SCHED; LDA(At, 1, 0); STAGE(SA(0, 1), A, brow + HALF, t + 2);
;     WAIT_L(8); BAR; WAIT_L(0); MMA(0, 0, At, B0); BAR; SCHED;
;     LDB(B1, 1, 1); STAGE(SB(1, 0), Bt, bcol, t + 3);
	s_add_u32 m0, s12, s33
	ds_read_b128 v[224:227], v172
	ds_read_b128 v[228:231], v172 offset:1024
	ds_read_b128 v[232:235], v172 offset:2048
	ds_read_b128 v[236:239], v172 offset:3072
	global_load_lds_dwordx4 v157, s[68:69]
	s_add_u32 s68, s68, 0x100
	s_addc_u32 s69, s69, 0
	s_add_u32 m0, s12, 0x2000
	s_add_u32 m0, m0, s33
	s_nop 0
	global_load_lds_dwordx4 v158, s[70:71]
	s_add_u32 s70, s70, 0x100
	s_addc_u32 s71, s71, 0
	s_barrier
	s_waitcnt lgkmcnt(0)
	s_waitcnt lgkmcnt(0)
	v_mfma_f32_16x16x32_bf16 v[92:95], v[224:227], v[192:195], v[92:95]
	v_mfma_f32_16x16x32_bf16 v[88:91], v[232:235], v[192:195], v[88:91]
	v_mfma_f32_16x16x32_bf16 v[84:87], v[224:227], v[200:203], v[84:87]
	v_mfma_f32_16x16x32_bf16 v[80:83], v[232:235], v[200:203], v[80:83]
	v_mfma_f32_16x16x32_bf16 v[76:79], v[224:227], v[208:211], v[76:79]
	v_mfma_f32_16x16x32_bf16 v[72:75], v[232:235], v[208:211], v[72:75]
	v_mfma_f32_16x16x32_bf16 v[68:71], v[224:227], v[216:219], v[68:71]
	v_mfma_f32_16x16x32_bf16 v[64:67], v[232:235], v[216:219], v[64:67]
	v_mfma_f32_16x16x32_bf16 v[92:95], v[228:231], v[196:199], v[92:95]
	v_mfma_f32_16x16x32_bf16 v[88:91], v[236:239], v[196:199], v[88:91]
	v_mfma_f32_16x16x32_bf16 v[84:87], v[228:231], v[204:207], v[84:87]
	v_mfma_f32_16x16x32_bf16 v[80:83], v[236:239], v[204:207], v[80:83]
	v_mfma_f32_16x16x32_bf16 v[76:79], v[228:231], v[212:215], v[76:79]
	v_mfma_f32_16x16x32_bf16 v[72:75], v[236:239], v[212:215], v[72:75]
	v_mfma_f32_16x16x32_bf16 v[68:71], v[228:231], v[220:223], v[68:71]
	v_mfma_f32_16x16x32_bf16 v[64:67], v[236:239], v[220:223], v[64:67]
	s_mov_b32 m0, s12
	s_barrier
	ds_read_b128 v[192:195], v153 offset:16384
	ds_read_b128 v[196:199], v153 offset:17408
	ds_read_b128 v[200:203], v152 offset:16384
	ds_read_b128 v[204:207], v152 offset:17408
	ds_read_b128 v[208:211], v151 offset:16384
	ds_read_b128 v[212:215], v151 offset:17408
	ds_read_b128 v[216:219], v150 offset:16384
	ds_read_b128 v[220:223], v150 offset:17408
	global_load_lds_dwordx4 v159, s[72:73]
	s_add_u32 s72, s72, 0x100
	s_addc_u32 s73, s73, 0
	s_add_u32 m0, s12, 0x2000
	s_nop 0
	global_load_lds_dwordx4 v160, s[74:75]
	s_add_u32 s74, s74, 0x100
	s_addc_u32 s75, s75, 0
	s_barrier
	s_waitcnt lgkmcnt(0)
	s_waitcnt lgkmcnt(0)
	v_mfma_f32_16x16x32_bf16 v[60:63], v[176:179], v[192:195], v[60:63]
	v_mfma_f32_16x16x32_bf16 v[56:59], v[184:187], v[192:195], v[56:59]
	v_mfma_f32_16x16x32_bf16 v[52:55], v[176:179], v[200:203], v[52:55]
	v_mfma_f32_16x16x32_bf16 v[48:51], v[184:187], v[200:203], v[48:51]
	v_mfma_f32_16x16x32_bf16 v[44:47], v[176:179], v[208:211], v[44:47]
	v_mfma_f32_16x16x32_bf16 v[40:43], v[184:187], v[208:211], v[40:43]
	v_mfma_f32_16x16x32_bf16 v[36:39], v[176:179], v[216:219], v[36:39]
	v_mfma_f32_16x16x32_bf16 v[32:35], v[184:187], v[216:219], v[32:35]
	v_mfma_f32_16x16x32_bf16 v[60:63], v[180:183], v[196:199], v[60:63]
	v_mfma_f32_16x16x32_bf16 v[56:59], v[188:191], v[196:199], v[56:59]
	v_mfma_f32_16x16x32_bf16 v[52:55], v[180:183], v[204:207], v[52:55]
	v_mfma_f32_16x16x32_bf16 v[48:51], v[188:191], v[204:207], v[48:51]
	v_mfma_f32_16x16x32_bf16 v[44:47], v[180:183], v[212:215], v[44:47]
	v_mfma_f32_16x16x32_bf16 v[40:43], v[188:191], v[212:215], v[40:43]
	v_mfma_f32_16x16x32_bf16 v[36:39], v[180:183], v[220:223], v[36:39]
	v_mfma_f32_16x16x32_bf16 v[32:35], v[188:191], v[220:223], v[32:35]
	s_barrier
	s_add_u32 m0, s12, s58
	s_nop 0
	global_load_lds_dwordx4 v162, s[76:77]
	s_add_u32 s76, s76, 0x100
	s_addc_u32 s77, s77, 0
	s_add_u32 m0, s12, 0x2000
	s_add_u32 m0, m0, s58
	s_nop 0
	global_load_lds_dwordx4 v163, s[78:79]
	s_add_u32 s78, s78, 0x100
	s_addc_u32 s79, s79, 0
	s_waitcnt vmcnt(6)
	s_barrier
	v_mfma_f32_16x16x32_bf16 v[28:31], v[224:227], v[192:195], v[28:31]
	v_mfma_f32_16x16x32_bf16 v[24:27], v[232:235], v[192:195], v[24:27]
	v_mfma_f32_16x16x32_bf16 v[20:23], v[224:227], v[200:203], v[20:23]
	v_mfma_f32_16x16x32_bf16 v[16:19], v[232:235], v[200:203], v[16:19]
	v_mfma_f32_16x16x32_bf16 v[12:15], v[224:227], v[208:211], v[12:15]
	v_mfma_f32_16x16x32_bf16 v[8:11], v[232:235], v[208:211], v[8:11]
	v_mfma_f32_16x16x32_bf16 v[4:7], v[224:227], v[216:219], v[4:7]
	v_mfma_f32_16x16x32_bf16 v[0:3], v[232:235], v[216:219], v[0:3]
	v_mfma_f32_16x16x32_bf16 v[28:31], v[228:231], v[196:199], v[28:31]
	v_mfma_f32_16x16x32_bf16 v[24:27], v[236:239], v[196:199], v[24:27]
	v_mfma_f32_16x16x32_bf16 v[20:23], v[228:231], v[204:207], v[20:23]
	v_mfma_f32_16x16x32_bf16 v[16:19], v[236:239], v[204:207], v[16:19]
	v_mfma_f32_16x16x32_bf16 v[12:15], v[228:231], v[212:215], v[12:15]
	v_mfma_f32_16x16x32_bf16 v[8:11], v[236:239], v[212:215], v[8:11]
	v_mfma_f32_16x16x32_bf16 v[4:7], v[228:231], v[220:223], v[4:7]
	v_mfma_f32_16x16x32_bf16 v[0:3], v[236:239], v[220:223], v[0:3]
	s_barrier
	ds_read_b128 v[176:179], v161
	ds_read_b128 v[180:183], v161 offset:1024
	ds_read_b128 v[184:187], v161 offset:2048
	ds_read_b128 v[188:191], v161 offset:3072
	s_add_u32 m0, s12, 0x4000
	ds_read_b128 v[192:195], v153 offset:32768
	ds_read_b128 v[196:199], v153 offset:33792
	ds_read_b128 v[200:203], v152 offset:32768
	ds_read_b128 v[204:207], v152 offset:33792
	ds_read_b128 v[208:211], v151 offset:32768
	ds_read_b128 v[212:215], v151 offset:33792
	ds_read_b128 v[216:219], v150 offset:32768
	ds_read_b128 v[220:223], v150 offset:33792
	global_load_lds_dwordx4 v159, s[80:81]
	s_add_u32 s80, s80, 0x100
	s_addc_u32 s81, s81, 0
	s_add_u32 m0, s12, 0x6000
	s_nop 0
	global_load_lds_dwordx4 v160, s[82:83]
	s_add_u32 s82, s82, 0x100
	s_addc_u32 s83, s83, 0
	s_waitcnt lgkmcnt(8)
	s_barrier
; #define WAIT_V(n) asm volatile("s_waitcnt vmcnt(" #n ")" ::: "memory")
; #define WAIT_L(n) asm volatile("s_waitcnt lgkmcnt(" #n ")" ::: "memory")
; #define BAR __builtin_amdgcn_s_barrier()
; #define SCHED __builtin_amdgcn_sched_barrier(0)
;     ...
;     WAIT_L(8); BAR; WAIT_L(0); MMA(0, 0, At, B0); BAR; SCHED;
;     LDB(B1, 1, 1); STAGE(SB(1, 0), Bt, bcol, t + 3);
;     BAR; WAIT_L(0); MMA(0, 1, At, B1); BAR;
;     LDA(At, 1, 1); STAGE(SA(1, 0), A, brow, t + 3);
;     BAR; WAIT_L(0); MMA(1, 0, At, B0); BAR; SCHED;
;     STAGE(SB(1, 1), Bt, bcol1, t + 3);
;     WAIT_V(6); BAR; MMA(1, 1, At, B1); BAR;
;   }
	s_waitcnt lgkmcnt(0)
	s_waitcnt lgkmcnt(0)
	v_mfma_f32_16x16x32_bf16 v[124:127], v[176:179], v[192:195], v[124:127]
	v_mfma_f32_16x16x32_bf16 v[120:123], v[184:187], v[192:195], v[120:123]
	v_mfma_f32_16x16x32_bf16 v[116:119], v[176:179], v[200:203], v[116:119]
	v_mfma_f32_16x16x32_bf16 v[112:115], v[184:187], v[200:203], v[112:115]
	v_mfma_f32_16x16x32_bf16 v[108:111], v[176:179], v[208:211], v[108:111]
	v_mfma_f32_16x16x32_bf16 v[104:107], v[184:187], v[208:211], v[104:107]
	v_mfma_f32_16x16x32_bf16 v[100:103], v[176:179], v[216:219], v[100:103]
	v_mfma_f32_16x16x32_bf16 v[96:99], v[184:187], v[216:219], v[96:99]
	v_mfma_f32_16x16x32_bf16 v[124:127], v[180:183], v[196:199], v[124:127]
	v_mfma_f32_16x16x32_bf16 v[120:123], v[188:191], v[196:199], v[120:123]
	v_mfma_f32_16x16x32_bf16 v[116:119], v[180:183], v[204:207], v[116:119]
	v_mfma_f32_16x16x32_bf16 v[112:115], v[188:191], v[204:207], v[112:115]
	v_mfma_f32_16x16x32_bf16 v[108:111], v[180:183], v[212:215], v[108:111]
	v_mfma_f32_16x16x32_bf16 v[104:107], v[188:191], v[212:215], v[104:107]
	v_mfma_f32_16x16x32_bf16 v[100:103], v[180:183], v[220:223], v[100:103]
	v_mfma_f32_16x16x32_bf16 v[96:99], v[188:191], v[220:223], v[96:99]
	s_barrier
	s_add_u32 m0, s12, s59
	ds_read_b128 v[224:227], v156
	ds_read_b128 v[228:231], v156 offset:1024
	ds_read_b128 v[232:235], v156 offset:2048
	ds_read_b128 v[236:239], v156 offset:3072
	global_load_lds_dwordx4 v157, s[84:85]
	s_add_u32 s84, s84, 0x100
	s_addc_u32 s85, s85, 0
	s_add_u32 m0, s12, 0x2000
	s_add_u32 m0, m0, s59
	s_nop 0
	global_load_lds_dwordx4 v158, s[86:87]
	s_add_u32 s86, s86, 0x100
	s_addc_u32 s87, s87, 0
	s_barrier
	s_waitcnt lgkmcnt(0)
	s_waitcnt lgkmcnt(0)
	v_mfma_f32_16x16x32_bf16 v[92:95], v[224:227], v[192:195], v[92:95]
	v_mfma_f32_16x16x32_bf16 v[88:91], v[232:235], v[192:195], v[88:91]
	v_mfma_f32_16x16x32_bf16 v[84:87], v[224:227], v[200:203], v[84:87]
	v_mfma_f32_16x16x32_bf16 v[80:83], v[232:235], v[200:203], v[80:83]
	v_mfma_f32_16x16x32_bf16 v[76:79], v[224:227], v[208:211], v[76:79]
	v_mfma_f32_16x16x32_bf16 v[72:75], v[232:235], v[208:211], v[72:75]
	v_mfma_f32_16x16x32_bf16 v[68:71], v[224:227], v[216:219], v[68:71]
	v_mfma_f32_16x16x32_bf16 v[64:67], v[232:235], v[216:219], v[64:67]
	v_mfma_f32_16x16x32_bf16 v[92:95], v[228:231], v[196:199], v[92:95]
	v_mfma_f32_16x16x32_bf16 v[88:91], v[236:239], v[196:199], v[88:91]
	v_mfma_f32_16x16x32_bf16 v[84:87], v[228:231], v[204:207], v[84:87]
	v_mfma_f32_16x16x32_bf16 v[80:83], v[236:239], v[204:207], v[80:83]
	v_mfma_f32_16x16x32_bf16 v[76:79], v[228:231], v[212:215], v[76:79]
	v_mfma_f32_16x16x32_bf16 v[72:75], v[236:239], v[212:215], v[72:75]
	v_mfma_f32_16x16x32_bf16 v[68:71], v[228:231], v[220:223], v[68:71]
	v_mfma_f32_16x16x32_bf16 v[64:67], v[236:239], v[220:223], v[64:67]
	s_add_u32 m0, s12, 0x8000
	s_barrier
	ds_read_b128 v[192:195], v153 offset:49152
	ds_read_b128 v[196:199], v153 offset:50176
	ds_read_b128 v[200:203], v152 offset:49152
	ds_read_b128 v[204:207], v152 offset:50176
	ds_read_b128 v[208:211], v151 offset:49152
	ds_read_b128 v[212:215], v151 offset:50176
	ds_read_b128 v[216:219], v150 offset:49152
	ds_read_b128 v[220:223], v150 offset:50176
	global_load_lds_dwordx4 v159, s[88:89]
	s_add_u32 s88, s88, 0x100
	s_addc_u32 s89, s89, 0
	s_add_u32 m0, s12, 0xa000
	s_nop 0
	global_load_lds_dwordx4 v160, s[90:91]
	s_add_u32 s90, s90, 0x100
	s_addc_u32 s91, s91, 0
	s_barrier
	s_waitcnt lgkmcnt(0)
	s_waitcnt lgkmcnt(0)
	v_mfma_f32_16x16x32_bf16 v[60:63], v[176:179], v[192:195], v[60:63]
	v_mfma_f32_16x16x32_bf16 v[56:59], v[184:187], v[192:195], v[56:59]
	v_mfma_f32_16x16x32_bf16 v[52:55], v[176:179], v[200:203], v[52:55]
	v_mfma_f32_16x16x32_bf16 v[48:51], v[184:187], v[200:203], v[48:51]
	v_mfma_f32_16x16x32_bf16 v[44:47], v[176:179], v[208:211], v[44:47]
	v_mfma_f32_16x16x32_bf16 v[40:43], v[184:187], v[208:211], v[40:43]
	v_mfma_f32_16x16x32_bf16 v[36:39], v[176:179], v[216:219], v[36:39]
	v_mfma_f32_16x16x32_bf16 v[32:35], v[184:187], v[216:219], v[32:35]
	v_mfma_f32_16x16x32_bf16 v[60:63], v[180:183], v[196:199], v[60:63]
	v_mfma_f32_16x16x32_bf16 v[56:59], v[188:191], v[196:199], v[56:59]
	v_mfma_f32_16x16x32_bf16 v[52:55], v[180:183], v[204:207], v[52:55]
	v_mfma_f32_16x16x32_bf16 v[48:51], v[188:191], v[204:207], v[48:51]
	v_mfma_f32_16x16x32_bf16 v[44:47], v[180:183], v[212:215], v[44:47]
	v_mfma_f32_16x16x32_bf16 v[40:43], v[188:191], v[212:215], v[40:43]
	v_mfma_f32_16x16x32_bf16 v[36:39], v[180:183], v[220:223], v[36:39]
	v_mfma_f32_16x16x32_bf16 v[32:35], v[188:191], v[220:223], v[32:35]
	s_barrier
	s_add_u32 m0, s12, s60
	s_nop 0
	global_load_lds_dwordx4 v162, s[92:93]
	s_add_u32 s92, s92, 0x100
	s_addc_u32 s93, s93, 0
	s_add_u32 m0, s12, 0x2000
	s_add_u32 m0, m0, s60
	s_nop 0
	global_load_lds_dwordx4 v163, s[94:95]
	s_add_u32 s94, s94, 0x100
	s_addc_u32 s95, s95, 0
	s_waitcnt vmcnt(6)
	s_barrier
	v_mfma_f32_16x16x32_bf16 v[28:31], v[224:227], v[192:195], v[28:31]
	v_mfma_f32_16x16x32_bf16 v[24:27], v[232:235], v[192:195], v[24:27]
	v_mfma_f32_16x16x32_bf16 v[20:23], v[224:227], v[200:203], v[20:23]
	v_mfma_f32_16x16x32_bf16 v[16:19], v[232:235], v[200:203], v[16:19]
	v_mfma_f32_16x16x32_bf16 v[12:15], v[224:227], v[208:211], v[12:15]
	v_mfma_f32_16x16x32_bf16 v[8:11], v[232:235], v[208:211], v[8:11]
	v_mfma_f32_16x16x32_bf16 v[4:7], v[224:227], v[216:219], v[4:7]
	v_mfma_f32_16x16x32_bf16 v[0:3], v[232:235], v[216:219], v[0:3]
	v_mfma_f32_16x16x32_bf16 v[28:31], v[228:231], v[196:199], v[28:31]
	v_mfma_f32_16x16x32_bf16 v[24:27], v[236:239], v[196:199], v[24:27]
	v_mfma_f32_16x16x32_bf16 v[20:23], v[228:231], v[204:207], v[20:23]
	v_mfma_f32_16x16x32_bf16 v[16:19], v[236:239], v[204:207], v[16:19]
	v_mfma_f32_16x16x32_bf16 v[12:15], v[228:231], v[212:215], v[12:15]
	v_mfma_f32_16x16x32_bf16 v[8:11], v[236:239], v[212:215], v[8:11]
	v_mfma_f32_16x16x32_bf16 v[4:7], v[228:231], v[220:223], v[4:7]
	v_mfma_f32_16x16x32_bf16 v[0:3], v[236:239], v[220:223], v[0:3]
	s_add_i32 s7, s7, 2
	s_add_u32 s4, s4, 0x100
	s_addc_u32 s5, s5, 0
	s_cmp_lt_u32 s7, 60
	s_barrier
; #define WAIT_V(n) asm volatile("s_waitcnt vmcnt(" #n ")" ::: "memory")
; #define WAIT_L(n) asm volatile("s_waitcnt lgkmcnt(" #n ")" ::: "memory")
; #define BAR __builtin_amdgcn_s_barrier()
;     ...
;   }
;   { LDB(B0, 0, 0); LDA(At, 0, 0); STAGE(SA(1, 1), A, brow + HALF, nt - 1);
;     BAR; WAIT_L(0); MMA(0, 0, At, B0); BAR;
;     LDB(B1, 0, 1); BAR; WAIT_L(0); MMA(0, 1, At, B1); BAR;
;     LDA(At, 0, 1); WAIT_V(4); BAR; WAIT_L(0); MMA(1, 0, At, B0); MMA(1, 1, At, B1); BAR; }
;   { LDB(B0, 1, 0); LDA(At, 1, 0); WAIT_V(2); BAR; WAIT_L(0); MMA(0, 0, At, B0); BAR;
	s_cbranch_scc1 .LBB0_1236
	v_readlane_b32 s64, v254, 0
	v_readlane_b32 s65, v254, 1
	v_readlane_b32 s66, v254, 2
	v_readlane_b32 s67, v254, 3
	v_readlane_b32 s68, v254, 4
	v_readlane_b32 s69, v254, 5
	v_readlane_b32 s70, v254, 6
	v_readlane_b32 s71, v254, 7
	v_readlane_b32 s72, v254, 8
	v_readlane_b32 s73, v254, 9
	v_readlane_b32 s74, v254, 10
	v_readlane_b32 s75, v254, 11
	v_readlane_b32 s76, v254, 12
	v_readlane_b32 s77, v254, 13
	v_readlane_b32 s78, v254, 14
	v_readlane_b32 s79, v254, 15
	v_readlane_b32 s80, v254, 16
	v_readlane_b32 s81, v254, 17
	v_readlane_b32 s82, v254, 18
	v_readlane_b32 s83, v254, 19
	v_readlane_b32 s84, v254, 20
	v_readlane_b32 s85, v254, 21
	v_readlane_b32 s86, v254, 22
	v_readlane_b32 s87, v254, 23
	v_readlane_b32 s88, v254, 24
	v_readlane_b32 s89, v254, 25
	v_readlane_b32 s90, v254, 26
	v_readlane_b32 s91, v254, 27
	v_readlane_b32 s92, v254, 28
	v_readlane_b32 s93, v254, 29
	v_readlane_b32 s94, v254, 30
	v_readlane_b32 s95, v254, 31
	s_nop 4
	s_add_u32 s4, s8, 0x1f80
	s_addc_u32 s5, s9, 0
	v_readfirstlane_b32 s7, v174
	v_lshl_add_u64 v[142:143], s[4:5], 0, v[148:149]
	s_mov_b32 m0, s7
	v_lshl_add_u64 v[128:129], s[4:5], 0, v[128:129]
	v_readfirstlane_b32 s4, v175
	ds_read_b128 v[130:133], v173
	ds_read_b128 v[134:137], v173 offset:1024
	ds_read_b128 v[138:141], v173 offset:2048
	ds_read_b128 v[162:165], v173 offset:3072
	ds_read_b128 v[176:179], v153
	ds_read_b128 v[180:183], v153 offset:1024
	ds_read_b128 v[184:187], v152
	ds_read_b128 v[188:191], v152 offset:1024
	ds_read_b128 v[192:195], v151
	ds_read_b128 v[196:199], v151 offset:1024
	ds_read_b128 v[200:203], v150
	ds_read_b128 v[204:207], v150 offset:1024
	global_load_lds_dwordx4 v[142:143], off
	s_mov_b32 m0, s4
	s_nop 0
	global_load_lds_dwordx4 v[128:129], off
	s_barrier
	s_waitcnt lgkmcnt(0)
	s_waitcnt lgkmcnt(0)
	v_mfma_f32_16x16x32_bf16 v[116:119], v[130:133], v[184:187], v[116:119]
	v_mfma_f32_16x16x32_bf16 v[108:111], v[130:133], v[192:195], v[108:111]
	v_mfma_f32_16x16x32_bf16 v[100:103], v[130:133], v[200:203], v[100:103]
	v_mfma_f32_16x16x32_bf16 v[96:99], v[138:141], v[200:203], v[96:99]
	v_mfma_f32_16x16x32_bf16 v[124:127], v[130:133], v[176:179], v[124:127]
	v_mfma_f32_16x16x32_bf16 v[120:123], v[138:141], v[176:179], v[120:123]
	v_mfma_f32_16x16x32_bf16 v[116:119], v[134:137], v[188:191], v[116:119]
	v_mfma_f32_16x16x32_bf16 v[112:115], v[138:141], v[184:187], v[112:115]
	v_mfma_f32_16x16x32_bf16 v[108:111], v[134:137], v[196:199], v[108:111]
	v_mfma_f32_16x16x32_bf16 v[104:107], v[138:141], v[192:195], v[104:107]
	v_mfma_f32_16x16x32_bf16 v[100:103], v[134:137], v[204:207], v[100:103]
	v_mfma_f32_16x16x32_bf16 v[96:99], v[162:165], v[204:207], v[96:99]
	v_mfma_f32_16x16x32_bf16 v[124:127], v[134:137], v[180:183], v[124:127]
	v_mfma_f32_16x16x32_bf16 v[208:211], v[162:165], v[180:183], v[120:123]
	v_mfma_f32_16x16x32_bf16 v[212:215], v[162:165], v[188:191], v[112:115]
	v_mfma_f32_16x16x32_bf16 v[216:219], v[162:165], v[196:199], v[104:107]
	s_barrier
	s_nop 0
	ds_read_b128 v[104:107], v172
	ds_read_b128 v[112:115], v172 offset:1024
	ds_read_b128 v[120:123], v172 offset:2048
	ds_read_b128 v[172:175], v172 offset:3072
	s_barrier
	s_waitcnt lgkmcnt(0)
	s_waitcnt lgkmcnt(0)
	v_mfma_f32_16x16x32_bf16 v[92:95], v[104:107], v[176:179], v[92:95]
	v_mfma_f32_16x16x32_bf16 v[84:87], v[104:107], v[184:187], v[84:87]
	v_mfma_f32_16x16x32_bf16 v[76:79], v[104:107], v[192:195], v[76:79]
	v_mfma_f32_16x16x32_bf16 v[64:67], v[120:123], v[200:203], v[64:67]
	v_mfma_f32_16x16x32_bf16 v[92:95], v[112:115], v[180:183], v[92:95]
	v_mfma_f32_16x16x32_bf16 v[88:91], v[120:123], v[176:179], v[88:91]
	v_mfma_f32_16x16x32_bf16 v[84:87], v[112:115], v[188:191], v[84:87]
	v_mfma_f32_16x16x32_bf16 v[80:83], v[120:123], v[184:187], v[80:83]
	v_mfma_f32_16x16x32_bf16 v[76:79], v[112:115], v[196:199], v[76:79]
	v_mfma_f32_16x16x32_bf16 v[72:75], v[120:123], v[192:195], v[72:75]
	v_mfma_f32_16x16x32_bf16 v[68:71], v[104:107], v[200:203], v[68:71]
	v_mfma_f32_16x16x32_bf16 v[64:67], v[172:175], v[204:207], v[64:67]
	v_mfma_f32_16x16x32_bf16 v[176:179], v[172:175], v[180:183], v[88:91]
	v_mfma_f32_16x16x32_bf16 v[180:183], v[172:175], v[188:191], v[80:83]
	v_mfma_f32_16x16x32_bf16 v[184:187], v[172:175], v[196:199], v[72:75]
	v_mfma_f32_16x16x32_bf16 v[188:191], v[112:115], v[204:207], v[68:71]
	s_barrier
	s_nop 0
	ds_read_b128 v[68:71], v153 offset:16384
	ds_read_b128 v[72:75], v153 offset:17408
	ds_read_b128 v[80:83], v152 offset:16384
	ds_read_b128 v[88:91], v152 offset:17408
	ds_read_b128 v[192:195], v151 offset:16384
	ds_read_b128 v[196:199], v151 offset:17408
	ds_read_b128 v[200:203], v150 offset:16384
	ds_read_b128 v[204:207], v150 offset:17408
	s_waitcnt vmcnt(4)
	s_barrier
; #define WAIT_V(n) asm volatile("s_waitcnt vmcnt(" #n ")" ::: "memory")
; #define WAIT_L(n) asm volatile("s_waitcnt lgkmcnt(" #n ")" ::: "memory")
; #define BAR __builtin_amdgcn_s_barrier()
;     ...
;     LDA(At, 0, 1); WAIT_V(4); BAR; WAIT_L(0); MMA(1, 0, At, B0); MMA(1, 1, At, B1); BAR; }
;   { LDB(B0, 1, 0); LDA(At, 1, 0); WAIT_V(2); BAR; WAIT_L(0); MMA(0, 0, At, B0); BAR;
	s_waitcnt lgkmcnt(0)
	s_waitcnt lgkmcnt(0)
	v_mfma_f32_16x16x32_bf16 v[60:63], v[130:133], v[68:71], v[60:63]
	v_mfma_f32_16x16x32_bf16 v[52:55], v[130:133], v[80:83], v[52:55]
	v_mfma_f32_16x16x32_bf16 v[44:47], v[130:133], v[192:195], v[44:47]
	v_mfma_f32_16x16x32_bf16 v[36:39], v[130:133], v[200:203], v[36:39]
	v_mfma_f32_16x16x32_bf16 v[32:35], v[138:141], v[200:203], v[32:35]
	v_mfma_f32_16x16x32_bf16 v[60:63], v[134:137], v[72:75], v[60:63]
	v_mfma_f32_16x16x32_bf16 v[56:59], v[138:141], v[68:71], v[56:59]
	v_mfma_f32_16x16x32_bf16 v[52:55], v[134:137], v[88:91], v[52:55]
	v_mfma_f32_16x16x32_bf16 v[48:51], v[138:141], v[80:83], v[48:51]
	v_mfma_f32_16x16x32_bf16 v[44:47], v[134:137], v[196:199], v[44:47]
	v_mfma_f32_16x16x32_bf16 v[40:43], v[138:141], v[192:195], v[40:43]
	v_mfma_f32_16x16x32_bf16 v[36:39], v[134:137], v[204:207], v[36:39]
	v_mfma_f32_16x16x32_bf16 v[32:35], v[162:165], v[204:207], v[32:35]
	v_mfma_f32_16x16x32_bf16 v[220:223], v[162:165], v[72:75], v[56:59]
	v_mfma_f32_16x16x32_bf16 v[224:227], v[162:165], v[88:91], v[48:51]
	v_mfma_f32_16x16x32_bf16 v[228:231], v[162:165], v[196:199], v[40:43]
	v_mfma_f32_16x16x32_bf16 v[28:31], v[104:107], v[68:71], v[28:31]
	v_mfma_f32_16x16x32_bf16 v[20:23], v[104:107], v[80:83], v[20:23]
	v_mfma_f32_16x16x32_bf16 v[12:15], v[104:107], v[192:195], v[12:15]
	v_mfma_f32_16x16x32_bf16 v[0:3], v[120:123], v[200:203], v[0:3]
	v_mfma_f32_16x16x32_bf16 v[28:31], v[112:115], v[72:75], v[28:31]
	v_mfma_f32_16x16x32_bf16 v[24:27], v[120:123], v[68:71], v[24:27]
	v_mfma_f32_16x16x32_bf16 v[20:23], v[112:115], v[88:91], v[20:23]
	v_mfma_f32_16x16x32_bf16 v[16:19], v[120:123], v[80:83], v[16:19]
	v_mfma_f32_16x16x32_bf16 v[12:15], v[112:115], v[196:199], v[12:15]
	v_mfma_f32_16x16x32_bf16 v[8:11], v[120:123], v[192:195], v[8:11]
	v_mfma_f32_16x16x32_bf16 v[4:7], v[104:107], v[200:203], v[4:7]
	v_mfma_f32_16x16x32_bf16 v[0:3], v[172:175], v[204:207], v[0:3]
	v_mfma_f32_16x16x32_bf16 v[128:131], v[172:175], v[72:75], v[24:27]
	v_mfma_f32_16x16x32_bf16 v[132:135], v[172:175], v[88:91], v[16:19]
	v_mfma_f32_16x16x32_bf16 v[136:139], v[172:175], v[196:199], v[8:11]
	v_mfma_f32_16x16x32_bf16 v[162:165], v[112:115], v[204:207], v[4:7]
	s_barrier
	s_nop 0
	ds_read_b128 v[4:7], v161
	ds_read_b128 v[172:175], v161 offset:1024
	ds_read_b128 v[192:195], v161 offset:2048
	ds_read_b128 v[158:161], v161 offset:3072
	ds_read_b128 v[8:11], v153 offset:32768
	ds_read_b128 v[16:19], v153 offset:33792
	ds_read_b128 v[24:27], v152 offset:32768
	ds_read_b128 v[40:43], v152 offset:33792
	ds_read_b128 v[48:51], v151 offset:32768
	ds_read_b128 v[56:59], v151 offset:33792
	ds_read_b128 v[196:199], v150 offset:32768
	ds_read_b128 v[200:203], v150 offset:33792
	s_waitcnt vmcnt(2)
	s_barrier
	s_waitcnt lgkmcnt(0)
	s_waitcnt lgkmcnt(0)
	v_mfma_f32_16x16x32_bf16 v[68:71], v[4:7], v[8:11], v[124:127]
	v_mfma_f32_16x16x32_bf16 v[120:123], v[172:175], v[16:19], v[68:71]
	v_mfma_f32_16x16x32_bf16 v[68:71], v[192:195], v[8:11], v[208:211]
	v_mfma_f32_16x16x32_bf16 v[88:91], v[158:161], v[16:19], v[68:71]
	v_mfma_f32_16x16x32_bf16 v[68:71], v[4:7], v[24:27], v[116:119]
	v_mfma_f32_16x16x32_bf16 v[112:115], v[172:175], v[40:43], v[68:71]
	v_mfma_f32_16x16x32_bf16 v[68:71], v[192:195], v[24:27], v[212:215]
	v_mfma_f32_16x16x32_bf16 v[80:83], v[158:161], v[40:43], v[68:71]
	v_mfma_f32_16x16x32_bf16 v[68:71], v[4:7], v[48:51], v[108:111]
	v_mfma_f32_16x16x32_bf16 v[104:107], v[172:175], v[56:59], v[68:71]
	v_mfma_f32_16x16x32_bf16 v[68:71], v[192:195], v[48:51], v[216:219]
	v_mfma_f32_16x16x32_bf16 v[72:75], v[158:161], v[56:59], v[68:71]
	v_mfma_f32_16x16x32_bf16 v[68:71], v[4:7], v[196:199], v[100:103]
	v_mfma_f32_16x16x32_bf16 v[100:103], v[172:175], v[200:203], v[68:71]
	v_mfma_f32_16x16x32_bf16 v[68:71], v[192:195], v[196:199], v[96:99]
	v_mfma_f32_16x16x32_bf16 v[68:71], v[158:161], v[200:203], v[68:71]
	s_barrier
; #define WAIT_V(n) asm volatile("s_waitcnt vmcnt(" #n ")" ::: "memory")
; #define WAIT_L(n) asm volatile("s_waitcnt lgkmcnt(" #n ")" ::: "memory")
; #define BAR __builtin_amdgcn_s_barrier()
;     ...
;   { LDB(B0, 1, 0); LDA(At, 1, 0); WAIT_V(2); BAR; WAIT_L(0); MMA(0, 0, At, B0); BAR;
;     LDB(B1, 1, 1); WAIT_V(0); BAR; WAIT_L(0); MMA(0, 1, At, B1); BAR;
;     LDA(At, 1, 1); BAR; WAIT_L(0); MMA(1, 0, At, B0); MMA(1, 1, At, B1); BAR; }
;   if (wr == 0) BAR;
	ds_read_b128 v[124:127], v156
	ds_read_b128 v[204:207], v156 offset:1024
	ds_read_b128 v[208:211], v156 offset:2048
	ds_read_b128 v[154:157], v156 offset:3072
	s_waitcnt vmcnt(0)
	s_barrier
	s_waitcnt lgkmcnt(0)
	s_waitcnt lgkmcnt(0)
	v_mfma_f32_16x16x32_bf16 v[92:95], v[124:127], v[8:11], v[92:95]
	v_mfma_f32_16x16x32_bf16 v[8:11], v[208:211], v[8:11], v[176:179]
	v_mfma_f32_16x16x32_bf16 v[140:143], v[204:207], v[16:19], v[92:95]
	v_mfma_f32_16x16x32_bf16 v[92:95], v[154:157], v[16:19], v[8:11]
	v_mfma_f32_16x16x32_bf16 v[8:11], v[124:127], v[24:27], v[84:87]
	v_mfma_f32_16x16x32_bf16 v[116:119], v[204:207], v[40:43], v[8:11]
	v_mfma_f32_16x16x32_bf16 v[8:11], v[208:211], v[24:27], v[180:183]
	v_mfma_f32_16x16x32_bf16 v[84:87], v[154:157], v[40:43], v[8:11]
	v_mfma_f32_16x16x32_bf16 v[8:11], v[124:127], v[48:51], v[76:79]
	v_mfma_f32_16x16x32_bf16 v[108:111], v[204:207], v[56:59], v[8:11]
	v_mfma_f32_16x16x32_bf16 v[8:11], v[208:211], v[48:51], v[184:187]
	v_mfma_f32_16x16x32_bf16 v[76:79], v[154:157], v[56:59], v[8:11]
	v_mfma_f32_16x16x32_bf16 v[8:11], v[124:127], v[196:199], v[188:191]
	v_mfma_f32_16x16x32_bf16 v[96:99], v[204:207], v[200:203], v[8:11]
	v_mfma_f32_16x16x32_bf16 v[8:11], v[208:211], v[196:199], v[64:67]
	v_mfma_f32_16x16x32_bf16 v[64:67], v[154:157], v[200:203], v[8:11]
	s_barrier
	ds_read_b128 v[176:179], v153 offset:49152
	ds_read_b128 v[180:183], v153 offset:50176
	ds_read_b128 v[184:187], v152 offset:49152
	ds_read_b128 v[188:191], v152 offset:50176
	ds_read_b128 v[196:199], v151 offset:49152
	ds_read_b128 v[200:203], v151 offset:50176
	ds_read_b128 v[212:215], v150 offset:49152
	ds_read_b128 v[150:153], v150 offset:50176
	s_barrier
	s_waitcnt lgkmcnt(0)
	s_waitcnt lgkmcnt(0)
	v_mfma_f32_16x16x32_bf16 v[8:11], v[4:7], v[176:179], v[60:63]
	v_mfma_f32_16x16x32_bf16 v[56:59], v[172:175], v[180:183], v[8:11]
	v_mfma_f32_16x16x32_bf16 v[8:11], v[192:195], v[176:179], v[220:223]
	v_mfma_f32_16x16x32_bf16 v[24:27], v[158:161], v[180:183], v[8:11]
	v_mfma_f32_16x16x32_bf16 v[8:11], v[4:7], v[184:187], v[52:55]
	v_mfma_f32_16x16x32_bf16 v[48:51], v[172:175], v[188:191], v[8:11]
	v_mfma_f32_16x16x32_bf16 v[8:11], v[192:195], v[184:187], v[224:227]
	v_mfma_f32_16x16x32_bf16 v[16:19], v[158:161], v[188:191], v[8:11]
	v_mfma_f32_16x16x32_bf16 v[8:11], v[4:7], v[196:199], v[44:47]
	v_mfma_f32_16x16x32_bf16 v[4:7], v[4:7], v[212:215], v[36:39]
	v_mfma_f32_16x16x32_bf16 v[40:43], v[172:175], v[200:203], v[8:11]
	v_mfma_f32_16x16x32_bf16 v[8:11], v[192:195], v[196:199], v[228:231]
	v_mfma_f32_16x16x32_bf16 v[36:39], v[172:175], v[150:153], v[4:7]
	v_mfma_f32_16x16x32_bf16 v[4:7], v[192:195], v[212:215], v[32:35]
	v_mfma_f32_16x16x32_bf16 v[8:11], v[158:161], v[200:203], v[8:11]
	v_mfma_f32_16x16x32_bf16 v[4:7], v[158:161], v[150:153], v[4:7]
	v_mfma_f32_16x16x32_bf16 v[28:31], v[124:127], v[176:179], v[28:31]
	v_mfma_f32_16x16x32_bf16 v[20:23], v[124:127], v[184:187], v[20:23]
	v_mfma_f32_16x16x32_bf16 v[12:15], v[124:127], v[196:199], v[12:15]
	v_mfma_f32_16x16x32_bf16 v[60:63], v[204:207], v[180:183], v[28:31]
	v_mfma_f32_16x16x32_bf16 v[28:31], v[208:211], v[176:179], v[128:131]
	v_mfma_f32_16x16x32_bf16 v[52:55], v[204:207], v[188:191], v[20:23]
	v_mfma_f32_16x16x32_bf16 v[20:23], v[208:211], v[184:187], v[132:135]
	v_mfma_f32_16x16x32_bf16 v[44:47], v[204:207], v[200:203], v[12:15]
	v_mfma_f32_16x16x32_bf16 v[12:15], v[208:211], v[196:199], v[136:139]
	v_mfma_f32_16x16x32_bf16 v[32:35], v[124:127], v[212:215], v[162:165]
	v_mfma_f32_16x16x32_bf16 v[0:3], v[208:211], v[212:215], v[0:3]
	v_mfma_f32_16x16x32_bf16 v[28:31], v[154:157], v[180:183], v[28:31]
	v_mfma_f32_16x16x32_bf16 v[20:23], v[154:157], v[188:191], v[20:23]
	v_mfma_f32_16x16x32_bf16 v[12:15], v[154:157], v[200:203], v[12:15]
	v_mfma_f32_16x16x32_bf16 v[32:35], v[204:207], v[150:153], v[32:35]
	v_mfma_f32_16x16x32_bf16 v[0:3], v[154:157], v[150:153], v[0:3]
	v_cmp_gt_u32_e64 s[4:5], s84, v145
	s_barrier
	s_and_saveexec_b64 s[8:9], s[4:5]
	s_cbranch_execz .LBB0_1239
	s_barrier

; #define WAIT_V(n) asm volatile("s_waitcnt vmcnt(" #n ")" ::: "memory")
; #define BAR __builtin_amdgcn_s_barrier()
;     ...
;   const int wid = tx >> 6, lane = tx & 63, wr = wid >> 2, wc = wid & 3, fr = lane & 15, fq = lane >> 4;
;   f32x4 acc[2][2][4][2] = {};
;   bf16x8 At[4][2], B0[2][2], B1[2][2];
;   const int nt = K / BK;
;   unsigned soff0, soff1;
;   { int _r, _c; stage_rc(tx * 16, _r, _c); soff0 = (unsigned)(_r * K + _c) * 2u;
;     stage_rc(tx * 16 + 8192, _r, _c); soff1 = (unsigned)(_r * K + _c) * 2u; }
;   STAGE(SB(0, 0), Bt, bcol, 0); STAGE(SA(0, 0), A, brow, 0);
;   STAGE(SB(0, 1), Bt, bcol1, 0); STAGE(SA(0, 1), A, brow + HALF, 0);
;   if (wr == 1) BAR;
;   WAIT_V(4); BAR;
;   STAGE(SB(1, 0), Bt, bcol, 1); STAGE(SA(1, 0), A, brow, 1); STAGE(SB(1, 1), Bt, bcol1, 1);
;   WAIT_V(6); BAR;
.LBB0_1334:
	s_or_b64 exec, exec, s[22:23]
	v_add_u32_e32 v162, s59, v15
	v_add_u32_e32 v163, 0x2000, v162
	v_readfirstlane_b32 s22, v162
	v_lshl_add_u64 v[6:7], v[6:7], 0, s[10:11]
	s_mov_b32 m0, s22
	v_readfirstlane_b32 s22, v163
	v_add_u32_e32 v164, 0x8000, v155
	s_waitcnt vmcnt(4)
	s_barrier
	global_load_lds_dwordx4 v[6:7], off
	v_lshl_add_u64 v[4:5], v[4:5], 0, s[10:11]
	s_mov_b32 m0, s22
	v_readfirstlane_b32 s22, v164
	v_add_u32_e32 v165, 0xa000, v155
	global_load_lds_dwordx4 v[4:5], off
	v_lshl_add_u64 v[2:3], v[2:3], 0, s[10:11]
	s_mov_b32 m0, s22
	v_readfirstlane_b32 s22, v165
	s_add_u32 s6, s6, 0x2b0080
	v_add_u32_e32 v166, s60, v15
	global_load_lds_dwordx4 v[2:3], off
	v_lshl_add_u64 v[0:1], v[0:1], 0, s[10:11]
	s_mov_b32 m0, s22
	s_addc_u32 s7, s7, 0
	v_readfirstlane_b32 s22, v166
	global_load_lds_dwordx4 v[0:1], off
	v_lshl_add_u64 v[0:1], s[6:7], 0, v[128:129]
	s_mov_b32 m0, s22
	v_add_u32_e32 v167, 0x2000, v166
	global_load_lds_dwordx4 v[0:1], off
	v_lshl_add_u64 v[0:1], s[6:7], 0, v[130:131]
	v_readfirstlane_b32 s6, v167
	s_mov_b32 m0, s6
	v_and_b32_e32 v142, 15, v140
	global_load_lds_dwordx4 v[0:1], off
	v_lshlrev_b32_e32 v2, 2, v140
	v_and_b32_e32 v0, 48, v140
	v_lshlrev_b32_e32 v1, 6, v142
	v_and_b32_e32 v2, 32, v2
	v_bitop3_b32 v1, v1, v2, v0 bitop3:0x36
	v_add_u32_e32 v5, s33, v1
	v_add_u32_e32 v6, s58, v1
	v_add_u32_e32 v7, s59, v1
	v_add_u32_e32 v15, s60, v1
	v_add_u32_e32 v18, 0, v1
	v_lshlrev_b32_e32 v1, 6, v140
	v_and_or_b32 v0, v1, s28, v0
	v_xad_u32 v19, v0, v2, 0
	v_lshrrev_b32_e32 v1, 1, v8
	v_mul_lo_u32 v0, v9, s27
	v_lshrrev_b32_e32 v3, 1, v12
	v_mul_lo_u32 v2, v13, s27
	v_mad_u64_u32 v[0:1], s[6:7], v1, s29, v[0:1]
	v_mad_u64_u32 v[2:3], s[22:23], v3, s29, v[2:3]
	v_or_b32_e32 v0, v0, v10
	s_add_u32 s6, s0, s37
	v_or_b32_e32 v2, v2, v14
	v_add_lshl_u32 v0, v0, v11, 1
	v_mov_b32_e32 v1, v129
	s_addc_u32 s7, s1, s38
	v_add_lshl_u32 v2, v2, v16, 1
	v_mov_b32_e32 v3, v129
	v_lshl_add_u64 v[132:133], s[6:7], 0, v[0:1]
	v_lshl_add_u64 v[134:135], s[6:7], 0, v[2:3]
	s_add_i32 s6, s35, s36
	s_mul_hi_i32 s7, s6, 0x5600
	s_mulk_i32 s6, 0x5600
	s_add_u32 s6, s2, s6
	v_bfe_u32 v141, v148, 6, 2
	s_waitcnt vmcnt(6)
	v_lshlrev_b32_e32 v143, 6, v17
	v_lshlrev_b32_e32 v17, 13, v17
	s_addc_u32 s7, s3, s7
	v_lshlrev_b32_e32 v4, 12, v141
	v_or_b32_e32 v20, 0x800, v17
	v_or_b32_e32 v21, 0x1000, v17
	v_or_b32_e32 v22, 0x1800, v17
	v_lshl_add_u64 v[136:137], s[6:7], 0, v[0:1]
	v_mov_b32_e32 v0, 0
	v_or_b32_e32 v149, v143, v142
	v_lshl_add_u64 v[138:139], s[6:7], 0, v[2:3]
	s_mov_b32 s22, -2
	s_mov_b64 s[6:7], 0
	v_add_u32_e32 v169, v5, v4
	v_add_u32_e32 v151, v18, v17
	v_add_u32_e32 v150, v19, v20
	v_add_u32_e32 v145, v19, v21
	v_add_u32_e32 v144, v19, v22
	v_add_u32_e32 v168, v6, v4
	v_add_u32_e32 v160, v7, v4
	v_add_u32_e32 v154, v15, v4
	v_mov_b32_e32 v1, v0
	v_mov_b32_e32 v2, v0
	v_mov_b32_e32 v3, v0
	v_mov_b32_e32 v4, v0
	v_mov_b32_e32 v5, v0
	v_mov_b32_e32 v6, v0
	v_mov_b32_e32 v7, v0
	v_mov_b32_e32 v8, v0
	v_mov_b32_e32 v9, v0
	v_mov_b32_e32 v10, v0
	v_mov_b32_e32 v11, v0
	v_mov_b32_e32 v12, v0
	v_mov_b32_e32 v13, v0
	v_mov_b32_e32 v14, v0
	v_mov_b32_e32 v15, v0
	v_mov_b32_e32 v16, v0
	v_mov_b32_e32 v17, v0
	v_mov_b32_e32 v18, v0
	v_mov_b32_e32 v19, v0
	v_mov_b32_e32 v20, v0
	v_mov_b32_e32 v21, v0
	v_mov_b32_e32 v22, v0
	v_mov_b32_e32 v23, v0
	v_mov_b32_e32 v24, v0
	v_mov_b32_e32 v25, v0
	v_mov_b32_e32 v26, v0
	v_mov_b32_e32 v27, v0
	v_mov_b32_e32 v28, v0
	v_mov_b32_e32 v29, v0
	v_mov_b32_e32 v30, v0
	v_mov_b32_e32 v31, v0
	v_mov_b32_e32 v32, v0
	v_mov_b32_e32 v33, v0
	v_mov_b32_e32 v34, v0
	v_mov_b32_e32 v35, v0
	v_mov_b32_e32 v36, v0
	v_mov_b32_e32 v37, v0
	v_mov_b32_e32 v38, v0
	v_mov_b32_e32 v39, v0
	v_mov_b32_e32 v40, v0
	v_mov_b32_e32 v41, v0
	v_mov_b32_e32 v42, v0
	v_mov_b32_e32 v43, v0
	v_mov_b32_e32 v44, v0
	v_mov_b32_e32 v45, v0
	v_mov_b32_e32 v46, v0
	v_mov_b32_e32 v47, v0
	v_mov_b32_e32 v48, v0
	v_mov_b32_e32 v49, v0
	v_mov_b32_e32 v50, v0
	v_mov_b32_e32 v51, v0
	v_mov_b32_e32 v52, v0
	v_mov_b32_e32 v53, v0
	v_mov_b32_e32 v54, v0
	v_mov_b32_e32 v55, v0
	v_mov_b32_e32 v56, v0
	v_mov_b32_e32 v57, v0
	v_mov_b32_e32 v58, v0
	v_mov_b32_e32 v59, v0
	v_mov_b32_e32 v60, v0
	v_mov_b32_e32 v61, v0
	v_mov_b32_e32 v62, v0
	v_mov_b32_e32 v63, v0
	v_mov_b32_e32 v64, v0
	v_mov_b32_e32 v65, v0
	v_mov_b32_e32 v66, v0
	v_mov_b32_e32 v67, v0
	v_mov_b32_e32 v68, v0
	v_mov_b32_e32 v69, v0
	v_mov_b32_e32 v70, v0
	v_mov_b32_e32 v71, v0
	v_mov_b32_e32 v72, v0
	v_mov_b32_e32 v73, v0
	v_mov_b32_e32 v74, v0
	v_mov_b32_e32 v75, v0
	v_mov_b32_e32 v76, v0
	v_mov_b32_e32 v77, v0
	v_mov_b32_e32 v78, v0
	v_mov_b32_e32 v79, v0
	v_mov_b32_e32 v80, v0
	v_mov_b32_e32 v81, v0
	v_mov_b32_e32 v82, v0
	v_mov_b32_e32 v83, v0
	v_mov_b32_e32 v84, v0
	v_mov_b32_e32 v85, v0
	v_mov_b32_e32 v86, v0
	v_mov_b32_e32 v87, v0
	v_mov_b32_e32 v88, v0
	v_mov_b32_e32 v89, v0
	v_mov_b32_e32 v90, v0
	v_mov_b32_e32 v91, v0
	v_mov_b32_e32 v92, v0
	v_mov_b32_e32 v93, v0
	v_mov_b32_e32 v94, v0
	v_mov_b32_e32 v95, v0
	v_mov_b32_e32 v96, v0
	v_mov_b32_e32 v97, v0
	v_mov_b32_e32 v98, v0
	v_mov_b32_e32 v99, v0
	v_mov_b32_e32 v100, v0
	v_mov_b32_e32 v101, v0
	v_mov_b32_e32 v102, v0
	v_mov_b32_e32 v103, v0
	v_mov_b32_e32 v104, v0
	v_mov_b32_e32 v105, v0
	v_mov_b32_e32 v106, v0
	v_mov_b32_e32 v107, v0
	v_mov_b32_e32 v108, v0
	v_mov_b32_e32 v109, v0
	v_mov_b32_e32 v110, v0
	v_mov_b32_e32 v111, v0
	v_mov_b32_e32 v112, v0
	v_mov_b32_e32 v113, v0
	v_mov_b32_e32 v114, v0
	v_mov_b32_e32 v115, v0
	v_mov_b32_e32 v116, v0
	v_mov_b32_e32 v117, v0
	v_mov_b32_e32 v118, v0
	v_mov_b32_e32 v119, v0
	v_mov_b32_e32 v120, v0
	v_mov_b32_e32 v121, v0
	v_mov_b32_e32 v122, v0
	v_mov_b32_e32 v123, v0
	v_mov_b32_e32 v124, v0
	v_mov_b32_e32 v125, v0
	v_mov_b32_e32 v126, v0
	v_mov_b32_e32 v127, v0
	s_barrier
; #define WAIT_L(n) asm volatile("s_waitcnt lgkmcnt(" #n ")" ::: "memory")
; #define BAR __builtin_amdgcn_s_barrier()
; #define SCHED __builtin_amdgcn_sched_barrier(0)
;     ...
;   for (int t = 0; t < nt - 2; t += 2) {
;     LDB(B0, 0, 0); SCHED; LDA(At, 0, 0); STAGE(SA(1, 1), A, brow + HALF, t + 1);
;     WAIT_L(8); BAR; WAIT_L(0); MMA(0, 0, At, B0); BAR; SCHED;
;     LDB(B1, 0, 1); STAGE(SB(0, 0), Bt, bcol, t + 2);
	v_readfirstlane_b32 s23, v155
	v_writelane_b32 v254, s64, 0
	v_writelane_b32 v254, s65, 1
	v_writelane_b32 v254, s66, 2
	v_writelane_b32 v254, s67, 3
	v_writelane_b32 v254, s68, 4
	v_writelane_b32 v254, s69, 5
	v_writelane_b32 v254, s70, 6
	v_writelane_b32 v254, s71, 7
	v_writelane_b32 v254, s72, 8
	v_writelane_b32 v254, s73, 9
	v_writelane_b32 v254, s74, 10
	v_writelane_b32 v254, s75, 11
	v_writelane_b32 v254, s76, 12
	v_writelane_b32 v254, s77, 13
	v_writelane_b32 v254, s78, 14
	v_writelane_b32 v254, s79, 15
	v_writelane_b32 v254, s80, 16
	v_writelane_b32 v254, s81, 17
	v_writelane_b32 v254, s82, 18
	v_writelane_b32 v254, s83, 19
	v_writelane_b32 v254, s84, 20
	v_writelane_b32 v254, s85, 21
	v_writelane_b32 v254, s86, 22
	v_writelane_b32 v254, s87, 23
	v_writelane_b32 v254, s88, 24
	v_writelane_b32 v254, s89, 25
	v_writelane_b32 v254, s90, 26
	v_writelane_b32 v254, s91, 27
	v_writelane_b32 v254, s92, 28
	v_writelane_b32 v254, s93, 29
	v_writelane_b32 v254, s94, 30
	v_writelane_b32 v254, s95, 31
	v_readfirstlane_b32 s64, v136
	v_readfirstlane_b32 s65, v137
	v_readfirstlane_b32 s66, v138
	v_readfirstlane_b32 s67, v139
	v_readfirstlane_b32 s68, v132
	v_readfirstlane_b32 s69, v133
	v_readfirstlane_b32 s70, v134
	v_readfirstlane_b32 s71, v135
	v_readfirstlane_b32 s72, v136
	v_readfirstlane_b32 s73, v137
	v_readfirstlane_b32 s74, v138
	v_readfirstlane_b32 s75, v139
	v_readfirstlane_b32 s76, v132
	v_readfirstlane_b32 s77, v133
	v_readfirstlane_b32 s78, v134
	v_readfirstlane_b32 s79, v135
	v_readfirstlane_b32 s80, v136
	v_readfirstlane_b32 s81, v137
	v_readfirstlane_b32 s82, v138
	v_readfirstlane_b32 s83, v139
	v_readfirstlane_b32 s84, v132
	v_readfirstlane_b32 s85, v133
	v_readfirstlane_b32 s86, v134
	v_readfirstlane_b32 s87, v135
	v_readfirstlane_b32 s88, v136
	v_readfirstlane_b32 s89, v137
	v_readfirstlane_b32 s90, v138
	v_readfirstlane_b32 s91, v139
	v_readfirstlane_b32 s92, v132
	v_readfirstlane_b32 s93, v133
	v_readfirstlane_b32 s94, v134
	v_readfirstlane_b32 s95, v135
	s_nop 3
	v_subrev_u32_e32 v158, s64, v136
	v_subrev_u32_e32 v159, s66, v138
	v_subrev_u32_e32 v156, s68, v132
	v_subrev_u32_e32 v157, s70, v134
	s_add_u32 s64, s64, s6
	s_addc_u32 s65, s65, s7
	s_add_u32 s64, s64, s12
	s_addc_u32 s65, s65, s13
	s_add_u32 s66, s66, s6
	s_addc_u32 s67, s67, s7
	s_add_u32 s66, s66, s12
	s_addc_u32 s67, s67, s13
	s_add_u32 s68, s68, s6
	s_addc_u32 s69, s69, s7
	s_add_u32 s68, s68, s14
	s_addc_u32 s69, s69, s15
	s_add_u32 s70, s70, s6
	s_addc_u32 s71, s71, s7
	s_add_u32 s70, s70, s14
	s_addc_u32 s71, s71, s15
	s_add_u32 s72, s72, s6
	s_addc_u32 s73, s73, s7
	s_add_u32 s72, s72, s14
	s_addc_u32 s73, s73, s15
	s_add_u32 s74, s74, s6
	s_addc_u32 s75, s75, s7
	s_add_u32 s74, s74, s14
	s_addc_u32 s75, s75, s15
	s_add_u32 s76, s76, s6
	s_addc_u32 s77, s77, s7
	s_add_u32 s76, s76, s16
	s_addc_u32 s77, s77, s17
	s_add_u32 s78, s78, s6
	s_addc_u32 s79, s79, s7
	s_add_u32 s78, s78, s16
	s_addc_u32 s79, s79, s17
	s_add_u32 s80, s80, s6
	s_addc_u32 s81, s81, s7
	s_add_u32 s80, s80, s16
	s_addc_u32 s81, s81, s17
	s_add_u32 s82, s82, s6
	s_addc_u32 s83, s83, s7
	s_add_u32 s82, s82, s16
	s_addc_u32 s83, s83, s17
	s_add_u32 s84, s84, s6
	s_addc_u32 s85, s85, s7
	s_add_u32 s84, s84, s18
	s_addc_u32 s85, s85, s19
	s_add_u32 s86, s86, s6
	s_addc_u32 s87, s87, s7
	s_add_u32 s86, s86, s18
	s_addc_u32 s87, s87, s19
	s_add_u32 s88, s88, s6
	s_addc_u32 s89, s89, s7
	s_add_u32 s88, s88, s18
	s_addc_u32 s89, s89, s19
	s_add_u32 s90, s90, s6
	s_addc_u32 s91, s91, s7
	s_add_u32 s90, s90, s18
	s_addc_u32 s91, s91, s19
	s_add_u32 s92, s92, s6
	s_addc_u32 s93, s93, s7
	s_add_u32 s92, s92, s20
	s_addc_u32 s93, s93, s21
	s_add_u32 s94, s94, s6
	s_addc_u32 s95, s95, s7
	s_add_u32 s94, s94, s20
	s_addc_u32 s95, s95, s21
.LBB0_1335:
	ds_read_b128 v[172:175], v169
	ds_read_b128 v[176:179], v169 offset:1024
	ds_read_b128 v[180:183], v169 offset:2048
	ds_read_b128 v[184:187], v169 offset:3072
	v_add_u32_e32 v170, 0xc000, v155
	v_add_u32_e32 v171, 0xe000, v155
	s_add_u32 m0, s23, 0xc000
	ds_read_b128 v[188:191], v151
	ds_read_b128 v[192:195], v151 offset:1024
	ds_read_b128 v[196:199], v150
	ds_read_b128 v[200:203], v150 offset:1024
	ds_read_b128 v[204:207], v145
	ds_read_b128 v[208:211], v145 offset:1024
	ds_read_b128 v[212:215], v144
	ds_read_b128 v[216:219], v144 offset:1024
	global_load_lds_dwordx4 v158, s[64:65]
	s_add_u32 s64, s64, 0x100
	s_addc_u32 s65, s65, 0
	s_add_u32 m0, s23, 0xe000
	s_nop 0
	global_load_lds_dwordx4 v159, s[66:67]
	s_add_u32 s66, s66, 0x100
	s_addc_u32 s67, s67, 0
	s_waitcnt lgkmcnt(8)
	s_barrier
	s_waitcnt lgkmcnt(0)
	s_waitcnt lgkmcnt(0)
	v_mfma_f32_16x16x32_bf16 v[124:127], v[172:175], v[188:191], v[124:127]
	v_mfma_f32_16x16x32_bf16 v[120:123], v[180:183], v[188:191], v[120:123]
	v_mfma_f32_16x16x32_bf16 v[116:119], v[172:175], v[196:199], v[116:119]
	v_mfma_f32_16x16x32_bf16 v[112:115], v[180:183], v[196:199], v[112:115]
	v_mfma_f32_16x16x32_bf16 v[108:111], v[172:175], v[204:207], v[108:111]
	v_mfma_f32_16x16x32_bf16 v[104:107], v[180:183], v[204:207], v[104:107]
	v_mfma_f32_16x16x32_bf16 v[100:103], v[172:175], v[212:215], v[100:103]
	v_mfma_f32_16x16x32_bf16 v[96:99], v[180:183], v[212:215], v[96:99]
	v_mfma_f32_16x16x32_bf16 v[124:127], v[176:179], v[192:195], v[124:127]
	v_mfma_f32_16x16x32_bf16 v[120:123], v[184:187], v[192:195], v[120:123]
	v_mfma_f32_16x16x32_bf16 v[116:119], v[176:179], v[200:203], v[116:119]
	v_mfma_f32_16x16x32_bf16 v[112:115], v[184:187], v[200:203], v[112:115]
	v_mfma_f32_16x16x32_bf16 v[108:111], v[176:179], v[208:211], v[108:111]
	v_mfma_f32_16x16x32_bf16 v[104:107], v[184:187], v[208:211], v[104:107]
	v_mfma_f32_16x16x32_bf16 v[100:103], v[176:179], v[216:219], v[100:103]
	v_mfma_f32_16x16x32_bf16 v[96:99], v[184:187], v[216:219], v[96:99]
	s_barrier
; #define WAIT_V(n) asm volatile("s_waitcnt vmcnt(" #n ")" ::: "memory")
; #define WAIT_L(n) asm volatile("s_waitcnt lgkmcnt(" #n ")" ::: "memory")
; #define BAR __builtin_amdgcn_s_barrier()
; #define SCHED __builtin_amdgcn_sched_barrier(0)
;     ...
;     LDB(B1, 0, 1); STAGE(SB(0, 0), Bt, bcol, t + 2);
;     BAR; WAIT_L(0); MMA(0, 1, At, B1); BAR;
;     LDA(At, 0, 1); STAGE(SA(0, 0), A, brow, t + 2);
;     BAR; WAIT_L(0); MMA(1, 0, At, B0); BAR; SCHED;
;     STAGE(SB(0, 1), Bt, bcol1, t + 2);
;     WAIT_V(6); BAR; MMA(1, 1, At, B1); BAR;
;     LDB(B0, 1, 0); SCHED; LDA(At, 1, 0); STAGE(SA(0, 1), A, brow + HALF, t + 2);
	s_add_u32 m0, s23, s33
	ds_read_b128 v[220:223], v168
	ds_read_b128 v[224:227], v168 offset:1024
	ds_read_b128 v[228:231], v168 offset:2048
	ds_read_b128 v[232:235], v168 offset:3072
	global_load_lds_dwordx4 v156, s[68:69]
	s_add_u32 s68, s68, 0x100
	s_addc_u32 s69, s69, 0
	s_add_u32 m0, s23, 0x2000
	s_add_u32 m0, m0, s33
	s_nop 0
	global_load_lds_dwordx4 v157, s[70:71]
	s_add_u32 s70, s70, 0x100
	s_addc_u32 s71, s71, 0
	s_barrier
	s_waitcnt lgkmcnt(0)
	s_waitcnt lgkmcnt(0)
	v_mfma_f32_16x16x32_bf16 v[92:95], v[220:223], v[188:191], v[92:95]
	v_mfma_f32_16x16x32_bf16 v[88:91], v[228:231], v[188:191], v[88:91]
	v_mfma_f32_16x16x32_bf16 v[84:87], v[220:223], v[196:199], v[84:87]
	v_mfma_f32_16x16x32_bf16 v[80:83], v[228:231], v[196:199], v[80:83]
	v_mfma_f32_16x16x32_bf16 v[76:79], v[220:223], v[204:207], v[76:79]
	v_mfma_f32_16x16x32_bf16 v[72:75], v[228:231], v[204:207], v[72:75]
	v_mfma_f32_16x16x32_bf16 v[68:71], v[220:223], v[212:215], v[68:71]
	v_mfma_f32_16x16x32_bf16 v[64:67], v[228:231], v[212:215], v[64:67]
	v_mfma_f32_16x16x32_bf16 v[92:95], v[224:227], v[192:195], v[92:95]
	v_mfma_f32_16x16x32_bf16 v[88:91], v[232:235], v[192:195], v[88:91]
	v_mfma_f32_16x16x32_bf16 v[84:87], v[224:227], v[200:203], v[84:87]
	v_mfma_f32_16x16x32_bf16 v[80:83], v[232:235], v[200:203], v[80:83]
	v_mfma_f32_16x16x32_bf16 v[76:79], v[224:227], v[208:211], v[76:79]
	v_mfma_f32_16x16x32_bf16 v[72:75], v[232:235], v[208:211], v[72:75]
	v_mfma_f32_16x16x32_bf16 v[68:71], v[224:227], v[216:219], v[68:71]
	v_mfma_f32_16x16x32_bf16 v[64:67], v[232:235], v[216:219], v[64:67]
	s_mov_b32 m0, s23
	s_barrier
	ds_read_b128 v[188:191], v151 offset:16384
	ds_read_b128 v[192:195], v151 offset:17408
	ds_read_b128 v[196:199], v150 offset:16384
	ds_read_b128 v[200:203], v150 offset:17408
	ds_read_b128 v[204:207], v145 offset:16384
	ds_read_b128 v[208:211], v145 offset:17408
	ds_read_b128 v[212:215], v144 offset:16384
	ds_read_b128 v[216:219], v144 offset:17408
	global_load_lds_dwordx4 v158, s[72:73]
	s_add_u32 s72, s72, 0x100
	s_addc_u32 s73, s73, 0
	s_add_u32 m0, s23, 0x2000
	s_nop 0
	global_load_lds_dwordx4 v159, s[74:75]
	s_add_u32 s74, s74, 0x100
	s_addc_u32 s75, s75, 0
	s_barrier
	s_waitcnt lgkmcnt(0)
	s_waitcnt lgkmcnt(0)
	v_mfma_f32_16x16x32_bf16 v[60:63], v[172:175], v[188:191], v[60:63]
	v_mfma_f32_16x16x32_bf16 v[56:59], v[180:183], v[188:191], v[56:59]
	v_mfma_f32_16x16x32_bf16 v[52:55], v[172:175], v[196:199], v[52:55]
	v_mfma_f32_16x16x32_bf16 v[48:51], v[180:183], v[196:199], v[48:51]
	v_mfma_f32_16x16x32_bf16 v[44:47], v[172:175], v[204:207], v[44:47]
	v_mfma_f32_16x16x32_bf16 v[40:43], v[180:183], v[204:207], v[40:43]
	v_mfma_f32_16x16x32_bf16 v[36:39], v[172:175], v[212:215], v[36:39]
	v_mfma_f32_16x16x32_bf16 v[32:35], v[180:183], v[212:215], v[32:35]
	v_mfma_f32_16x16x32_bf16 v[60:63], v[176:179], v[192:195], v[60:63]
	v_mfma_f32_16x16x32_bf16 v[56:59], v[184:187], v[192:195], v[56:59]
	v_mfma_f32_16x16x32_bf16 v[52:55], v[176:179], v[200:203], v[52:55]
	v_mfma_f32_16x16x32_bf16 v[48:51], v[184:187], v[200:203], v[48:51]
	v_mfma_f32_16x16x32_bf16 v[44:47], v[176:179], v[208:211], v[44:47]
	v_mfma_f32_16x16x32_bf16 v[40:43], v[184:187], v[208:211], v[40:43]
	v_mfma_f32_16x16x32_bf16 v[36:39], v[176:179], v[216:219], v[36:39]
	v_mfma_f32_16x16x32_bf16 v[32:35], v[184:187], v[216:219], v[32:35]
	s_barrier
	s_add_u32 m0, s23, s58
	s_nop 0
	global_load_lds_dwordx4 v156, s[76:77]
	s_add_u32 s76, s76, 0x100
	s_addc_u32 s77, s77, 0
	s_add_u32 m0, s23, 0x2000
	s_add_u32 m0, m0, s58
	s_nop 0
	global_load_lds_dwordx4 v157, s[78:79]
	s_add_u32 s78, s78, 0x100
	s_addc_u32 s79, s79, 0
	s_waitcnt vmcnt(6)
	s_barrier
	v_mfma_f32_16x16x32_bf16 v[28:31], v[220:223], v[188:191], v[28:31]
	v_mfma_f32_16x16x32_bf16 v[24:27], v[228:231], v[188:191], v[24:27]
	v_mfma_f32_16x16x32_bf16 v[20:23], v[220:223], v[196:199], v[20:23]
	v_mfma_f32_16x16x32_bf16 v[16:19], v[228:231], v[196:199], v[16:19]
	v_mfma_f32_16x16x32_bf16 v[12:15], v[220:223], v[204:207], v[12:15]
	v_mfma_f32_16x16x32_bf16 v[8:11], v[228:231], v[204:207], v[8:11]
	v_mfma_f32_16x16x32_bf16 v[4:7], v[220:223], v[212:215], v[4:7]
	v_mfma_f32_16x16x32_bf16 v[0:3], v[228:231], v[212:215], v[0:3]
	v_mfma_f32_16x16x32_bf16 v[28:31], v[224:227], v[192:195], v[28:31]
	v_mfma_f32_16x16x32_bf16 v[24:27], v[232:235], v[192:195], v[24:27]
	v_mfma_f32_16x16x32_bf16 v[20:23], v[224:227], v[200:203], v[20:23]
	v_mfma_f32_16x16x32_bf16 v[16:19], v[232:235], v[200:203], v[16:19]
	v_mfma_f32_16x16x32_bf16 v[12:15], v[224:227], v[208:211], v[12:15]
	v_mfma_f32_16x16x32_bf16 v[8:11], v[232:235], v[208:211], v[8:11]
	v_mfma_f32_16x16x32_bf16 v[4:7], v[224:227], v[216:219], v[4:7]
	v_mfma_f32_16x16x32_bf16 v[0:3], v[232:235], v[216:219], v[0:3]
	s_barrier
	ds_read_b128 v[172:175], v160
	ds_read_b128 v[176:179], v160 offset:1024
	ds_read_b128 v[180:183], v160 offset:2048
	ds_read_b128 v[184:187], v160 offset:3072
	s_add_u32 m0, s23, 0x4000
	ds_read_b128 v[188:191], v151 offset:32768
	ds_read_b128 v[192:195], v151 offset:33792
	ds_read_b128 v[196:199], v150 offset:32768
	ds_read_b128 v[200:203], v150 offset:33792
	ds_read_b128 v[204:207], v145 offset:32768
	ds_read_b128 v[208:211], v145 offset:33792
	ds_read_b128 v[212:215], v144 offset:32768
	ds_read_b128 v[216:219], v144 offset:33792
	global_load_lds_dwordx4 v158, s[80:81]
	s_add_u32 s80, s80, 0x100
	s_addc_u32 s81, s81, 0
	s_add_u32 m0, s23, 0x6000
	s_nop 0
	global_load_lds_dwordx4 v159, s[82:83]
	s_add_u32 s82, s82, 0x100
	s_addc_u32 s83, s83, 0
	s_waitcnt lgkmcnt(8)
	s_barrier
; #define WAIT_V(n) asm volatile("s_waitcnt vmcnt(" #n ")" ::: "memory")
; #define WAIT_L(n) asm volatile("s_waitcnt lgkmcnt(" #n ")" ::: "memory")
; #define BAR __builtin_amdgcn_s_barrier()
; #define SCHED __builtin_amdgcn_sched_barrier(0)
;     ...
;     WAIT_L(8); BAR; WAIT_L(0); MMA(0, 0, At, B0); BAR; SCHED;
;     LDB(B1, 1, 1); STAGE(SB(1, 0), Bt, bcol, t + 3);
;     BAR; WAIT_L(0); MMA(0, 1, At, B1); BAR;
;     LDA(At, 1, 1); STAGE(SA(1, 0), A, brow, t + 3);
;     BAR; WAIT_L(0); MMA(1, 0, At, B0); BAR; SCHED;
;     STAGE(SB(1, 1), Bt, bcol1, t + 3);
;     WAIT_V(6); BAR; MMA(1, 1, At, B1); BAR;
	s_waitcnt lgkmcnt(0)
	s_waitcnt lgkmcnt(0)
	v_mfma_f32_16x16x32_bf16 v[124:127], v[172:175], v[188:191], v[124:127]
	v_mfma_f32_16x16x32_bf16 v[120:123], v[180:183], v[188:191], v[120:123]
	v_mfma_f32_16x16x32_bf16 v[116:119], v[172:175], v[196:199], v[116:119]
	v_mfma_f32_16x16x32_bf16 v[112:115], v[180:183], v[196:199], v[112:115]
	v_mfma_f32_16x16x32_bf16 v[108:111], v[172:175], v[204:207], v[108:111]
	v_mfma_f32_16x16x32_bf16 v[104:107], v[180:183], v[204:207], v[104:107]
	v_mfma_f32_16x16x32_bf16 v[100:103], v[172:175], v[212:215], v[100:103]
	v_mfma_f32_16x16x32_bf16 v[96:99], v[180:183], v[212:215], v[96:99]
	v_mfma_f32_16x16x32_bf16 v[124:127], v[176:179], v[192:195], v[124:127]
	v_mfma_f32_16x16x32_bf16 v[120:123], v[184:187], v[192:195], v[120:123]
	v_mfma_f32_16x16x32_bf16 v[116:119], v[176:179], v[200:203], v[116:119]
	v_mfma_f32_16x16x32_bf16 v[112:115], v[184:187], v[200:203], v[112:115]
	v_mfma_f32_16x16x32_bf16 v[108:111], v[176:179], v[208:211], v[108:111]
	v_mfma_f32_16x16x32_bf16 v[104:107], v[184:187], v[208:211], v[104:107]
	v_mfma_f32_16x16x32_bf16 v[100:103], v[176:179], v[216:219], v[100:103]
	v_mfma_f32_16x16x32_bf16 v[96:99], v[184:187], v[216:219], v[96:99]
	s_barrier
	s_add_u32 m0, s23, s59
	ds_read_b128 v[220:223], v154
	ds_read_b128 v[224:227], v154 offset:1024
	ds_read_b128 v[228:231], v154 offset:2048
	ds_read_b128 v[232:235], v154 offset:3072
	global_load_lds_dwordx4 v156, s[84:85]
	s_add_u32 s84, s84, 0x100
	s_addc_u32 s85, s85, 0
	s_add_u32 m0, s23, 0x2000
	s_add_u32 m0, m0, s59
	s_nop 0
	global_load_lds_dwordx4 v157, s[86:87]
	s_add_u32 s86, s86, 0x100
	s_addc_u32 s87, s87, 0
	s_barrier
	s_waitcnt lgkmcnt(0)
	s_waitcnt lgkmcnt(0)
	v_mfma_f32_16x16x32_bf16 v[92:95], v[220:223], v[188:191], v[92:95]
	v_mfma_f32_16x16x32_bf16 v[88:91], v[228:231], v[188:191], v[88:91]
	v_mfma_f32_16x16x32_bf16 v[84:87], v[220:223], v[196:199], v[84:87]
	v_mfma_f32_16x16x32_bf16 v[80:83], v[228:231], v[196:199], v[80:83]
	v_mfma_f32_16x16x32_bf16 v[76:79], v[220:223], v[204:207], v[76:79]
	v_mfma_f32_16x16x32_bf16 v[72:75], v[228:231], v[204:207], v[72:75]
	v_mfma_f32_16x16x32_bf16 v[68:71], v[220:223], v[212:215], v[68:71]
	v_mfma_f32_16x16x32_bf16 v[64:67], v[228:231], v[212:215], v[64:67]
	v_mfma_f32_16x16x32_bf16 v[92:95], v[224:227], v[192:195], v[92:95]
	v_mfma_f32_16x16x32_bf16 v[88:91], v[232:235], v[192:195], v[88:91]
	v_mfma_f32_16x16x32_bf16 v[84:87], v[224:227], v[200:203], v[84:87]
	v_mfma_f32_16x16x32_bf16 v[80:83], v[232:235], v[200:203], v[80:83]
	v_mfma_f32_16x16x32_bf16 v[76:79], v[224:227], v[208:211], v[76:79]
	v_mfma_f32_16x16x32_bf16 v[72:75], v[232:235], v[208:211], v[72:75]
	v_mfma_f32_16x16x32_bf16 v[68:71], v[224:227], v[216:219], v[68:71]
	v_mfma_f32_16x16x32_bf16 v[64:67], v[232:235], v[216:219], v[64:67]
	s_add_u32 m0, s23, 0x8000
	s_barrier
	ds_read_b128 v[188:191], v151 offset:49152
	ds_read_b128 v[192:195], v151 offset:50176
	ds_read_b128 v[196:199], v150 offset:49152
	ds_read_b128 v[200:203], v150 offset:50176
	ds_read_b128 v[204:207], v145 offset:49152
	ds_read_b128 v[208:211], v145 offset:50176
	ds_read_b128 v[212:215], v144 offset:49152
	ds_read_b128 v[216:219], v144 offset:50176
	global_load_lds_dwordx4 v158, s[88:89]
	s_add_u32 s88, s88, 0x100
	s_addc_u32 s89, s89, 0
	s_add_u32 m0, s23, 0xa000
	s_nop 0
	global_load_lds_dwordx4 v159, s[90:91]
	s_add_u32 s90, s90, 0x100
	s_addc_u32 s91, s91, 0
	s_barrier
	s_waitcnt lgkmcnt(0)
	s_waitcnt lgkmcnt(0)
	v_mfma_f32_16x16x32_bf16 v[60:63], v[172:175], v[188:191], v[60:63]
	v_mfma_f32_16x16x32_bf16 v[56:59], v[180:183], v[188:191], v[56:59]
	v_mfma_f32_16x16x32_bf16 v[52:55], v[172:175], v[196:199], v[52:55]
	v_mfma_f32_16x16x32_bf16 v[48:51], v[180:183], v[196:199], v[48:51]
	v_mfma_f32_16x16x32_bf16 v[44:47], v[172:175], v[204:207], v[44:47]
	v_mfma_f32_16x16x32_bf16 v[40:43], v[180:183], v[204:207], v[40:43]
	v_mfma_f32_16x16x32_bf16 v[36:39], v[172:175], v[212:215], v[36:39]
	v_mfma_f32_16x16x32_bf16 v[32:35], v[180:183], v[212:215], v[32:35]
	v_mfma_f32_16x16x32_bf16 v[60:63], v[176:179], v[192:195], v[60:63]
	v_mfma_f32_16x16x32_bf16 v[56:59], v[184:187], v[192:195], v[56:59]
	v_mfma_f32_16x16x32_bf16 v[52:55], v[176:179], v[200:203], v[52:55]
	v_mfma_f32_16x16x32_bf16 v[48:51], v[184:187], v[200:203], v[48:51]
	v_mfma_f32_16x16x32_bf16 v[44:47], v[176:179], v[208:211], v[44:47]
	v_mfma_f32_16x16x32_bf16 v[40:43], v[184:187], v[208:211], v[40:43]
	v_mfma_f32_16x16x32_bf16 v[36:39], v[176:179], v[216:219], v[36:39]
	v_mfma_f32_16x16x32_bf16 v[32:35], v[184:187], v[216:219], v[32:35]
	s_barrier
	s_add_u32 m0, s23, s60
	s_nop 0
	global_load_lds_dwordx4 v156, s[92:93]
	s_add_u32 s92, s92, 0x100
	s_addc_u32 s93, s93, 0
	s_add_u32 m0, s23, 0x2000
	s_add_u32 m0, m0, s60
	s_nop 0
	global_load_lds_dwordx4 v157, s[94:95]
	s_add_u32 s94, s94, 0x100
	s_addc_u32 s95, s95, 0
	s_waitcnt vmcnt(6)
	s_barrier
	v_mfma_f32_16x16x32_bf16 v[28:31], v[220:223], v[188:191], v[28:31]
	v_mfma_f32_16x16x32_bf16 v[24:27], v[228:231], v[188:191], v[24:27]
	v_mfma_f32_16x16x32_bf16 v[20:23], v[220:223], v[196:199], v[20:23]
	v_mfma_f32_16x16x32_bf16 v[16:19], v[228:231], v[196:199], v[16:19]
	v_mfma_f32_16x16x32_bf16 v[12:15], v[220:223], v[204:207], v[12:15]
	v_mfma_f32_16x16x32_bf16 v[8:11], v[228:231], v[204:207], v[8:11]
	v_mfma_f32_16x16x32_bf16 v[4:7], v[220:223], v[212:215], v[4:7]
	v_mfma_f32_16x16x32_bf16 v[0:3], v[228:231], v[212:215], v[0:3]
	v_mfma_f32_16x16x32_bf16 v[28:31], v[224:227], v[192:195], v[28:31]
	v_mfma_f32_16x16x32_bf16 v[24:27], v[232:235], v[192:195], v[24:27]
	v_mfma_f32_16x16x32_bf16 v[20:23], v[224:227], v[200:203], v[20:23]
	v_mfma_f32_16x16x32_bf16 v[16:19], v[232:235], v[200:203], v[16:19]
	v_mfma_f32_16x16x32_bf16 v[12:15], v[224:227], v[208:211], v[12:15]
	v_mfma_f32_16x16x32_bf16 v[8:11], v[232:235], v[208:211], v[8:11]
	v_mfma_f32_16x16x32_bf16 v[4:7], v[224:227], v[216:219], v[4:7]
	v_mfma_f32_16x16x32_bf16 v[0:3], v[232:235], v[216:219], v[0:3]
	s_add_i32 s22, s22, 2
	s_add_u32 s6, s6, 0x100
	s_addc_u32 s7, s7, 0
	s_cmpk_lt_u32 s22, 0xa8
	s_barrier
; #define WAIT_V(n) asm volatile("s_waitcnt vmcnt(" #n ")" ::: "memory")
; #define WAIT_L(n) asm volatile("s_waitcnt lgkmcnt(" #n ")" ::: "memory")
; #define BAR __builtin_amdgcn_s_barrier()
;     ...
;   { LDB(B0, 0, 0); LDA(At, 0, 0); STAGE(SA(1, 1), A, brow + HALF, nt - 1);
;     BAR; WAIT_L(0); MMA(0, 0, At, B0); BAR;
;     LDB(B1, 0, 1); BAR; WAIT_L(0); MMA(0, 1, At, B1); BAR;
;     LDA(At, 0, 1); WAIT_V(4); BAR; WAIT_L(0); MMA(1, 0, At, B0); MMA(1, 1, At, B1); BAR; }
	s_cbranch_scc1 .LBB0_1335
	v_readlane_b32 s64, v254, 0
	v_readlane_b32 s65, v254, 1
	v_readlane_b32 s66, v254, 2
	v_readlane_b32 s67, v254, 3
	v_readlane_b32 s68, v254, 4
	v_readlane_b32 s69, v254, 5
	v_readlane_b32 s70, v254, 6
	v_readlane_b32 s71, v254, 7
	v_readlane_b32 s72, v254, 8
	v_readlane_b32 s73, v254, 9
	v_readlane_b32 s74, v254, 10
	v_readlane_b32 s75, v254, 11
	v_readlane_b32 s76, v254, 12
	v_readlane_b32 s77, v254, 13
	v_readlane_b32 s78, v254, 14
	v_readlane_b32 s79, v254, 15
	v_readlane_b32 s80, v254, 16
	v_readlane_b32 s81, v254, 17
	v_readlane_b32 s82, v254, 18
	v_readlane_b32 s83, v254, 19
	v_readlane_b32 s84, v254, 20
	v_readlane_b32 s85, v254, 21
	v_readlane_b32 s86, v254, 22
	v_readlane_b32 s87, v254, 23
	v_readlane_b32 s88, v254, 24
	v_readlane_b32 s89, v254, 25
	v_readlane_b32 s90, v254, 26
	v_readlane_b32 s91, v254, 27
	v_readlane_b32 s92, v254, 28
	v_readlane_b32 s93, v254, 29
	v_readlane_b32 s94, v254, 30
	v_readlane_b32 s95, v254, 31
	s_nop 4
	s_add_u32 s4, s4, 0x5580
	s_addc_u32 s5, s5, 0
	v_readfirstlane_b32 s6, v170
	v_lshl_add_u64 v[152:153], s[4:5], 0, v[128:129]
	s_mov_b32 m0, s6
	v_lshl_add_u64 v[130:131], s[4:5], 0, v[130:131]
	v_readfirstlane_b32 s4, v171
	ds_read_b128 v[132:135], v169
	ds_read_b128 v[136:139], v169 offset:1024
	ds_read_b128 v[156:159], v169 offset:2048
	ds_read_b128 v[162:165], v169 offset:3072
	ds_read_b128 v[172:175], v151
	ds_read_b128 v[176:179], v151 offset:1024
	ds_read_b128 v[180:183], v150
	ds_read_b128 v[184:187], v150 offset:1024
	ds_read_b128 v[188:191], v145
	ds_read_b128 v[192:195], v145 offset:1024
	ds_read_b128 v[196:199], v144
	ds_read_b128 v[200:203], v144 offset:1024
	global_load_lds_dwordx4 v[152:153], off
	s_mov_b32 m0, s4
	s_nop 0
	global_load_lds_dwordx4 v[130:131], off
	s_barrier
	s_waitcnt lgkmcnt(0)
	s_waitcnt lgkmcnt(0)
	v_mfma_f32_16x16x32_bf16 v[124:127], v[132:135], v[172:175], v[124:127]
	v_mfma_f32_16x16x32_bf16 v[120:123], v[156:159], v[172:175], v[120:123]
	v_mfma_f32_16x16x32_bf16 v[108:111], v[132:135], v[188:191], v[108:111]
	v_mfma_f32_16x16x32_bf16 v[104:107], v[156:159], v[188:191], v[104:107]
	v_mfma_f32_16x16x32_bf16 v[124:127], v[136:139], v[176:179], v[124:127]
	v_mfma_f32_16x16x32_bf16 v[120:123], v[162:165], v[176:179], v[120:123]
	v_mfma_f32_16x16x32_bf16 v[116:119], v[132:135], v[180:183], v[116:119]
	v_mfma_f32_16x16x32_bf16 v[112:115], v[156:159], v[180:183], v[112:115]
	v_mfma_f32_16x16x32_bf16 v[108:111], v[136:139], v[192:195], v[108:111]
	v_mfma_f32_16x16x32_bf16 v[104:107], v[162:165], v[192:195], v[104:107]
	v_mfma_f32_16x16x32_bf16 v[100:103], v[132:135], v[196:199], v[100:103]
	v_mfma_f32_16x16x32_bf16 v[96:99], v[156:159], v[196:199], v[96:99]
	v_mfma_f32_16x16x32_bf16 v[204:207], v[136:139], v[184:187], v[116:119]
	v_mfma_f32_16x16x32_bf16 v[208:211], v[162:165], v[184:187], v[112:115]
	v_mfma_f32_16x16x32_bf16 v[212:215], v[136:139], v[200:203], v[100:103]
	v_mfma_f32_16x16x32_bf16 v[216:219], v[162:165], v[200:203], v[96:99]
	s_barrier
	s_nop 1
	ds_read_b128 v[96:99], v168
	ds_read_b128 v[100:103], v168 offset:1024
	ds_read_b128 v[112:115], v168 offset:2048
	ds_read_b128 v[116:119], v168 offset:3072
	s_barrier
	s_waitcnt lgkmcnt(0)
	s_waitcnt lgkmcnt(0)
	v_mfma_f32_16x16x32_bf16 v[92:95], v[96:99], v[172:175], v[92:95]
	v_mfma_f32_16x16x32_bf16 v[88:91], v[112:115], v[172:175], v[88:91]
	v_mfma_f32_16x16x32_bf16 v[76:79], v[96:99], v[188:191], v[76:79]
	v_mfma_f32_16x16x32_bf16 v[72:75], v[112:115], v[188:191], v[72:75]
	v_mfma_f32_16x16x32_bf16 v[92:95], v[100:103], v[176:179], v[92:95]
	v_mfma_f32_16x16x32_bf16 v[88:91], v[116:119], v[176:179], v[88:91]
	v_mfma_f32_16x16x32_bf16 v[84:87], v[96:99], v[180:183], v[84:87]
	v_mfma_f32_16x16x32_bf16 v[80:83], v[112:115], v[180:183], v[80:83]
	v_mfma_f32_16x16x32_bf16 v[76:79], v[100:103], v[192:195], v[76:79]
	v_mfma_f32_16x16x32_bf16 v[72:75], v[116:119], v[192:195], v[72:75]
	v_mfma_f32_16x16x32_bf16 v[68:71], v[96:99], v[196:199], v[68:71]
	v_mfma_f32_16x16x32_bf16 v[64:67], v[112:115], v[196:199], v[64:67]
	v_mfma_f32_16x16x32_bf16 v[166:169], v[100:103], v[184:187], v[84:87]
	v_mfma_f32_16x16x32_bf16 v[170:173], v[116:119], v[184:187], v[80:83]
	v_mfma_f32_16x16x32_bf16 v[174:177], v[100:103], v[200:203], v[68:71]
	v_mfma_f32_16x16x32_bf16 v[178:181], v[116:119], v[200:203], v[64:67]
	s_barrier
	s_nop 1
	ds_read_b128 v[64:67], v151 offset:16384
	ds_read_b128 v[68:71], v151 offset:17408
	ds_read_b128 v[80:83], v150 offset:16384
	ds_read_b128 v[84:87], v150 offset:17408
	ds_read_b128 v[182:185], v145 offset:16384
	ds_read_b128 v[186:189], v145 offset:17408
	ds_read_b128 v[190:193], v144 offset:16384
	ds_read_b128 v[194:197], v144 offset:17408
	s_waitcnt vmcnt(4)
	s_barrier
; #define WAIT_V(n) asm volatile("s_waitcnt vmcnt(" #n ")" ::: "memory")
; #define WAIT_L(n) asm volatile("s_waitcnt lgkmcnt(" #n ")" ::: "memory")
; #define BAR __builtin_amdgcn_s_barrier()
;     ...
;     LDA(At, 0, 1); WAIT_V(4); BAR; WAIT_L(0); MMA(1, 0, At, B0); MMA(1, 1, At, B1); BAR; }
;   { LDB(B0, 1, 0); LDA(At, 1, 0); WAIT_V(2); BAR; WAIT_L(0); MMA(0, 0, At, B0); BAR;
	s_waitcnt lgkmcnt(0)
	s_waitcnt lgkmcnt(0)
	v_mfma_f32_16x16x32_bf16 v[60:63], v[132:135], v[64:67], v[60:63]
	v_mfma_f32_16x16x32_bf16 v[56:59], v[156:159], v[64:67], v[56:59]
	v_mfma_f32_16x16x32_bf16 v[44:47], v[132:135], v[182:185], v[44:47]
	v_mfma_f32_16x16x32_bf16 v[40:43], v[156:159], v[182:185], v[40:43]
	v_mfma_f32_16x16x32_bf16 v[60:63], v[136:139], v[68:71], v[60:63]
	v_mfma_f32_16x16x32_bf16 v[56:59], v[162:165], v[68:71], v[56:59]
	v_mfma_f32_16x16x32_bf16 v[52:55], v[132:135], v[80:83], v[52:55]
	v_mfma_f32_16x16x32_bf16 v[48:51], v[156:159], v[80:83], v[48:51]
	v_mfma_f32_16x16x32_bf16 v[44:47], v[136:139], v[186:189], v[44:47]
	v_mfma_f32_16x16x32_bf16 v[40:43], v[162:165], v[186:189], v[40:43]
	v_mfma_f32_16x16x32_bf16 v[36:39], v[132:135], v[190:193], v[36:39]
	v_mfma_f32_16x16x32_bf16 v[32:35], v[156:159], v[190:193], v[32:35]
	v_mfma_f32_16x16x32_bf16 v[198:201], v[136:139], v[84:87], v[52:55]
	v_mfma_f32_16x16x32_bf16 v[220:223], v[162:165], v[84:87], v[48:51]
	v_mfma_f32_16x16x32_bf16 v[130:133], v[136:139], v[194:197], v[36:39]
	v_mfma_f32_16x16x32_bf16 v[134:137], v[162:165], v[194:197], v[32:35]
	v_mfma_f32_16x16x32_bf16 v[28:31], v[96:99], v[64:67], v[28:31]
	v_mfma_f32_16x16x32_bf16 v[24:27], v[112:115], v[64:67], v[24:27]
	v_mfma_f32_16x16x32_bf16 v[12:15], v[96:99], v[182:185], v[12:15]
	v_mfma_f32_16x16x32_bf16 v[8:11], v[112:115], v[182:185], v[8:11]
	v_mfma_f32_16x16x32_bf16 v[28:31], v[100:103], v[68:71], v[28:31]
	v_mfma_f32_16x16x32_bf16 v[24:27], v[116:119], v[68:71], v[24:27]
	v_mfma_f32_16x16x32_bf16 v[20:23], v[96:99], v[80:83], v[20:23]
	v_mfma_f32_16x16x32_bf16 v[16:19], v[112:115], v[80:83], v[16:19]
	v_mfma_f32_16x16x32_bf16 v[12:15], v[100:103], v[186:189], v[12:15]
	v_mfma_f32_16x16x32_bf16 v[8:11], v[116:119], v[186:189], v[8:11]
	v_mfma_f32_16x16x32_bf16 v[4:7], v[96:99], v[190:193], v[4:7]
	v_mfma_f32_16x16x32_bf16 v[0:3], v[112:115], v[190:193], v[0:3]
	v_mfma_f32_16x16x32_bf16 v[156:159], v[100:103], v[84:87], v[20:23]
	v_mfma_f32_16x16x32_bf16 v[162:165], v[116:119], v[84:87], v[16:19]
	v_mfma_f32_16x16x32_bf16 v[182:185], v[100:103], v[194:197], v[4:7]
	v_mfma_f32_16x16x32_bf16 v[186:189], v[116:119], v[194:197], v[0:3]
	s_barrier
	s_nop 1
	ds_read_b128 v[0:3], v160
	ds_read_b128 v[4:7], v160 offset:1024
	ds_read_b128 v[190:193], v160 offset:2048
	ds_read_b128 v[194:197], v160 offset:3072
	ds_read_b128 v[16:19], v151 offset:32768
	ds_read_b128 v[20:23], v151 offset:33792
	ds_read_b128 v[32:35], v150 offset:32768
	ds_read_b128 v[36:39], v150 offset:33792
	ds_read_b128 v[48:51], v145 offset:32768
	ds_read_b128 v[52:55], v145 offset:33792
	ds_read_b128 v[224:227], v144 offset:32768
	ds_read_b128 v[228:231], v144 offset:33792
	s_waitcnt vmcnt(2)
	s_barrier
	s_waitcnt lgkmcnt(0)
	s_waitcnt lgkmcnt(0)
	v_mfma_f32_16x16x32_bf16 v[64:67], v[0:3], v[16:19], v[124:127]
	v_mfma_f32_16x16x32_bf16 v[112:115], v[4:7], v[20:23], v[64:67]
	v_mfma_f32_16x16x32_bf16 v[64:67], v[190:193], v[16:19], v[120:123]
	v_mfma_f32_16x16x32_bf16 v[116:119], v[194:197], v[20:23], v[64:67]
	v_mfma_f32_16x16x32_bf16 v[64:67], v[0:3], v[32:35], v[204:207]
	v_mfma_f32_16x16x32_bf16 v[96:99], v[4:7], v[36:39], v[64:67]
	v_mfma_f32_16x16x32_bf16 v[64:67], v[190:193], v[32:35], v[208:211]
	v_mfma_f32_16x16x32_bf16 v[100:103], v[194:197], v[36:39], v[64:67]
	v_mfma_f32_16x16x32_bf16 v[64:67], v[0:3], v[48:51], v[108:111]
	v_mfma_f32_16x16x32_bf16 v[80:83], v[4:7], v[52:55], v[64:67]
	v_mfma_f32_16x16x32_bf16 v[64:67], v[190:193], v[48:51], v[104:107]
	v_mfma_f32_16x16x32_bf16 v[84:87], v[194:197], v[52:55], v[64:67]
	v_mfma_f32_16x16x32_bf16 v[64:67], v[0:3], v[224:227], v[212:215]
	v_mfma_f32_16x16x32_bf16 v[68:71], v[190:193], v[224:227], v[216:219]
	v_mfma_f32_16x16x32_bf16 v[64:67], v[4:7], v[228:231], v[64:67]
	v_mfma_f32_16x16x32_bf16 v[68:71], v[194:197], v[228:231], v[68:71]
	s_barrier
; #define WAIT_V(n) asm volatile("s_waitcnt vmcnt(" #n ")" ::: "memory")
; #define WAIT_L(n) asm volatile("s_waitcnt lgkmcnt(" #n ")" ::: "memory")
; #define BAR __builtin_amdgcn_s_barrier()
;     ...
;     LDB(B1, 1, 1); WAIT_V(0); BAR; WAIT_L(0); MMA(0, 1, At, B1); BAR;
;     LDA(At, 1, 1); BAR; WAIT_L(0); MMA(1, 0, At, B0); MMA(1, 1, At, B1); BAR; }
;   if (wr == 0) BAR;
	ds_read_b128 v[202:205], v154
	ds_read_b128 v[206:209], v154 offset:1024
	ds_read_b128 v[210:213], v154 offset:2048
	ds_read_b128 v[152:155], v154 offset:3072
	s_waitcnt vmcnt(0)
	s_barrier
	s_waitcnt lgkmcnt(0)
	s_waitcnt lgkmcnt(0)
	v_mfma_f32_16x16x32_bf16 v[92:95], v[202:205], v[16:19], v[92:95]
	v_mfma_f32_16x16x32_bf16 v[16:19], v[210:213], v[16:19], v[88:91]
	v_mfma_f32_16x16x32_bf16 v[120:123], v[152:155], v[20:23], v[16:19]
	v_mfma_f32_16x16x32_bf16 v[16:19], v[202:205], v[32:35], v[166:169]
	v_mfma_f32_16x16x32_bf16 v[108:111], v[206:209], v[36:39], v[16:19]
	v_mfma_f32_16x16x32_bf16 v[16:19], v[210:213], v[32:35], v[170:173]
	v_mfma_f32_16x16x32_bf16 v[104:107], v[152:155], v[36:39], v[16:19]
	v_mfma_f32_16x16x32_bf16 v[16:19], v[202:205], v[48:51], v[76:79]
	v_mfma_f32_16x16x32_bf16 v[124:127], v[206:209], v[20:23], v[92:95]
	v_mfma_f32_16x16x32_bf16 v[92:95], v[206:209], v[52:55], v[16:19]
	v_mfma_f32_16x16x32_bf16 v[16:19], v[210:213], v[48:51], v[72:75]
	v_mfma_f32_16x16x32_bf16 v[88:91], v[152:155], v[52:55], v[16:19]
	v_mfma_f32_16x16x32_bf16 v[16:19], v[202:205], v[224:227], v[174:177]
	v_mfma_f32_16x16x32_bf16 v[76:79], v[206:209], v[228:231], v[16:19]
	v_mfma_f32_16x16x32_bf16 v[16:19], v[210:213], v[224:227], v[178:181]
	v_mfma_f32_16x16x32_bf16 v[72:75], v[152:155], v[228:231], v[16:19]
	s_barrier
	ds_read_b128 v[166:169], v151 offset:49152
	ds_read_b128 v[170:173], v151 offset:50176
	ds_read_b128 v[174:177], v150 offset:49152
	ds_read_b128 v[178:181], v150 offset:50176
	ds_read_b128 v[214:217], v145 offset:49152
	ds_read_b128 v[224:227], v145 offset:50176
	ds_read_b128 v[228:231], v144 offset:49152
	ds_read_b128 v[232:235], v144 offset:50176
	s_barrier
	s_waitcnt lgkmcnt(0)
	s_waitcnt lgkmcnt(0)
	v_mfma_f32_16x16x32_bf16 v[16:19], v[0:3], v[166:169], v[60:63]
	v_mfma_f32_16x16x32_bf16 v[48:51], v[4:7], v[170:173], v[16:19]
	v_mfma_f32_16x16x32_bf16 v[16:19], v[190:193], v[166:169], v[56:59]
	v_mfma_f32_16x16x32_bf16 v[52:55], v[194:197], v[170:173], v[16:19]
	v_mfma_f32_16x16x32_bf16 v[16:19], v[0:3], v[174:177], v[198:201]
	v_mfma_f32_16x16x32_bf16 v[32:35], v[4:7], v[178:181], v[16:19]
	v_mfma_f32_16x16x32_bf16 v[16:19], v[190:193], v[174:177], v[220:223]
	v_mfma_f32_16x16x32_bf16 v[36:39], v[194:197], v[178:181], v[16:19]
	v_mfma_f32_16x16x32_bf16 v[16:19], v[0:3], v[214:217], v[44:47]
	v_mfma_f32_16x16x32_bf16 v[0:3], v[0:3], v[228:231], v[130:133]
	v_mfma_f32_16x16x32_bf16 v[16:19], v[4:7], v[224:227], v[16:19]
	v_mfma_f32_16x16x32_bf16 v[20:23], v[190:193], v[214:217], v[40:43]
	v_mfma_f32_16x16x32_bf16 v[0:3], v[4:7], v[232:235], v[0:3]
	v_mfma_f32_16x16x32_bf16 v[4:7], v[190:193], v[228:231], v[134:137]
	v_mfma_f32_16x16x32_bf16 v[20:23], v[194:197], v[224:227], v[20:23]
	v_mfma_f32_16x16x32_bf16 v[4:7], v[194:197], v[232:235], v[4:7]
	v_mfma_f32_16x16x32_bf16 v[24:27], v[210:213], v[166:169], v[24:27]
	v_mfma_f32_16x16x32_bf16 v[56:59], v[152:155], v[170:173], v[24:27]
	v_mfma_f32_16x16x32_bf16 v[24:27], v[202:205], v[174:177], v[156:159]
	v_mfma_f32_16x16x32_bf16 v[44:47], v[206:209], v[178:181], v[24:27]
	v_mfma_f32_16x16x32_bf16 v[24:27], v[210:213], v[174:177], v[162:165]
	v_mfma_f32_16x16x32_bf16 v[8:11], v[210:213], v[214:217], v[8:11]
	v_mfma_f32_16x16x32_bf16 v[28:31], v[202:205], v[166:169], v[28:31]
	v_mfma_f32_16x16x32_bf16 v[40:43], v[152:155], v[178:181], v[24:27]
	v_mfma_f32_16x16x32_bf16 v[12:15], v[202:205], v[214:217], v[12:15]
	v_mfma_f32_16x16x32_bf16 v[24:27], v[152:155], v[224:227], v[8:11]
	v_mfma_f32_16x16x32_bf16 v[8:11], v[202:205], v[228:231], v[182:185]
	v_mfma_f32_16x16x32_bf16 v[60:63], v[206:209], v[170:173], v[28:31]
	v_mfma_f32_16x16x32_bf16 v[28:31], v[206:209], v[224:227], v[12:15]
	v_mfma_f32_16x16x32_bf16 v[12:15], v[206:209], v[232:235], v[8:11]
	v_mfma_f32_16x16x32_bf16 v[8:11], v[210:213], v[228:231], v[186:189]
	v_mfma_f32_16x16x32_bf16 v[8:11], v[152:155], v[232:235], v[8:11]
	v_cmp_gt_u32_e32 vcc, s30, v148
	s_barrier
	s_and_saveexec_b64 s[4:5], vcc
	s_cbranch_execz .LBB0_1338
	s_barrier

; __global__ void __launch_bounds__(NT) mega(Params pv) {
;   extern __shared__ __attribute__((aligned(16))) char smem[];
;   const int bid = blockIdx.x, nb = gridDim.x;
;   cg::grid_group grid = cg::this_grid();
;   int wv = __builtin_amdgcn_readfirstlane((int)(threadIdx.x >> 6));
;   asm volatile("" : "+s"(wv));
	.amdhsa_kernel _Z4mega6Params
		.amdhsa_group_segment_fixed_size 0
		.amdhsa_private_segment_fixed_size 0
		.amdhsa_kernarg_size 560
		.amdhsa_user_sgpr_count 2
		.amdhsa_user_sgpr_dispatch_ptr 0
		.amdhsa_user_sgpr_queue_ptr 0
		.amdhsa_user_sgpr_kernarg_segment_ptr 1
		.amdhsa_user_sgpr_dispatch_id 0
		.amdhsa_user_sgpr_kernarg_preload_length 0
		.amdhsa_user_sgpr_kernarg_preload_offset 0
		.amdhsa_user_sgpr_private_segment_size 0
		.amdhsa_uses_dynamic_stack 0
		.amdhsa_enable_private_segment 0
		.amdhsa_system_sgpr_workgroup_id_x 1
		.amdhsa_system_sgpr_workgroup_id_y 0
		.amdhsa_system_sgpr_workgroup_id_z 0
		.amdhsa_system_sgpr_workgroup_info 0
		.amdhsa_system_vgpr_workitem_id 2
		.amdhsa_next_free_vgpr 256
		.amdhsa_next_free_sgpr 98
		.amdhsa_accum_offset 256
		.amdhsa_reserve_vcc 1
		.amdhsa_float_round_mode_32 0
		.amdhsa_float_round_mode_16_64 0
		.amdhsa_float_denorm_mode_32 3
		.amdhsa_float_denorm_mode_16_64 3
		.amdhsa_dx10_clamp 1
		.amdhsa_ieee_mode 1
		.amdhsa_fp16_overflow 0
		.amdhsa_tg_split 0
		.amdhsa_exception_fp_ieee_invalid_op 0
		.amdhsa_exception_fp_denorm_src 0
		.amdhsa_exception_fp_ieee_div_zero 0
		.amdhsa_exception_fp_ieee_overflow 0
		.amdhsa_exception_fp_ieee_underflow 0
		.amdhsa_exception_fp_ieee_inexact 0
		.amdhsa_exception_int_div_zero 0
	.end_amdhsa_kernel

; __global__ void __launch_bounds__(NT) mega(Params pv) {
;   extern __shared__ __attribute__((aligned(16))) char smem[];
;   const int bid = blockIdx.x, nb = gridDim.x;
;   cg::grid_group grid = cg::this_grid();
;   int wv = __builtin_amdgcn_readfirstlane((int)(threadIdx.x >> 6));
;   asm volatile("" : "+s"(wv));
amdhsa.kernels:
  - .agpr_count:     0
    .args:
      - .offset:         0
        .size:           304
        .value_kind:     by_value
      - .offset:         304
        .size:           4
        .value_kind:     hidden_block_count_x
      - .offset:         308
        .size:           4
        .value_kind:     hidden_block_count_y
      - .offset:         312
        .size:           4
        .value_kind:     hidden_block_count_z
      - .offset:         316
        .size:           2
        .value_kind:     hidden_group_size_x
      - .offset:         318
        .size:           2
        .value_kind:     hidden_group_size_y
      - .offset:         320
        .size:           2
        .value_kind:     hidden_group_size_z
      - .offset:         322
        .size:           2
        .value_kind:     hidden_remainder_x
      - .offset:         324
        .size:           2
        .value_kind:     hidden_remainder_y
      - .offset:         326
        .size:           2
        .value_kind:     hidden_remainder_z
      - .offset:         344
        .size:           8
        .value_kind:     hidden_global_offset_x
      - .offset:         352
        .size:           8
        .value_kind:     hidden_global_offset_y
      - .offset:         360
        .size:           8
        .value_kind:     hidden_global_offset_z
      - .offset:         368
        .size:           2
        .value_kind:     hidden_grid_dims
      - .offset:         392
        .size:           8
        .value_kind:     hidden_multigrid_sync_arg
      - .offset:         424
        .size:           4
        .value_kind:     hidden_dynamic_lds_size
    .group_segment_fixed_size: 0
    .kernarg_segment_align: 8
    .kernarg_segment_size: 560
    .language:       OpenCL C
    .language_version:
      - 2
      - 0
    .max_flat_workgroup_size: 512
    .name:           _Z4mega6Params
    .private_segment_fixed_size: 0
    .sgpr_count:     104
    .sgpr_spill_count: 93
    .symbol:         _Z4mega6Params.kd
    .uniform_work_group_size: 1
    .uses_dynamic_stack: false
    .vgpr_count:     256
    .vgpr_spill_count: 0
    .wavefront_size: 64
